# GEMM K-loops: M0 wait slots filled with LDS fragment reads instead of s_nop, stage constants folded into the M0 adds
# speedup vs baseline: 1.0031x; 1.0031x over previous
; #define PG8_STAGE(bufoff, gbase, voff) do { _Pragma("unroll") for (int _i = 0; _i < 2; ++_i) \
;     __builtin_amdgcn_global_load_lds((const unsigned*)((const char*)(gbase) + (voff)[_i]), (LAS unsigned*)(lds + (bufoff) + ldsw + _i * 8192), 16, 0, 0); } while (0)
; #define PG8_LDA(dst, b, h) do { _Pragma("unroll") for (int m = 0; m < 4; ++m) _Pragma("unroll") for (int k = 0; k < 2; ++k) dst[m][k] = *(const LAS bf16x8*)(lds + PG8_SA(b, h) + aoff + m * 2048 + k * 1024); } while (0)
; #define PG8_LDB(dst, b, h) do { _Pragma("unroll") for (int n = 0; n < 2; ++n) _Pragma("unroll") for (int k = 0; k < 2; ++k) dst[n][k] = *(const LAS bf16x8*)(lds + PG8_SB(b, h) + boff + n * 2048 + k * 1024); } while (0)
; #define PG8_MMA(ai, bj, At, Bt) do { __builtin_amdgcn_s_setprio(1); _Pragma("unroll") for (int m = 0; m < 4; ++m) _Pragma("unroll") for (int n = 0; n < 2; ++n) _Pragma("unroll") for (int k = 0; k < 2; ++k) \
;     acc[ai][bj][m][n] = __builtin_amdgcn_mfma_f32_16x16x32_bf16(Bt[n][k], At[m][k], acc[ai][bj][m][n], 0, 0, 0); __builtin_amdgcn_s_setprio(0); } while (0)
; #define PG8_WAIT_V(n) asm volatile("s_waitcnt vmcnt(" #n ")" ::: "memory")
; #define PG8_WAIT_L(n) asm volatile("s_waitcnt lgkmcnt(" #n ")" ::: "memory")
; #define PG8_BAR __builtin_amdgcn_s_barrier()
; #define PG8_SCHED __builtin_amdgcn_sched_barrier(0)
; template <class Epi, class Sched>
; DI void gemm_phase(LAS unsigned char* lds, const Gemm g, const Sched& S, const Epi& E) {
;     ...
;     for (int t = 0; t < nt; t += 2) {
;       const bool last = (t == nt - 2);
;       const char* a1 = cA + (size_t)(t + 1) * kstep;
;       const char* a2 = last ? nA : cA + (size_t)(t + 2) * kstep; const char* b2 = last ? nB : cB + (size_t)(t + 2) * kstep;
;       const char* a3 = a2 + kstep; const char* b3 = b2 + kstep;
;       PG8_LDB(B0, 0, 0); PG8_SCHED; PG8_LDA(At, 0, 0); PG8_STAGE(PG8_SA(1, 1), a1 + hstep, voffA);
;       PG8_WAIT_L(8); PG8_BAR; PG8_WAIT_L(0); PG8_MMA(0, 0, At, B0); PG8_BAR; PG8_SCHED;
;       PG8_LDB(B1, 0, 1); PG8_STAGE(PG8_SB(0, 0), b2, voffB);
;       PG8_BAR; PG8_WAIT_L(0); PG8_MMA(0, 1, At, B1); PG8_BAR;
;       PG8_LDA(At, 0, 1); PG8_STAGE(PG8_SA(0, 0), a2, voffA);
;       PG8_BAR; PG8_WAIT_L(0); PG8_MMA(1, 0, At, B0); PG8_BAR; PG8_SCHED;
;       PG8_STAGE(PG8_SB(0, 1), b2 + hstep, voffB);
;       PG8_WAIT_V(6); PG8_BAR; PG8_MMA(1, 1, At, B1); PG8_BAR;
.LBB0_370:
	s_add_u32 s4, s2, 0xfffc0080
	s_addc_u32 s5, s3, -1
	ds_read_b128 v[128:131], v228
	ds_read_b128 v[146:149], v228 offset:1024
	ds_read_b128 v[150:153], v228 offset:2048
	ds_read_b128 v[160:163], v228 offset:3072
	s_cmp_eq_u32 s50, 12
	s_cselect_b32 s21, s15, s5
	s_cselect_b32 s20, s29, s4
	s_cselect_b32 s5, s13, s49
	s_cselect_b32 s4, s36, s37
	s_add_i32 m0, s40, 0xc000
	ds_read_b128 v[164:167], v158
	ds_read_b128 v[168:171], v158 offset:1024
	ds_read_b128 v[172:175], v158 offset:2048
	ds_read_b128 v[176:179], v158 offset:3072
	ds_read_b128 v[196:199], v158 offset:4096
	ds_read_b128 v[200:203], v158 offset:5120
	ds_read_b128 v[204:207], v158 offset:6144
	global_load_lds_dwordx4 v140, s[2:3]
	s_add_i32 m0, s40, 0xe000
	ds_read_b128 v[208:211], v158 offset:7168
	global_load_lds_dwordx4 v142, s[2:3]
	s_waitcnt lgkmcnt(8)
	s_barrier
	s_waitcnt lgkmcnt(0)
	v_mfma_f32_16x16x32_bf16 v[124:127], v[128:131], v[164:167], v[124:127]
	v_mfma_f32_16x16x32_bf16 v[120:123], v[150:153], v[164:167], v[120:123]
	v_mfma_f32_16x16x32_bf16 v[108:111], v[128:131], v[172:175], v[108:111]
	v_mfma_f32_16x16x32_bf16 v[104:107], v[150:153], v[172:175], v[104:107]
	v_mfma_f32_16x16x32_bf16 v[92:95], v[128:131], v[196:199], v[92:95]
	v_mfma_f32_16x16x32_bf16 v[88:91], v[150:153], v[196:199], v[88:91]
	v_mfma_f32_16x16x32_bf16 v[76:79], v[128:131], v[204:207], v[76:79]
	v_mfma_f32_16x16x32_bf16 v[72:75], v[150:153], v[204:207], v[72:75]
	v_mfma_f32_16x16x32_bf16 v[124:127], v[146:149], v[168:171], v[124:127]
	v_mfma_f32_16x16x32_bf16 v[120:123], v[160:163], v[168:171], v[120:123]
	v_mfma_f32_16x16x32_bf16 v[108:111], v[146:149], v[176:179], v[108:111]
	v_mfma_f32_16x16x32_bf16 v[104:107], v[160:163], v[176:179], v[104:107]
	v_mfma_f32_16x16x32_bf16 v[92:95], v[146:149], v[200:203], v[92:95]
	v_mfma_f32_16x16x32_bf16 v[88:91], v[160:163], v[200:203], v[88:91]
	v_mfma_f32_16x16x32_bf16 v[76:79], v[146:149], v[208:211], v[76:79]
	v_mfma_f32_16x16x32_bf16 v[72:75], v[160:163], v[208:211], v[72:75]
	s_barrier
	s_add_i32 s51, s34, 0x10000
	s_add_u32 vcc_lo, s4, s0
	s_addc_u32 vcc_hi, s5, s1
	s_mov_b32 m0, s51
	ds_read_b128 v[212:215], v229
	ds_read_b128 v[216:219], v229 offset:1024
	ds_read_b128 v[220:223], v229 offset:2048
	global_load_lds_dwordx4 v136, s[4:5]
	s_add_i32 m0, s51, 0x2000
	ds_read_b128 v[224:227], v229 offset:3072
	global_load_lds_dwordx4 v132, s[4:5]
	s_barrier
	s_waitcnt lgkmcnt(0)
	v_mfma_f32_16x16x32_bf16 v[116:119], v[212:215], v[164:167], v[116:119]
	v_mfma_f32_16x16x32_bf16 v[112:115], v[220:223], v[164:167], v[112:115]
	v_mfma_f32_16x16x32_bf16 v[100:103], v[212:215], v[172:175], v[100:103]
	v_mfma_f32_16x16x32_bf16 v[96:99], v[220:223], v[172:175], v[96:99]
	v_mfma_f32_16x16x32_bf16 v[84:87], v[212:215], v[196:199], v[84:87]
	v_mfma_f32_16x16x32_bf16 v[80:83], v[220:223], v[196:199], v[80:83]
	v_mfma_f32_16x16x32_bf16 v[68:71], v[212:215], v[204:207], v[68:71]
	v_mfma_f32_16x16x32_bf16 v[64:67], v[220:223], v[204:207], v[64:67]
	v_mfma_f32_16x16x32_bf16 v[116:119], v[216:219], v[168:171], v[116:119]
	v_mfma_f32_16x16x32_bf16 v[112:115], v[224:227], v[168:171], v[112:115]
	v_mfma_f32_16x16x32_bf16 v[100:103], v[216:219], v[176:179], v[100:103]
	v_mfma_f32_16x16x32_bf16 v[96:99], v[224:227], v[176:179], v[96:99]
	v_mfma_f32_16x16x32_bf16 v[84:87], v[216:219], v[200:203], v[84:87]
	v_mfma_f32_16x16x32_bf16 v[80:83], v[224:227], v[200:203], v[80:83]
	v_mfma_f32_16x16x32_bf16 v[68:71], v[216:219], v[208:211], v[68:71]
	v_mfma_f32_16x16x32_bf16 v[64:67], v[224:227], v[208:211], v[64:67]
	s_mov_b32 m0, s40
	s_add_u32 s100, s20, s0
	s_addc_u32 s101, s21, s1
	s_barrier
	ds_read_b128 v[164:167], v158 offset:16384
	ds_read_b128 v[168:171], v158 offset:17408
	ds_read_b128 v[172:175], v158 offset:18432
	ds_read_b128 v[176:179], v158 offset:19456
	ds_read_b128 v[196:199], v158 offset:20480
	ds_read_b128 v[200:203], v158 offset:21504
	ds_read_b128 v[204:207], v158 offset:22528
	global_load_lds_dwordx4 v138, s[20:21]
	s_mov_b32 m0, s41
	ds_read_b128 v[208:211], v158 offset:23552
	global_load_lds_dwordx4 v134, s[20:21]
	s_barrier
	s_waitcnt lgkmcnt(0)
	v_mfma_f32_16x16x32_bf16 v[60:63], v[128:131], v[164:167], v[60:63]
	v_mfma_f32_16x16x32_bf16 v[56:59], v[150:153], v[164:167], v[56:59]
	v_mfma_f32_16x16x32_bf16 v[44:47], v[128:131], v[172:175], v[44:47]
	v_mfma_f32_16x16x32_bf16 v[40:43], v[150:153], v[172:175], v[40:43]
	v_mfma_f32_16x16x32_bf16 v[28:31], v[128:131], v[196:199], v[28:31]
	v_mfma_f32_16x16x32_bf16 v[24:27], v[150:153], v[196:199], v[24:27]
	v_mfma_f32_16x16x32_bf16 v[12:15], v[128:131], v[204:207], v[12:15]
	v_mfma_f32_16x16x32_bf16 v[8:11], v[150:153], v[204:207], v[8:11]
	v_mfma_f32_16x16x32_bf16 v[60:63], v[146:149], v[168:171], v[60:63]
	v_mfma_f32_16x16x32_bf16 v[56:59], v[160:163], v[168:171], v[56:59]
	v_mfma_f32_16x16x32_bf16 v[44:47], v[146:149], v[176:179], v[44:47]
	v_mfma_f32_16x16x32_bf16 v[40:43], v[160:163], v[176:179], v[40:43]
	v_mfma_f32_16x16x32_bf16 v[28:31], v[146:149], v[200:203], v[28:31]
	v_mfma_f32_16x16x32_bf16 v[24:27], v[160:163], v[200:203], v[24:27]
	v_mfma_f32_16x16x32_bf16 v[12:15], v[146:149], v[208:211], v[12:15]
	v_mfma_f32_16x16x32_bf16 v[8:11], v[160:163], v[208:211], v[8:11]
	s_barrier
	s_add_u32 s52, s4, 0x40000
	s_addc_u32 s53, s5, 0
	s_add_i32 s51, s34, 0x14000
	s_mov_b32 m0, s51
	s_nop 0
	global_load_lds_dwordx4 v136, s[52:53]
	s_add_i32 m0, s51, 0x2000
	s_nop 0
	global_load_lds_dwordx4 v132, s[52:53]
	s_waitcnt vmcnt(6)
	s_barrier
; #define PG8_STAGE(bufoff, gbase, voff) do { _Pragma("unroll") for (int _i = 0; _i < 2; ++_i) \
;     __builtin_amdgcn_global_load_lds((const unsigned*)((const char*)(gbase) + (voff)[_i]), (LAS unsigned*)(lds + (bufoff) + ldsw + _i * 8192), 16, 0, 0); } while (0)
; #define PG8_LDA(dst, b, h) do { _Pragma("unroll") for (int m = 0; m < 4; ++m) _Pragma("unroll") for (int k = 0; k < 2; ++k) dst[m][k] = *(const LAS bf16x8*)(lds + PG8_SA(b, h) + aoff + m * 2048 + k * 1024); } while (0)
; #define PG8_LDB(dst, b, h) do { _Pragma("unroll") for (int n = 0; n < 2; ++n) _Pragma("unroll") for (int k = 0; k < 2; ++k) dst[n][k] = *(const LAS bf16x8*)(lds + PG8_SB(b, h) + boff + n * 2048 + k * 1024); } while (0)
; #define PG8_MMA(ai, bj, At, Bt) do { __builtin_amdgcn_s_setprio(1); _Pragma("unroll") for (int m = 0; m < 4; ++m) _Pragma("unroll") for (int n = 0; n < 2; ++n) _Pragma("unroll") for (int k = 0; k < 2; ++k) \
;     acc[ai][bj][m][n] = __builtin_amdgcn_mfma_f32_16x16x32_bf16(Bt[n][k], At[m][k], acc[ai][bj][m][n], 0, 0, 0); __builtin_amdgcn_s_setprio(0); } while (0)
; #define PG8_WAIT_V(n) asm volatile("s_waitcnt vmcnt(" #n ")" ::: "memory")
; #define PG8_WAIT_L(n) asm volatile("s_waitcnt lgkmcnt(" #n ")" ::: "memory")
; #define PG8_BAR __builtin_amdgcn_s_barrier()
; #define PG8_SCHED __builtin_amdgcn_sched_barrier(0)
; template <class Epi, class Sched>
; DI void gemm_phase(LAS unsigned char* lds, const Gemm g, const Sched& S, const Epi& E) {
;     ...
;       PG8_WAIT_V(6); PG8_BAR; PG8_MMA(1, 1, At, B1); PG8_BAR;
;       PG8_LDB(B0, 1, 0); PG8_SCHED; PG8_LDA(At, 1, 0); PG8_STAGE(PG8_SA(0, 1), a2 + hstep, voffA);
;       PG8_WAIT_L(8); PG8_BAR; PG8_WAIT_L(0); PG8_MMA(0, 0, At, B0); PG8_BAR; PG8_SCHED;
;       PG8_LDB(B1, 1, 1); PG8_STAGE(PG8_SB(1, 0), b3, voffB);
;       PG8_BAR; PG8_WAIT_L(0); PG8_MMA(0, 1, At, B1); PG8_BAR;
;       PG8_LDA(At, 1, 1); PG8_STAGE(PG8_SA(1, 0), a3, voffA);
;       PG8_BAR; PG8_WAIT_L(0); PG8_MMA(1, 0, At, B0); PG8_BAR; PG8_SCHED;
	v_mfma_f32_16x16x32_bf16 v[52:55], v[212:215], v[164:167], v[52:55]
	v_mfma_f32_16x16x32_bf16 v[48:51], v[220:223], v[164:167], v[48:51]
	v_mfma_f32_16x16x32_bf16 v[36:39], v[212:215], v[172:175], v[36:39]
	v_mfma_f32_16x16x32_bf16 v[32:35], v[220:223], v[172:175], v[32:35]
	v_mfma_f32_16x16x32_bf16 v[20:23], v[212:215], v[196:199], v[20:23]
	v_mfma_f32_16x16x32_bf16 v[16:19], v[220:223], v[196:199], v[16:19]
	v_mfma_f32_16x16x32_bf16 v[4:7], v[212:215], v[204:207], v[4:7]
	v_mfma_f32_16x16x32_bf16 v[0:3], v[220:223], v[204:207], v[0:3]
	v_mfma_f32_16x16x32_bf16 v[52:55], v[216:219], v[168:171], v[52:55]
	v_mfma_f32_16x16x32_bf16 v[48:51], v[224:227], v[168:171], v[48:51]
	v_mfma_f32_16x16x32_bf16 v[36:39], v[216:219], v[176:179], v[36:39]
	v_mfma_f32_16x16x32_bf16 v[32:35], v[224:227], v[176:179], v[32:35]
	v_mfma_f32_16x16x32_bf16 v[20:23], v[216:219], v[200:203], v[20:23]
	v_mfma_f32_16x16x32_bf16 v[16:19], v[224:227], v[200:203], v[16:19]
	v_mfma_f32_16x16x32_bf16 v[4:7], v[216:219], v[208:211], v[4:7]
	v_mfma_f32_16x16x32_bf16 v[0:3], v[224:227], v[208:211], v[0:3]
	s_barrier
	ds_read_b128 v[128:131], v230
	ds_read_b128 v[146:149], v230 offset:1024
	ds_read_b128 v[150:153], v230 offset:2048
	ds_read_b128 v[160:163], v230 offset:3072
	s_add_u32 s20, s20, 0x40000
	s_addc_u32 s21, s21, 0
	s_mov_b32 m0, s42
	ds_read_b128 v[164:167], v158 offset:32768
	ds_read_b128 v[168:171], v158 offset:33792
	ds_read_b128 v[172:175], v158 offset:34816
	ds_read_b128 v[176:179], v158 offset:35840
	ds_read_b128 v[196:199], v158 offset:36864
	ds_read_b128 v[200:203], v158 offset:37888
	ds_read_b128 v[204:207], v158 offset:38912
	global_load_lds_dwordx4 v138, s[20:21]
	s_mov_b32 m0, s43
	ds_read_b128 v[208:211], v158 offset:39936
	global_load_lds_dwordx4 v134, s[20:21]
	s_waitcnt lgkmcnt(8)
	s_barrier
	s_waitcnt lgkmcnt(0)
	v_mfma_f32_16x16x32_bf16 v[124:127], v[128:131], v[164:167], v[124:127]
	v_mfma_f32_16x16x32_bf16 v[120:123], v[150:153], v[164:167], v[120:123]
	v_mfma_f32_16x16x32_bf16 v[108:111], v[128:131], v[172:175], v[108:111]
	v_mfma_f32_16x16x32_bf16 v[104:107], v[150:153], v[172:175], v[104:107]
	v_mfma_f32_16x16x32_bf16 v[92:95], v[128:131], v[196:199], v[92:95]
	v_mfma_f32_16x16x32_bf16 v[88:91], v[150:153], v[196:199], v[88:91]
	v_mfma_f32_16x16x32_bf16 v[76:79], v[128:131], v[204:207], v[76:79]
	v_mfma_f32_16x16x32_bf16 v[72:75], v[150:153], v[204:207], v[72:75]
	v_mfma_f32_16x16x32_bf16 v[124:127], v[146:149], v[168:171], v[124:127]
	v_mfma_f32_16x16x32_bf16 v[120:123], v[160:163], v[168:171], v[120:123]
	v_mfma_f32_16x16x32_bf16 v[108:111], v[146:149], v[176:179], v[108:111]
	v_mfma_f32_16x16x32_bf16 v[104:107], v[160:163], v[176:179], v[104:107]
	v_mfma_f32_16x16x32_bf16 v[92:95], v[146:149], v[200:203], v[92:95]
	v_mfma_f32_16x16x32_bf16 v[88:91], v[160:163], v[200:203], v[88:91]
	v_mfma_f32_16x16x32_bf16 v[76:79], v[146:149], v[208:211], v[76:79]
	v_mfma_f32_16x16x32_bf16 v[72:75], v[160:163], v[208:211], v[72:75]
	s_barrier
	s_add_i32 s21, s34, 0x18000
	s_mov_b32 m0, s21
	ds_read_b128 v[212:215], v231
	ds_read_b128 v[216:219], v231 offset:1024
	ds_read_b128 v[220:223], v231 offset:2048
	global_load_lds_dwordx4 v136, vcc
	s_add_i32 m0, s21, 0x2000
	ds_read_b128 v[224:227], v231 offset:3072
	global_load_lds_dwordx4 v132, vcc
	s_barrier
	s_waitcnt lgkmcnt(0)
	v_mfma_f32_16x16x32_bf16 v[116:119], v[212:215], v[164:167], v[116:119]
	v_mfma_f32_16x16x32_bf16 v[112:115], v[220:223], v[164:167], v[112:115]
	v_mfma_f32_16x16x32_bf16 v[100:103], v[212:215], v[172:175], v[100:103]
	v_mfma_f32_16x16x32_bf16 v[96:99], v[220:223], v[172:175], v[96:99]
	v_mfma_f32_16x16x32_bf16 v[84:87], v[212:215], v[196:199], v[84:87]
	v_mfma_f32_16x16x32_bf16 v[80:83], v[220:223], v[196:199], v[80:83]
	v_mfma_f32_16x16x32_bf16 v[68:71], v[212:215], v[204:207], v[68:71]
	v_mfma_f32_16x16x32_bf16 v[64:67], v[220:223], v[204:207], v[64:67]
	v_mfma_f32_16x16x32_bf16 v[116:119], v[216:219], v[168:171], v[116:119]
	v_mfma_f32_16x16x32_bf16 v[112:115], v[224:227], v[168:171], v[112:115]
	v_mfma_f32_16x16x32_bf16 v[100:103], v[216:219], v[176:179], v[100:103]
	v_mfma_f32_16x16x32_bf16 v[96:99], v[224:227], v[176:179], v[96:99]
	v_mfma_f32_16x16x32_bf16 v[84:87], v[216:219], v[200:203], v[84:87]
	v_mfma_f32_16x16x32_bf16 v[80:83], v[224:227], v[200:203], v[80:83]
	v_mfma_f32_16x16x32_bf16 v[68:71], v[216:219], v[208:211], v[68:71]
	v_mfma_f32_16x16x32_bf16 v[64:67], v[224:227], v[208:211], v[64:67]
	s_mov_b32 m0, s46
	s_barrier
; #define PG8_STAGE(bufoff, gbase, voff) do { _Pragma("unroll") for (int _i = 0; _i < 2; ++_i) \
;     __builtin_amdgcn_global_load_lds((const unsigned*)((const char*)(gbase) + (voff)[_i]), (LAS unsigned*)(lds + (bufoff) + ldsw + _i * 8192), 16, 0, 0); } while (0)
; #define PG8_MMA(ai, bj, At, Bt) do { __builtin_amdgcn_s_setprio(1); _Pragma("unroll") for (int m = 0; m < 4; ++m) _Pragma("unroll") for (int n = 0; n < 2; ++n) _Pragma("unroll") for (int k = 0; k < 2; ++k) \
;     acc[ai][bj][m][n] = __builtin_amdgcn_mfma_f32_16x16x32_bf16(Bt[n][k], At[m][k], acc[ai][bj][m][n], 0, 0, 0); __builtin_amdgcn_s_setprio(0); } while (0)
; #define PG8_WAIT_V(n) asm volatile("s_waitcnt vmcnt(" #n ")" ::: "memory")
; #define PG8_WAIT_L(n) asm volatile("s_waitcnt lgkmcnt(" #n ")" ::: "memory")
; #define PG8_BAR __builtin_amdgcn_s_barrier()
; #define PG8_SCHED __builtin_amdgcn_sched_barrier(0)
; template <class Epi, class Sched>
; DI void gemm_phase(LAS unsigned char* lds, const Gemm g, const Sched& S, const Epi& E) {
;     ...
;       PG8_BAR; PG8_WAIT_L(0); PG8_MMA(1, 0, At, B0); PG8_BAR; PG8_SCHED;
;       PG8_STAGE(PG8_SB(1, 1), b3 + hstep, voffB);
;       PG8_WAIT_V(6); PG8_BAR; PG8_MMA(1, 1, At, B1); PG8_BAR;
;     }
;   DI void operator()(const f32x4 (&acc)[2][2][4][2], const pg8::Unit& u, int wr, int wc, int fr_, int fq_) const {
;     ...
;             } else if (EPI == EPI_CIN) {
;               if (n == 0) {
;                 const int gb = u.pn * 256 + bj * 128 + wc * 32;
;                 const int f8 = gb + 8 * fq;
;                 const f32x4 v1 = acc[ai][bj][m][1];
;                 if (gb < 1024) st_bf8((u16*)(big + O_QD) + (size_t)token * 1024 + f8, v, v1, rinv * (0.125f * LOG2E));
;                 else if (gb < 2048) st_bf8((u16*)(big + O_KD) + (size_t)token * 1024 + (f8 - 1024), v, v1, rinv);
;                 else st_bf8((u16*)(big + O_VDT) + (size_t)token * 1024 + (f8 - 2048), v, v1, rinv);
;               }
	ds_read_b128 v[164:167], v158 offset:49152
	ds_read_b128 v[168:171], v158 offset:50176
	ds_read_b128 v[172:175], v158 offset:51200
	ds_read_b128 v[176:179], v158 offset:52224
	ds_read_b128 v[196:199], v158 offset:53248
	ds_read_b128 v[200:203], v158 offset:54272
	ds_read_b128 v[204:207], v158 offset:55296
	global_load_lds_dwordx4 v138, s[100:101]
	s_mov_b32 m0, s47
	ds_read_b128 v[208:211], v158 offset:56320
	global_load_lds_dwordx4 v134, s[100:101]
	s_barrier
	s_waitcnt lgkmcnt(0)
	v_mfma_f32_16x16x32_bf16 v[60:63], v[128:131], v[164:167], v[60:63]
	v_mfma_f32_16x16x32_bf16 v[56:59], v[150:153], v[164:167], v[56:59]
	v_mfma_f32_16x16x32_bf16 v[44:47], v[128:131], v[172:175], v[44:47]
	v_mfma_f32_16x16x32_bf16 v[40:43], v[150:153], v[172:175], v[40:43]
	v_mfma_f32_16x16x32_bf16 v[28:31], v[128:131], v[196:199], v[28:31]
	v_mfma_f32_16x16x32_bf16 v[24:27], v[150:153], v[196:199], v[24:27]
	v_mfma_f32_16x16x32_bf16 v[12:15], v[128:131], v[204:207], v[12:15]
	v_mfma_f32_16x16x32_bf16 v[8:11], v[150:153], v[204:207], v[8:11]
	v_mfma_f32_16x16x32_bf16 v[60:63], v[146:149], v[168:171], v[60:63]
	v_mfma_f32_16x16x32_bf16 v[56:59], v[160:163], v[168:171], v[56:59]
	v_mfma_f32_16x16x32_bf16 v[44:47], v[146:149], v[176:179], v[44:47]
	v_mfma_f32_16x16x32_bf16 v[40:43], v[160:163], v[176:179], v[40:43]
	v_mfma_f32_16x16x32_bf16 v[28:31], v[146:149], v[200:203], v[28:31]
	v_mfma_f32_16x16x32_bf16 v[24:27], v[160:163], v[200:203], v[24:27]
	v_mfma_f32_16x16x32_bf16 v[12:15], v[146:149], v[208:211], v[12:15]
	v_mfma_f32_16x16x32_bf16 v[8:11], v[160:163], v[208:211], v[8:11]
	s_barrier
	s_add_u32 s4, s4, 0x40080
	s_addc_u32 s5, s5, 0
	s_add_i32 s20, s34, 0x1c000
	s_mov_b32 m0, s20
	s_nop 0
	global_load_lds_dwordx4 v136, s[4:5]
	s_add_i32 m0, s20, 0x2000
	s_nop 0
	global_load_lds_dwordx4 v132, s[4:5]
	s_waitcnt vmcnt(6)
	s_barrier
	v_mfma_f32_16x16x32_bf16 v[52:55], v[212:215], v[164:167], v[52:55]
	v_mfma_f32_16x16x32_bf16 v[48:51], v[220:223], v[164:167], v[48:51]
	v_mfma_f32_16x16x32_bf16 v[36:39], v[212:215], v[172:175], v[36:39]
	v_mfma_f32_16x16x32_bf16 v[32:35], v[220:223], v[172:175], v[32:35]
	v_mfma_f32_16x16x32_bf16 v[20:23], v[212:215], v[196:199], v[20:23]
	v_mfma_f32_16x16x32_bf16 v[16:19], v[220:223], v[196:199], v[16:19]
	v_mfma_f32_16x16x32_bf16 v[4:7], v[212:215], v[204:207], v[4:7]
	v_mfma_f32_16x16x32_bf16 v[0:3], v[220:223], v[204:207], v[0:3]
	v_mfma_f32_16x16x32_bf16 v[52:55], v[216:219], v[168:171], v[52:55]
	v_mfma_f32_16x16x32_bf16 v[48:51], v[224:227], v[168:171], v[48:51]
	v_mfma_f32_16x16x32_bf16 v[36:39], v[216:219], v[176:179], v[36:39]
	v_mfma_f32_16x16x32_bf16 v[32:35], v[224:227], v[176:179], v[32:35]
	v_mfma_f32_16x16x32_bf16 v[20:23], v[216:219], v[200:203], v[20:23]
	v_mfma_f32_16x16x32_bf16 v[16:19], v[224:227], v[200:203], v[16:19]
	v_mfma_f32_16x16x32_bf16 v[4:7], v[216:219], v[208:211], v[4:7]
	v_mfma_f32_16x16x32_bf16 v[0:3], v[224:227], v[208:211], v[0:3]
	s_add_i32 s50, s50, 2
	s_add_u32 s2, s2, 0x100
	s_addc_u32 s3, s3, 0
	s_add_u32 s37, s37, 0x100
	s_addc_u32 s49, s49, 0
	s_cmp_gt_u32 s50, 13
	s_barrier
	s_cbranch_scc0 .LBB0_370
	v_mov_b32_e32 v128, v182
	s_lshl_b32 s2, s22, 10
	v_and_or_b32 v160, v128, 15, s44
	v_lshrrev_b32_e32 v128, 1, v128
	s_add_i32 s2, s2, 0
	v_and_b32_e32 v146, 24, v128
	v_lshl_add_u32 v128, v160, 2, s2
	v_add_u32_e32 v159, 0x20000, v128
	s_lshl_b32 s13, s28, 8
	s_lshl_b32 s3, s23, 8
	ds_read_b32 v154, v159
	v_add_u32_e32 v150, s13, v160
	s_or_b32 s20, s3, s45
	v_ashrrev_i32_e32 v151, 31, v150
	s_cmpk_gt_i32 s20, 0x3ff
	v_lshlrev_b64 v[128:129], 11, v[150:151]
	v_or_b32_e32 v148, s20, v146
	s_cselect_b64 s[4:5], -1, 0
	s_cmpk_gt_u32 s3, 0x7ff
	s_cselect_b64 s[2:3], -1, 0
	v_mov_b32_e32 v144, v148
	v_lshl_add_u64 v[152:153], s[10:11], 0, v[128:129]
	s_mov_b64 s[22:23], -1
	s_and_b64 vcc, exec, s[4:5]
	s_cbranch_vccz .LBB0_377
	s_waitcnt lgkmcnt(0)
	v_pk_mul_f32 v[128:129], v[124:125], v[154:155] op_sel_hi:[1,0]
	v_pk_mul_f32 v[130:131], v[126:127], v[154:155] op_sel_hi:[1,0]
	v_cvt_pk_bf16_f32 v128, v128, v129
	v_cvt_pk_bf16_f32 v129, v130, v131
	v_pk_mul_f32 v[130:131], v[120:121], v[154:155] op_sel_hi:[1,0]
	v_pk_mul_f32 v[162:163], v[122:123], v[154:155] op_sel_hi:[1,0]
	v_lshl_add_u64 v[156:157], v[144:145], 1, v[152:153]
	v_cvt_pk_bf16_f32 v130, v130, v131
	v_cvt_pk_bf16_f32 v131, v162, v163
	s_and_b64 vcc, exec, s[2:3]
	s_cbranch_vccz .LBB0_374
	v_add_co_u32_e32 v162, vcc, 0x7fff000, v156
	s_mov_b64 s[22:23], 0
	s_nop 0
	v_addc_co_u32_e32 v163, vcc, 0, v157, vcc
	global_store_dwordx4 v[162:163], v[128:131], off

; #define PG8_STAGE(bufoff, gbase, voff) do { _Pragma("unroll") for (int _i = 0; _i < 2; ++_i) \
;     __builtin_amdgcn_global_load_lds((const unsigned*)((const char*)(gbase) + (voff)[_i]), (LAS unsigned*)(lds + (bufoff) + ldsw + _i * 8192), 16, 0, 0); } while (0)
; #define PG8_LDA(dst, b, h) do { _Pragma("unroll") for (int m = 0; m < 4; ++m) _Pragma("unroll") for (int k = 0; k < 2; ++k) dst[m][k] = *(const LAS bf16x8*)(lds + PG8_SA(b, h) + aoff + m * 2048 + k * 1024); } while (0)
; #define PG8_LDB(dst, b, h) do { _Pragma("unroll") for (int n = 0; n < 2; ++n) _Pragma("unroll") for (int k = 0; k < 2; ++k) dst[n][k] = *(const LAS bf16x8*)(lds + PG8_SB(b, h) + boff + n * 2048 + k * 1024); } while (0)
; #define PG8_MMA(ai, bj, At, Bt) do { __builtin_amdgcn_s_setprio(1); _Pragma("unroll") for (int m = 0; m < 4; ++m) _Pragma("unroll") for (int n = 0; n < 2; ++n) _Pragma("unroll") for (int k = 0; k < 2; ++k) \
;     acc[ai][bj][m][n] = __builtin_amdgcn_mfma_f32_16x16x32_bf16(Bt[n][k], At[m][k], acc[ai][bj][m][n], 0, 0, 0); __builtin_amdgcn_s_setprio(0); } while (0)
; #define PG8_WAIT_V(n) asm volatile("s_waitcnt vmcnt(" #n ")" ::: "memory")
; #define PG8_WAIT_L(n) asm volatile("s_waitcnt lgkmcnt(" #n ")" ::: "memory")
; #define PG8_BAR __builtin_amdgcn_s_barrier()
; #define PG8_SCHED __builtin_amdgcn_sched_barrier(0)
; template <class Epi, class Sched>
; DI void gemm_phase(LAS unsigned char* lds, const Gemm g, const Sched& S, const Epi& E) {
;     ...
;     for (int t = 0; t < nt; t += 2) {
;       const bool last = (t == nt - 2);
;       const char* a1 = cA + (size_t)(t + 1) * kstep;
;       const char* a2 = last ? nA : cA + (size_t)(t + 2) * kstep; const char* b2 = last ? nB : cB + (size_t)(t + 2) * kstep;
;       const char* a3 = a2 + kstep; const char* b3 = b2 + kstep;
;       PG8_LDB(B0, 0, 0); PG8_SCHED; PG8_LDA(At, 0, 0); PG8_STAGE(PG8_SA(1, 1), a1 + hstep, voffA);
;       PG8_WAIT_L(8); PG8_BAR; PG8_WAIT_L(0); PG8_MMA(0, 0, At, B0); PG8_BAR; PG8_SCHED;
;       PG8_LDB(B1, 0, 1); PG8_STAGE(PG8_SB(0, 0), b2, voffB);
;       PG8_BAR; PG8_WAIT_L(0); PG8_MMA(0, 1, At, B1); PG8_BAR;
;       PG8_LDA(At, 0, 1); PG8_STAGE(PG8_SA(0, 0), a2, voffA);
;       PG8_BAR; PG8_WAIT_L(0); PG8_MMA(1, 0, At, B0); PG8_BAR; PG8_SCHED;
;       PG8_STAGE(PG8_SB(0, 1), b2 + hstep, voffB);
;       PG8_WAIT_V(6); PG8_BAR; PG8_MMA(1, 1, At, B1); PG8_BAR;
.LBB0_689:
	s_add_u32 s22, s20, 0xfffc0080
	s_addc_u32 s23, s21, -1
	ds_read_b128 v[128:131], v222
	ds_read_b128 v[132:135], v222 offset:1024
	ds_read_b128 v[150:153], v222 offset:2048
	ds_read_b128 v[154:157], v222 offset:3072
	s_cmp_eq_u32 s41, 12
	s_cselect_b32 s29, s13, s23
	s_cselect_b32 s28, s37, s22
	s_cselect_b32 s23, s15, s40
	s_cselect_b32 s22, s38, s39
	s_add_i32 m0, s56, 0xc000
	ds_read_b128 v[158:161], v197
	ds_read_b128 v[162:165], v197 offset:1024
	ds_read_b128 v[166:169], v197 offset:2048
	ds_read_b128 v[170:173], v197 offset:3072
	ds_read_b128 v[174:177], v197 offset:4096
	ds_read_b128 v[178:181], v197 offset:5120
	ds_read_b128 v[198:201], v197 offset:6144
	global_load_lds_dwordx4 v146, s[20:21]
	s_add_i32 m0, s56, 0xe000
	ds_read_b128 v[202:205], v197 offset:7168
	global_load_lds_dwordx4 v148, s[20:21]
	s_waitcnt lgkmcnt(8)
	s_barrier
	s_waitcnt lgkmcnt(0)
	v_mfma_f32_16x16x32_bf16 v[124:127], v[128:131], v[158:161], v[124:127]
	v_mfma_f32_16x16x32_bf16 v[120:123], v[150:153], v[158:161], v[120:123]
	v_mfma_f32_16x16x32_bf16 v[108:111], v[128:131], v[166:169], v[108:111]
	v_mfma_f32_16x16x32_bf16 v[104:107], v[150:153], v[166:169], v[104:107]
	v_mfma_f32_16x16x32_bf16 v[92:95], v[128:131], v[174:177], v[92:95]
	v_mfma_f32_16x16x32_bf16 v[88:91], v[150:153], v[174:177], v[88:91]
	v_mfma_f32_16x16x32_bf16 v[76:79], v[128:131], v[198:201], v[76:79]
	v_mfma_f32_16x16x32_bf16 v[72:75], v[150:153], v[198:201], v[72:75]
	v_mfma_f32_16x16x32_bf16 v[124:127], v[132:135], v[162:165], v[124:127]
	v_mfma_f32_16x16x32_bf16 v[120:123], v[154:157], v[162:165], v[120:123]
	v_mfma_f32_16x16x32_bf16 v[108:111], v[132:135], v[170:173], v[108:111]
	v_mfma_f32_16x16x32_bf16 v[104:107], v[154:157], v[170:173], v[104:107]
	v_mfma_f32_16x16x32_bf16 v[92:95], v[132:135], v[178:181], v[92:95]
	v_mfma_f32_16x16x32_bf16 v[88:91], v[154:157], v[178:181], v[88:91]
	v_mfma_f32_16x16x32_bf16 v[76:79], v[132:135], v[202:205], v[76:79]
	v_mfma_f32_16x16x32_bf16 v[72:75], v[154:157], v[202:205], v[72:75]
	s_barrier
	s_add_i32 s42, s52, 0x10000
	s_add_u32 vcc_lo, s22, s0
	s_addc_u32 vcc_hi, s23, s1
	s_mov_b32 m0, s42
	ds_read_b128 v[206:209], v223
	ds_read_b128 v[210:213], v223 offset:1024
	ds_read_b128 v[214:217], v223 offset:2048
	global_load_lds_dwordx4 v140, s[22:23]
	s_add_i32 m0, s42, 0x2000
	ds_read_b128 v[218:221], v223 offset:3072
	global_load_lds_dwordx4 v136, s[22:23]
	s_barrier
	s_waitcnt lgkmcnt(0)
	v_mfma_f32_16x16x32_bf16 v[116:119], v[206:209], v[158:161], v[116:119]
	v_mfma_f32_16x16x32_bf16 v[112:115], v[214:217], v[158:161], v[112:115]
	v_mfma_f32_16x16x32_bf16 v[100:103], v[206:209], v[166:169], v[100:103]
	v_mfma_f32_16x16x32_bf16 v[96:99], v[214:217], v[166:169], v[96:99]
	v_mfma_f32_16x16x32_bf16 v[84:87], v[206:209], v[174:177], v[84:87]
	v_mfma_f32_16x16x32_bf16 v[80:83], v[214:217], v[174:177], v[80:83]
	v_mfma_f32_16x16x32_bf16 v[68:71], v[206:209], v[198:201], v[68:71]
	v_mfma_f32_16x16x32_bf16 v[64:67], v[214:217], v[198:201], v[64:67]
	v_mfma_f32_16x16x32_bf16 v[116:119], v[210:213], v[162:165], v[116:119]
	v_mfma_f32_16x16x32_bf16 v[112:115], v[218:221], v[162:165], v[112:115]
	v_mfma_f32_16x16x32_bf16 v[100:103], v[210:213], v[170:173], v[100:103]
	v_mfma_f32_16x16x32_bf16 v[96:99], v[218:221], v[170:173], v[96:99]
	v_mfma_f32_16x16x32_bf16 v[84:87], v[210:213], v[178:181], v[84:87]
	v_mfma_f32_16x16x32_bf16 v[80:83], v[218:221], v[178:181], v[80:83]
	v_mfma_f32_16x16x32_bf16 v[68:71], v[210:213], v[202:205], v[68:71]
	v_mfma_f32_16x16x32_bf16 v[64:67], v[218:221], v[202:205], v[64:67]
	s_mov_b32 m0, s56
	s_add_u32 s100, s28, s0
	s_addc_u32 s101, s29, s1
	s_barrier
	ds_read_b128 v[158:161], v197 offset:16384
	ds_read_b128 v[162:165], v197 offset:17408
	ds_read_b128 v[166:169], v197 offset:18432
	ds_read_b128 v[170:173], v197 offset:19456
	ds_read_b128 v[174:177], v197 offset:20480
	ds_read_b128 v[178:181], v197 offset:21504
	ds_read_b128 v[198:201], v197 offset:22528
	global_load_lds_dwordx4 v142, s[28:29]
	s_mov_b32 m0, s57
	ds_read_b128 v[202:205], v197 offset:23552
	global_load_lds_dwordx4 v138, s[28:29]
	s_barrier
	s_waitcnt lgkmcnt(0)
	v_mfma_f32_16x16x32_bf16 v[60:63], v[128:131], v[158:161], v[60:63]
	v_mfma_f32_16x16x32_bf16 v[56:59], v[150:153], v[158:161], v[56:59]
	v_mfma_f32_16x16x32_bf16 v[44:47], v[128:131], v[166:169], v[44:47]
	v_mfma_f32_16x16x32_bf16 v[40:43], v[150:153], v[166:169], v[40:43]
	v_mfma_f32_16x16x32_bf16 v[28:31], v[128:131], v[174:177], v[28:31]
	v_mfma_f32_16x16x32_bf16 v[24:27], v[150:153], v[174:177], v[24:27]
	v_mfma_f32_16x16x32_bf16 v[12:15], v[128:131], v[198:201], v[12:15]
	v_mfma_f32_16x16x32_bf16 v[8:11], v[150:153], v[198:201], v[8:11]
	v_mfma_f32_16x16x32_bf16 v[60:63], v[132:135], v[162:165], v[60:63]
	v_mfma_f32_16x16x32_bf16 v[56:59], v[154:157], v[162:165], v[56:59]
	v_mfma_f32_16x16x32_bf16 v[44:47], v[132:135], v[170:173], v[44:47]
	v_mfma_f32_16x16x32_bf16 v[40:43], v[154:157], v[170:173], v[40:43]
	v_mfma_f32_16x16x32_bf16 v[28:31], v[132:135], v[178:181], v[28:31]
	v_mfma_f32_16x16x32_bf16 v[24:27], v[154:157], v[178:181], v[24:27]
	v_mfma_f32_16x16x32_bf16 v[12:15], v[132:135], v[202:205], v[12:15]
	v_mfma_f32_16x16x32_bf16 v[8:11], v[154:157], v[202:205], v[8:11]
	s_barrier
	s_add_u32 s42, s22, 0x40000
	s_addc_u32 s43, s23, 0
	s_add_i32 s44, s52, 0x14000
	s_mov_b32 m0, s44
	s_nop 0
	global_load_lds_dwordx4 v140, s[42:43]
	s_add_i32 m0, s44, 0x2000
	s_nop 0
	global_load_lds_dwordx4 v136, s[42:43]
	s_waitcnt vmcnt(6)
	s_barrier
; #define PG8_STAGE(bufoff, gbase, voff) do { _Pragma("unroll") for (int _i = 0; _i < 2; ++_i) \
;     __builtin_amdgcn_global_load_lds((const unsigned*)((const char*)(gbase) + (voff)[_i]), (LAS unsigned*)(lds + (bufoff) + ldsw + _i * 8192), 16, 0, 0); } while (0)
; #define PG8_LDA(dst, b, h) do { _Pragma("unroll") for (int m = 0; m < 4; ++m) _Pragma("unroll") for (int k = 0; k < 2; ++k) dst[m][k] = *(const LAS bf16x8*)(lds + PG8_SA(b, h) + aoff + m * 2048 + k * 1024); } while (0)
; #define PG8_LDB(dst, b, h) do { _Pragma("unroll") for (int n = 0; n < 2; ++n) _Pragma("unroll") for (int k = 0; k < 2; ++k) dst[n][k] = *(const LAS bf16x8*)(lds + PG8_SB(b, h) + boff + n * 2048 + k * 1024); } while (0)
; #define PG8_MMA(ai, bj, At, Bt) do { __builtin_amdgcn_s_setprio(1); _Pragma("unroll") for (int m = 0; m < 4; ++m) _Pragma("unroll") for (int n = 0; n < 2; ++n) _Pragma("unroll") for (int k = 0; k < 2; ++k) \
;     acc[ai][bj][m][n] = __builtin_amdgcn_mfma_f32_16x16x32_bf16(Bt[n][k], At[m][k], acc[ai][bj][m][n], 0, 0, 0); __builtin_amdgcn_s_setprio(0); } while (0)
; #define PG8_WAIT_V(n) asm volatile("s_waitcnt vmcnt(" #n ")" ::: "memory")
; #define PG8_WAIT_L(n) asm volatile("s_waitcnt lgkmcnt(" #n ")" ::: "memory")
; #define PG8_BAR __builtin_amdgcn_s_barrier()
; #define PG8_SCHED __builtin_amdgcn_sched_barrier(0)
; template <class Epi, class Sched>
; DI void gemm_phase(LAS unsigned char* lds, const Gemm g, const Sched& S, const Epi& E) {
;     ...
;       PG8_WAIT_V(6); PG8_BAR; PG8_MMA(1, 1, At, B1); PG8_BAR;
;       PG8_LDB(B0, 1, 0); PG8_SCHED; PG8_LDA(At, 1, 0); PG8_STAGE(PG8_SA(0, 1), a2 + hstep, voffA);
;       PG8_WAIT_L(8); PG8_BAR; PG8_WAIT_L(0); PG8_MMA(0, 0, At, B0); PG8_BAR; PG8_SCHED;
;       PG8_LDB(B1, 1, 1); PG8_STAGE(PG8_SB(1, 0), b3, voffB);
;       PG8_BAR; PG8_WAIT_L(0); PG8_MMA(0, 1, At, B1); PG8_BAR;
;       PG8_LDA(At, 1, 1); PG8_STAGE(PG8_SA(1, 0), a3, voffA);
;       PG8_BAR; PG8_WAIT_L(0); PG8_MMA(1, 0, At, B0); PG8_BAR; PG8_SCHED;
	v_mfma_f32_16x16x32_bf16 v[52:55], v[206:209], v[158:161], v[52:55]
	v_mfma_f32_16x16x32_bf16 v[48:51], v[214:217], v[158:161], v[48:51]
	v_mfma_f32_16x16x32_bf16 v[36:39], v[206:209], v[166:169], v[36:39]
	v_mfma_f32_16x16x32_bf16 v[32:35], v[214:217], v[166:169], v[32:35]
	v_mfma_f32_16x16x32_bf16 v[20:23], v[206:209], v[174:177], v[20:23]
	v_mfma_f32_16x16x32_bf16 v[16:19], v[214:217], v[174:177], v[16:19]
	v_mfma_f32_16x16x32_bf16 v[4:7], v[206:209], v[198:201], v[4:7]
	v_mfma_f32_16x16x32_bf16 v[0:3], v[214:217], v[198:201], v[0:3]
	v_mfma_f32_16x16x32_bf16 v[52:55], v[210:213], v[162:165], v[52:55]
	v_mfma_f32_16x16x32_bf16 v[48:51], v[218:221], v[162:165], v[48:51]
	v_mfma_f32_16x16x32_bf16 v[36:39], v[210:213], v[170:173], v[36:39]
	v_mfma_f32_16x16x32_bf16 v[32:35], v[218:221], v[170:173], v[32:35]
	v_mfma_f32_16x16x32_bf16 v[20:23], v[210:213], v[178:181], v[20:23]
	v_mfma_f32_16x16x32_bf16 v[16:19], v[218:221], v[178:181], v[16:19]
	v_mfma_f32_16x16x32_bf16 v[4:7], v[210:213], v[202:205], v[4:7]
	v_mfma_f32_16x16x32_bf16 v[0:3], v[218:221], v[202:205], v[0:3]
	s_barrier
	ds_read_b128 v[128:131], v224
	ds_read_b128 v[132:135], v224 offset:1024
	ds_read_b128 v[150:153], v224 offset:2048
	ds_read_b128 v[154:157], v224 offset:3072
	s_add_u32 s28, s28, 0x40000
	s_addc_u32 s29, s29, 0
	s_mov_b32 m0, s58
	ds_read_b128 v[158:161], v197 offset:32768
	ds_read_b128 v[162:165], v197 offset:33792
	ds_read_b128 v[166:169], v197 offset:34816
	ds_read_b128 v[170:173], v197 offset:35840
	ds_read_b128 v[174:177], v197 offset:36864
	ds_read_b128 v[178:181], v197 offset:37888
	ds_read_b128 v[198:201], v197 offset:38912
	global_load_lds_dwordx4 v142, s[28:29]
	s_mov_b32 m0, s59
	ds_read_b128 v[202:205], v197 offset:39936
	global_load_lds_dwordx4 v138, s[28:29]
	s_waitcnt lgkmcnt(8)
	s_barrier
	s_waitcnt lgkmcnt(0)
	v_mfma_f32_16x16x32_bf16 v[124:127], v[128:131], v[158:161], v[124:127]
	v_mfma_f32_16x16x32_bf16 v[120:123], v[150:153], v[158:161], v[120:123]
	v_mfma_f32_16x16x32_bf16 v[108:111], v[128:131], v[166:169], v[108:111]
	v_mfma_f32_16x16x32_bf16 v[104:107], v[150:153], v[166:169], v[104:107]
	v_mfma_f32_16x16x32_bf16 v[92:95], v[128:131], v[174:177], v[92:95]
	v_mfma_f32_16x16x32_bf16 v[88:91], v[150:153], v[174:177], v[88:91]
	v_mfma_f32_16x16x32_bf16 v[76:79], v[128:131], v[198:201], v[76:79]
	v_mfma_f32_16x16x32_bf16 v[72:75], v[150:153], v[198:201], v[72:75]
	v_mfma_f32_16x16x32_bf16 v[124:127], v[132:135], v[162:165], v[124:127]
	v_mfma_f32_16x16x32_bf16 v[120:123], v[154:157], v[162:165], v[120:123]
	v_mfma_f32_16x16x32_bf16 v[108:111], v[132:135], v[170:173], v[108:111]
	v_mfma_f32_16x16x32_bf16 v[104:107], v[154:157], v[170:173], v[104:107]
	v_mfma_f32_16x16x32_bf16 v[92:95], v[132:135], v[178:181], v[92:95]
	v_mfma_f32_16x16x32_bf16 v[88:91], v[154:157], v[178:181], v[88:91]
	v_mfma_f32_16x16x32_bf16 v[76:79], v[132:135], v[202:205], v[76:79]
	v_mfma_f32_16x16x32_bf16 v[72:75], v[154:157], v[202:205], v[72:75]
	s_barrier
	s_add_i32 s29, s52, 0x18000
	s_mov_b32 m0, s29
	ds_read_b128 v[206:209], v225
	ds_read_b128 v[210:213], v225 offset:1024
	ds_read_b128 v[214:217], v225 offset:2048
	global_load_lds_dwordx4 v140, vcc
	s_add_i32 m0, s29, 0x2000
	ds_read_b128 v[218:221], v225 offset:3072
	global_load_lds_dwordx4 v136, vcc
	s_barrier
	s_waitcnt lgkmcnt(0)
	v_mfma_f32_16x16x32_bf16 v[116:119], v[206:209], v[158:161], v[116:119]
	v_mfma_f32_16x16x32_bf16 v[112:115], v[214:217], v[158:161], v[112:115]
	v_mfma_f32_16x16x32_bf16 v[100:103], v[206:209], v[166:169], v[100:103]
	v_mfma_f32_16x16x32_bf16 v[96:99], v[214:217], v[166:169], v[96:99]
	v_mfma_f32_16x16x32_bf16 v[84:87], v[206:209], v[174:177], v[84:87]
	v_mfma_f32_16x16x32_bf16 v[80:83], v[214:217], v[174:177], v[80:83]
	v_mfma_f32_16x16x32_bf16 v[68:71], v[206:209], v[198:201], v[68:71]
	v_mfma_f32_16x16x32_bf16 v[64:67], v[214:217], v[198:201], v[64:67]
	v_mfma_f32_16x16x32_bf16 v[116:119], v[210:213], v[162:165], v[116:119]
	v_mfma_f32_16x16x32_bf16 v[112:115], v[218:221], v[162:165], v[112:115]
	v_mfma_f32_16x16x32_bf16 v[100:103], v[210:213], v[170:173], v[100:103]
	v_mfma_f32_16x16x32_bf16 v[96:99], v[218:221], v[170:173], v[96:99]
	v_mfma_f32_16x16x32_bf16 v[84:87], v[210:213], v[178:181], v[84:87]
	v_mfma_f32_16x16x32_bf16 v[80:83], v[218:221], v[178:181], v[80:83]
	v_mfma_f32_16x16x32_bf16 v[68:71], v[210:213], v[202:205], v[68:71]
	v_mfma_f32_16x16x32_bf16 v[64:67], v[218:221], v[202:205], v[64:67]
	s_mov_b32 m0, s62
	s_barrier
	ds_read_b128 v[158:161], v197 offset:49152
	ds_read_b128 v[162:165], v197 offset:50176
	ds_read_b128 v[166:169], v197 offset:51200
	ds_read_b128 v[170:173], v197 offset:52224
	ds_read_b128 v[174:177], v197 offset:53248
	ds_read_b128 v[178:181], v197 offset:54272
	ds_read_b128 v[198:201], v197 offset:55296
	global_load_lds_dwordx4 v142, s[100:101]
	s_mov_b32 m0, s63
	ds_read_b128 v[202:205], v197 offset:56320
	global_load_lds_dwordx4 v138, s[100:101]
	s_barrier
; #define PG8_STAGE(bufoff, gbase, voff) do { _Pragma("unroll") for (int _i = 0; _i < 2; ++_i) \
;     __builtin_amdgcn_global_load_lds((const unsigned*)((const char*)(gbase) + (voff)[_i]), (LAS unsigned*)(lds + (bufoff) + ldsw + _i * 8192), 16, 0, 0); } while (0)
; #define PG8_MMA(ai, bj, At, Bt) do { __builtin_amdgcn_s_setprio(1); _Pragma("unroll") for (int m = 0; m < 4; ++m) _Pragma("unroll") for (int n = 0; n < 2; ++n) _Pragma("unroll") for (int k = 0; k < 2; ++k) \
;     acc[ai][bj][m][n] = __builtin_amdgcn_mfma_f32_16x16x32_bf16(Bt[n][k], At[m][k], acc[ai][bj][m][n], 0, 0, 0); __builtin_amdgcn_s_setprio(0); } while (0)
; #define PG8_WAIT_V(n) asm volatile("s_waitcnt vmcnt(" #n ")" ::: "memory")
; #define PG8_WAIT_L(n) asm volatile("s_waitcnt lgkmcnt(" #n ")" ::: "memory")
; #define PG8_BAR __builtin_amdgcn_s_barrier()
; template <class Epi, class Sched>
; DI void gemm_phase(LAS unsigned char* lds, const Gemm g, const Sched& S, const Epi& E) {
;     ...
;       PG8_BAR; PG8_WAIT_L(0); PG8_MMA(1, 0, At, B0); PG8_BAR; PG8_SCHED;
;       PG8_STAGE(PG8_SB(1, 1), b3 + hstep, voffB);
;       PG8_WAIT_V(6); PG8_BAR; PG8_MMA(1, 1, At, B1); PG8_BAR;
;     }
;   DI void operator()(const f32x4 (&acc)[2][2][4][2], const pg8::Unit& u, int wr, int wc, int fr_, int fq_) const {
;     ...
;             if (EPI == EPI_ABIN) {
;               if (n == 0) {
;                 const int gb = u.pn * 256 + bj * 128 + wc * 32; const int f8 = gb + 8 * fq;
;                 const f32x4 v1 = acc[ai][bj][m][1];
;                 if (gb < 384) st_bf8((u16*)(big + E_CQ) + (size_t)token * 384 + f8, v, v1, rinv);
;                 else if (gb < 640) st_bf8((u16*)(big + E_CKV) + (size_t)token * 256 + (f8 - 384), v, v1, rinv);
;                 else if (gb < 672) {
;                   f32x4 a0 = v, a1 = v1;
;                   rope_perm(a0, a1, fq, t_ & 63, tcos, tsin, token & (S_ - 1));
;                   st_bf8((u16*)(big + E_KPE) + (size_t)token * 32 + 8 * fq, a0, a1, rinv);
;                 }
;                 else if (gb < 1184) st_bf8((u16*)(big + E_QNA) + (size_t)token * 512 + (f8 - 672), v, v1, rinv * (0.125f * LOG2E));
;                 else if (gb < 1696) st_bf8((u16*)(big + E_KNA) + (size_t)token * 512 + (f8 - 1184), v, v1, rinv);
;                 else if (gb < 2208) st_bf8((u16*)(big + E_VNAT) + (size_t)token * 512 + (f8 - 1696), v, v1, rinv);
;               }
	s_waitcnt lgkmcnt(0)
	v_mfma_f32_16x16x32_bf16 v[60:63], v[128:131], v[158:161], v[60:63]
	v_mfma_f32_16x16x32_bf16 v[56:59], v[150:153], v[158:161], v[56:59]
	v_mfma_f32_16x16x32_bf16 v[44:47], v[128:131], v[166:169], v[44:47]
	v_mfma_f32_16x16x32_bf16 v[40:43], v[150:153], v[166:169], v[40:43]
	v_mfma_f32_16x16x32_bf16 v[28:31], v[128:131], v[174:177], v[28:31]
	v_mfma_f32_16x16x32_bf16 v[24:27], v[150:153], v[174:177], v[24:27]
	v_mfma_f32_16x16x32_bf16 v[12:15], v[128:131], v[198:201], v[12:15]
	v_mfma_f32_16x16x32_bf16 v[8:11], v[150:153], v[198:201], v[8:11]
	v_mfma_f32_16x16x32_bf16 v[60:63], v[132:135], v[162:165], v[60:63]
	v_mfma_f32_16x16x32_bf16 v[56:59], v[154:157], v[162:165], v[56:59]
	v_mfma_f32_16x16x32_bf16 v[44:47], v[132:135], v[170:173], v[44:47]
	v_mfma_f32_16x16x32_bf16 v[40:43], v[154:157], v[170:173], v[40:43]
	v_mfma_f32_16x16x32_bf16 v[28:31], v[132:135], v[178:181], v[28:31]
	v_mfma_f32_16x16x32_bf16 v[24:27], v[154:157], v[178:181], v[24:27]
	v_mfma_f32_16x16x32_bf16 v[12:15], v[132:135], v[202:205], v[12:15]
	v_mfma_f32_16x16x32_bf16 v[8:11], v[154:157], v[202:205], v[8:11]
	s_barrier
	s_add_u32 s22, s22, 0x40080
	s_addc_u32 s23, s23, 0
	s_add_i32 s28, s52, 0x1c000
	s_mov_b32 m0, s28
	s_nop 0
	global_load_lds_dwordx4 v140, s[22:23]
	s_add_i32 m0, s28, 0x2000
	s_nop 0
	global_load_lds_dwordx4 v136, s[22:23]
	s_waitcnt vmcnt(6)
	s_barrier
	v_mfma_f32_16x16x32_bf16 v[52:55], v[206:209], v[158:161], v[52:55]
	v_mfma_f32_16x16x32_bf16 v[48:51], v[214:217], v[158:161], v[48:51]
	v_mfma_f32_16x16x32_bf16 v[36:39], v[206:209], v[166:169], v[36:39]
	v_mfma_f32_16x16x32_bf16 v[32:35], v[214:217], v[166:169], v[32:35]
	v_mfma_f32_16x16x32_bf16 v[20:23], v[206:209], v[174:177], v[20:23]
	v_mfma_f32_16x16x32_bf16 v[16:19], v[214:217], v[174:177], v[16:19]
	v_mfma_f32_16x16x32_bf16 v[4:7], v[206:209], v[198:201], v[4:7]
	v_mfma_f32_16x16x32_bf16 v[0:3], v[214:217], v[198:201], v[0:3]
	v_mfma_f32_16x16x32_bf16 v[52:55], v[210:213], v[162:165], v[52:55]
	v_mfma_f32_16x16x32_bf16 v[48:51], v[218:221], v[162:165], v[48:51]
	v_mfma_f32_16x16x32_bf16 v[36:39], v[210:213], v[170:173], v[36:39]
	v_mfma_f32_16x16x32_bf16 v[32:35], v[218:221], v[170:173], v[32:35]
	v_mfma_f32_16x16x32_bf16 v[20:23], v[210:213], v[178:181], v[20:23]
	v_mfma_f32_16x16x32_bf16 v[16:19], v[218:221], v[178:181], v[16:19]
	v_mfma_f32_16x16x32_bf16 v[4:7], v[210:213], v[202:205], v[4:7]
	v_mfma_f32_16x16x32_bf16 v[0:3], v[218:221], v[202:205], v[0:3]
	s_add_i32 s41, s41, 2
	s_add_u32 s20, s20, 0x100
	s_addc_u32 s21, s21, 0
	s_add_u32 s39, s39, 0x100
	s_addc_u32 s40, s40, 0
	s_cmp_gt_u32 s41, 13
	s_barrier
	s_cbranch_scc0 .LBB0_689
	v_mov_b32_e32 v128, v182
	s_lshl_b32 s20, s34, 10
	v_bfe_u32 v129, v128, 4, 2
	v_and_or_b32 v201, v128, 15, s60
	s_lshl_b32 s13, s35, 8
	v_lshlrev_b32_e32 v128, 2, v128
	s_movk_i32 s21, 0x80
	s_add_i32 s20, s20, 0
	s_lshl_b32 s15, s36, 8
	v_bitop3_b32 v198, v128, s21, v190 bitop3:0x6c
	v_lshl_add_u32 v128, v201, 2, s20
	s_or_b32 s20, s13, s61
	v_add_u32_e32 v200, 0x20000, v128
	s_cmpk_gt_i32 s20, 0x17f
	ds_read_b32 v156, v200
	s_cselect_b64 s[28:29], -1, 0
	s_cmpk_gt_u32 s13, 0x27f
	s_cselect_b64 s[46:47], -1, 0
	s_cmpk_gt_u32 s20, 0x29f
	s_cselect_b64 s[40:41], -1, 0
	s_cmpk_gt_u32 s20, 0x49f
	v_lshlrev_b32_e32 v144, 3, v129
	v_add_u32_e32 v154, s15, v201
	s_cselect_b64 s[34:35], -1, 0
	s_cmpk_gt_u32 s20, 0x69f
	v_ashrrev_i32_e32 v155, 31, v154
	v_lshlrev_b32_e32 v128, 4, v154
	v_or_b32_e32 v150, s20, v144
	s_cselect_b64 s[22:23], -1, 0
	s_cmpk_lt_u32 s20, 0x8a0
	v_and_b32_e32 v199, 8, v144
	v_cmp_lt_u32_e64 s[92:93], 1, v129
	v_lshlrev_b64 v[164:165], 10, v[154:155]
	s_waitcnt lgkmcnt(0)
	v_mul_f32_e32 v162, 0x3e38aa3b, v156
	v_and_b32_e32 v157, 0xfcf0, v128
	v_lshlrev_b64 v[160:161], 6, v[154:155]
	v_lshlrev_b64 v[158:159], 9, v[154:155]
	s_cselect_b64 s[20:21], -1, 0
	v_mov_b32_e32 v152, v150
	v_mov_b32_e32 v153, v145
	s_mov_b64 s[36:37], -1
	s_and_b64 vcc, exec, s[28:29]
	s_cbranch_vccz .LBB0_714
	s_and_b64 vcc, exec, s[46:47]
	s_cbranch_vccz .LBB0_711
	s_and_b64 vcc, exec, s[40:41]
	s_cbranch_vccz .LBB0_704
	s_and_b64 vcc, exec, s[34:35]
	s_cbranch_vccz .LBB0_701
	s_and_b64 vcc, exec, s[22:23]
	s_cbranch_vccz .LBB0_698
	s_andn2_b64 vcc, exec, s[20:21]
	s_cbranch_vccnz .LBB0_697
	v_lshl_add_u64 v[128:129], s[2:3], 0, v[164:165]
	v_lshl_add_u64 v[132:133], v[152:153], 1, v[128:129]
	v_pk_mul_f32 v[128:129], v[124:125], v[156:157] op_sel_hi:[1,0]
	v_pk_mul_f32 v[130:131], v[126:127], v[156:157] op_sel_hi:[1,0]
	v_cvt_pk_bf16_f32 v128, v128, v129
	v_cvt_pk_bf16_f32 v129, v130, v131
	v_pk_mul_f32 v[130:131], v[120:121], v[156:157] op_sel_hi:[1,0]
	v_pk_mul_f32 v[134:135], v[122:123], v[156:157] op_sel_hi:[1,0]
	v_add_co_u32_e32 v132, vcc, 0x69ff000, v132
	v_cvt_pk_bf16_f32 v130, v130, v131
	v_cvt_pk_bf16_f32 v131, v134, v135
	v_addc_co_u32_e32 v133, vcc, 0, v133, vcc
	global_store_dwordx4 v[132:133], v[128:131], off offset:704

; #define PG8_STAGE(bufoff, gbase, voff) do { _Pragma("unroll") for (int _i = 0; _i < 2; ++_i) \
;     __builtin_amdgcn_global_load_lds((const unsigned*)((const char*)(gbase) + (voff)[_i]), (LAS unsigned*)(lds + (bufoff) + ldsw + _i * 8192), 16, 0, 0); } while (0)
; #define PG8_LDA(dst, b, h) do { _Pragma("unroll") for (int m = 0; m < 4; ++m) _Pragma("unroll") for (int k = 0; k < 2; ++k) dst[m][k] = *(const LAS bf16x8*)(lds + PG8_SA(b, h) + aoff + m * 2048 + k * 1024); } while (0)
; #define PG8_LDB(dst, b, h) do { _Pragma("unroll") for (int n = 0; n < 2; ++n) _Pragma("unroll") for (int k = 0; k < 2; ++k) dst[n][k] = *(const LAS bf16x8*)(lds + PG8_SB(b, h) + boff + n * 2048 + k * 1024); } while (0)
; #define PG8_MMA(ai, bj, At, Bt) do { __builtin_amdgcn_s_setprio(1); _Pragma("unroll") for (int m = 0; m < 4; ++m) _Pragma("unroll") for (int n = 0; n < 2; ++n) _Pragma("unroll") for (int k = 0; k < 2; ++k) \
;     acc[ai][bj][m][n] = __builtin_amdgcn_mfma_f32_16x16x32_bf16(Bt[n][k], At[m][k], acc[ai][bj][m][n], 0, 0, 0); __builtin_amdgcn_s_setprio(0); } while (0)
; #define PG8_WAIT_V(n) asm volatile("s_waitcnt vmcnt(" #n ")" ::: "memory")
; #define PG8_WAIT_L(n) asm volatile("s_waitcnt lgkmcnt(" #n ")" ::: "memory")
; #define PG8_BAR __builtin_amdgcn_s_barrier()
; #define PG8_SCHED __builtin_amdgcn_sched_barrier(0)
; template <class Epi, class Sched>
; DI void gemm_phase(LAS unsigned char* lds, const Gemm g, const Sched& S, const Epi& E) {
;     ...
;     for (int t = 0; t < nt; t += 2) {
;       const bool last = (t == nt - 2);
;       const char* a1 = cA + (size_t)(t + 1) * kstep;
;       const char* a2 = last ? nA : cA + (size_t)(t + 2) * kstep; const char* b2 = last ? nB : cB + (size_t)(t + 2) * kstep;
;       const char* a3 = a2 + kstep; const char* b3 = b2 + kstep;
;       PG8_LDB(B0, 0, 0); PG8_SCHED; PG8_LDA(At, 0, 0); PG8_STAGE(PG8_SA(1, 1), a1 + hstep, voffA);
;       PG8_WAIT_L(8); PG8_BAR; PG8_WAIT_L(0); PG8_MMA(0, 0, At, B0); PG8_BAR; PG8_SCHED;
;       PG8_LDB(B1, 0, 1); PG8_STAGE(PG8_SB(0, 0), b2, voffB);
;       PG8_BAR; PG8_WAIT_L(0); PG8_MMA(0, 1, At, B1); PG8_BAR;
;       PG8_LDA(At, 0, 1); PG8_STAGE(PG8_SA(0, 0), a2, voffA);
;       PG8_BAR; PG8_WAIT_L(0); PG8_MMA(1, 0, At, B0); PG8_BAR; PG8_SCHED;
;       PG8_STAGE(PG8_SB(0, 1), b2 + hstep, voffB);
;       PG8_WAIT_V(6); PG8_BAR; PG8_MMA(1, 1, At, B1); PG8_BAR;
.LBB0_1202:
	s_add_u32 s20, s18, 0x100
	s_addc_u32 s21, s19, 0
	ds_read_b128 v[140:143], v224
	ds_read_b128 v[146:149], v224 offset:1024
	ds_read_b128 v[150:153], v224 offset:2048
	ds_read_b128 v[154:157], v224 offset:3072
	s_cmp_eq_u32 s54, 2
	s_cselect_b32 s29, s3, s21
	s_cselect_b32 s28, s2, s20
	s_cselect_b32 s23, s5, s53
	s_cselect_b32 s22, s4, s52
	s_add_i32 m0, s38, 0xc000
	ds_read_b128 v[158:161], v163
	ds_read_b128 v[164:167], v163 offset:1024
	ds_read_b128 v[168:171], v163 offset:2048
	ds_read_b128 v[172:175], v163 offset:3072
	ds_read_b128 v[176:179], v163 offset:4096
	ds_read_b128 v[196:199], v163 offset:5120
	ds_read_b128 v[200:203], v163 offset:6144
	global_load_lds_dwordx4 v136, s[18:19]
	s_add_i32 m0, s38, 0xe000
	ds_read_b128 v[204:207], v163 offset:7168
	global_load_lds_dwordx4 v138, s[18:19]
	s_waitcnt lgkmcnt(8)
	s_barrier
	s_waitcnt lgkmcnt(0)
	v_mfma_f32_16x16x32_bf16 v[124:127], v[140:143], v[158:161], v[124:127]
	v_mfma_f32_16x16x32_bf16 v[120:123], v[150:153], v[158:161], v[120:123]
	v_mfma_f32_16x16x32_bf16 v[108:111], v[140:143], v[168:171], v[108:111]
	v_mfma_f32_16x16x32_bf16 v[104:107], v[150:153], v[168:171], v[104:107]
	v_mfma_f32_16x16x32_bf16 v[92:95], v[140:143], v[176:179], v[92:95]
	v_mfma_f32_16x16x32_bf16 v[88:91], v[150:153], v[176:179], v[88:91]
	v_mfma_f32_16x16x32_bf16 v[76:79], v[140:143], v[200:203], v[76:79]
	v_mfma_f32_16x16x32_bf16 v[72:75], v[150:153], v[200:203], v[72:75]
	v_mfma_f32_16x16x32_bf16 v[124:127], v[146:149], v[164:167], v[124:127]
	v_mfma_f32_16x16x32_bf16 v[120:123], v[154:157], v[164:167], v[120:123]
	v_mfma_f32_16x16x32_bf16 v[108:111], v[146:149], v[172:175], v[108:111]
	v_mfma_f32_16x16x32_bf16 v[104:107], v[154:157], v[172:175], v[104:107]
	v_mfma_f32_16x16x32_bf16 v[92:95], v[146:149], v[196:199], v[92:95]
	v_mfma_f32_16x16x32_bf16 v[88:91], v[154:157], v[196:199], v[88:91]
	v_mfma_f32_16x16x32_bf16 v[76:79], v[146:149], v[204:207], v[76:79]
	v_mfma_f32_16x16x32_bf16 v[72:75], v[154:157], v[204:207], v[72:75]
	s_barrier
	s_add_i32 s18, s35, 0x10000
	s_add_u32 vcc_lo, s22, s0
	s_addc_u32 vcc_hi, s23, s1
	s_mov_b32 m0, s18
	ds_read_b128 v[208:211], v225
	ds_read_b128 v[212:215], v225 offset:1024
	ds_read_b128 v[216:219], v225 offset:2048
	global_load_lds_dwordx4 v130, s[22:23]
	s_add_i32 m0, s18, 0x2000
	ds_read_b128 v[220:223], v225 offset:3072
	global_load_lds_dwordx4 v134, s[22:23]
	s_barrier
	s_waitcnt lgkmcnt(0)
	v_mfma_f32_16x16x32_bf16 v[116:119], v[208:211], v[158:161], v[116:119]
	v_mfma_f32_16x16x32_bf16 v[112:115], v[216:219], v[158:161], v[112:115]
	v_mfma_f32_16x16x32_bf16 v[100:103], v[208:211], v[168:171], v[100:103]
	v_mfma_f32_16x16x32_bf16 v[96:99], v[216:219], v[168:171], v[96:99]
	v_mfma_f32_16x16x32_bf16 v[84:87], v[208:211], v[176:179], v[84:87]
	v_mfma_f32_16x16x32_bf16 v[80:83], v[216:219], v[176:179], v[80:83]
	v_mfma_f32_16x16x32_bf16 v[68:71], v[208:211], v[200:203], v[68:71]
	v_mfma_f32_16x16x32_bf16 v[64:67], v[216:219], v[200:203], v[64:67]
	v_mfma_f32_16x16x32_bf16 v[116:119], v[212:215], v[164:167], v[116:119]
	v_mfma_f32_16x16x32_bf16 v[112:115], v[220:223], v[164:167], v[112:115]
	v_mfma_f32_16x16x32_bf16 v[100:103], v[212:215], v[172:175], v[100:103]
	v_mfma_f32_16x16x32_bf16 v[96:99], v[220:223], v[172:175], v[96:99]
	v_mfma_f32_16x16x32_bf16 v[84:87], v[212:215], v[196:199], v[84:87]
	v_mfma_f32_16x16x32_bf16 v[80:83], v[220:223], v[196:199], v[80:83]
	v_mfma_f32_16x16x32_bf16 v[68:71], v[212:215], v[204:207], v[68:71]
	v_mfma_f32_16x16x32_bf16 v[64:67], v[220:223], v[204:207], v[64:67]
	s_mov_b32 m0, s38
	s_add_u32 s100, s28, s0
	s_addc_u32 s101, s29, s1
	s_barrier
	ds_read_b128 v[158:161], v163 offset:16384
	ds_read_b128 v[164:167], v163 offset:17408
	ds_read_b128 v[168:171], v163 offset:18432
	ds_read_b128 v[172:175], v163 offset:19456
	ds_read_b128 v[176:179], v163 offset:20480
	ds_read_b128 v[196:199], v163 offset:21504
	ds_read_b128 v[200:203], v163 offset:22528
	global_load_lds_dwordx4 v128, s[28:29]
	s_mov_b32 m0, s39
	ds_read_b128 v[204:207], v163 offset:23552
	global_load_lds_dwordx4 v132, s[28:29]
	s_barrier
	s_waitcnt lgkmcnt(0)
	v_mfma_f32_16x16x32_bf16 v[60:63], v[140:143], v[158:161], v[60:63]
	v_mfma_f32_16x16x32_bf16 v[56:59], v[150:153], v[158:161], v[56:59]
	v_mfma_f32_16x16x32_bf16 v[44:47], v[140:143], v[168:171], v[44:47]
	v_mfma_f32_16x16x32_bf16 v[40:43], v[150:153], v[168:171], v[40:43]
	v_mfma_f32_16x16x32_bf16 v[28:31], v[140:143], v[176:179], v[28:31]
	v_mfma_f32_16x16x32_bf16 v[24:27], v[150:153], v[176:179], v[24:27]
	v_mfma_f32_16x16x32_bf16 v[12:15], v[140:143], v[200:203], v[12:15]
	v_mfma_f32_16x16x32_bf16 v[8:11], v[150:153], v[200:203], v[8:11]
	v_mfma_f32_16x16x32_bf16 v[60:63], v[146:149], v[164:167], v[60:63]
	v_mfma_f32_16x16x32_bf16 v[56:59], v[154:157], v[164:167], v[56:59]
	v_mfma_f32_16x16x32_bf16 v[44:47], v[146:149], v[172:175], v[44:47]
	v_mfma_f32_16x16x32_bf16 v[40:43], v[154:157], v[172:175], v[40:43]
	v_mfma_f32_16x16x32_bf16 v[28:31], v[146:149], v[196:199], v[28:31]
	v_mfma_f32_16x16x32_bf16 v[24:27], v[154:157], v[196:199], v[24:27]
	v_mfma_f32_16x16x32_bf16 v[12:15], v[146:149], v[204:207], v[12:15]
	v_mfma_f32_16x16x32_bf16 v[8:11], v[154:157], v[204:207], v[8:11]
	s_barrier
	s_add_u32 s18, s22, 0x18000
	s_addc_u32 s19, s23, 0
	s_add_i32 s55, s35, 0x14000
	s_mov_b32 m0, s55
	s_nop 0
	global_load_lds_dwordx4 v130, s[18:19]
	s_add_i32 m0, s55, 0x2000
	s_nop 0
	global_load_lds_dwordx4 v134, s[18:19]
	s_waitcnt vmcnt(6)
	s_barrier
; #define PG8_STAGE(bufoff, gbase, voff) do { _Pragma("unroll") for (int _i = 0; _i < 2; ++_i) \
;     __builtin_amdgcn_global_load_lds((const unsigned*)((const char*)(gbase) + (voff)[_i]), (LAS unsigned*)(lds + (bufoff) + ldsw + _i * 8192), 16, 0, 0); } while (0)
; #define PG8_LDA(dst, b, h) do { _Pragma("unroll") for (int m = 0; m < 4; ++m) _Pragma("unroll") for (int k = 0; k < 2; ++k) dst[m][k] = *(const LAS bf16x8*)(lds + PG8_SA(b, h) + aoff + m * 2048 + k * 1024); } while (0)
; #define PG8_LDB(dst, b, h) do { _Pragma("unroll") for (int n = 0; n < 2; ++n) _Pragma("unroll") for (int k = 0; k < 2; ++k) dst[n][k] = *(const LAS bf16x8*)(lds + PG8_SB(b, h) + boff + n * 2048 + k * 1024); } while (0)
; #define PG8_MMA(ai, bj, At, Bt) do { __builtin_amdgcn_s_setprio(1); _Pragma("unroll") for (int m = 0; m < 4; ++m) _Pragma("unroll") for (int n = 0; n < 2; ++n) _Pragma("unroll") for (int k = 0; k < 2; ++k) \
;     acc[ai][bj][m][n] = __builtin_amdgcn_mfma_f32_16x16x32_bf16(Bt[n][k], At[m][k], acc[ai][bj][m][n], 0, 0, 0); __builtin_amdgcn_s_setprio(0); } while (0)
; #define PG8_WAIT_V(n) asm volatile("s_waitcnt vmcnt(" #n ")" ::: "memory")
; #define PG8_WAIT_L(n) asm volatile("s_waitcnt lgkmcnt(" #n ")" ::: "memory")
; #define PG8_BAR __builtin_amdgcn_s_barrier()
; #define PG8_SCHED __builtin_amdgcn_sched_barrier(0)
; template <class Epi, class Sched>
; DI void gemm_phase(LAS unsigned char* lds, const Gemm g, const Sched& S, const Epi& E) {
;     ...
;       PG8_WAIT_V(6); PG8_BAR; PG8_MMA(1, 1, At, B1); PG8_BAR;
;       PG8_LDB(B0, 1, 0); PG8_SCHED; PG8_LDA(At, 1, 0); PG8_STAGE(PG8_SA(0, 1), a2 + hstep, voffA);
;       PG8_WAIT_L(8); PG8_BAR; PG8_WAIT_L(0); PG8_MMA(0, 0, At, B0); PG8_BAR; PG8_SCHED;
;       PG8_LDB(B1, 1, 1); PG8_STAGE(PG8_SB(1, 0), b3, voffB);
;       PG8_BAR; PG8_WAIT_L(0); PG8_MMA(0, 1, At, B1); PG8_BAR;
;       PG8_LDA(At, 1, 1); PG8_STAGE(PG8_SA(1, 0), a3, voffA);
;       PG8_BAR; PG8_WAIT_L(0); PG8_MMA(1, 0, At, B0); PG8_BAR; PG8_SCHED;
	v_mfma_f32_16x16x32_bf16 v[52:55], v[208:211], v[158:161], v[52:55]
	v_mfma_f32_16x16x32_bf16 v[48:51], v[216:219], v[158:161], v[48:51]
	v_mfma_f32_16x16x32_bf16 v[36:39], v[208:211], v[168:171], v[36:39]
	v_mfma_f32_16x16x32_bf16 v[32:35], v[216:219], v[168:171], v[32:35]
	v_mfma_f32_16x16x32_bf16 v[20:23], v[208:211], v[176:179], v[20:23]
	v_mfma_f32_16x16x32_bf16 v[16:19], v[216:219], v[176:179], v[16:19]
	v_mfma_f32_16x16x32_bf16 v[4:7], v[208:211], v[200:203], v[4:7]
	v_mfma_f32_16x16x32_bf16 v[0:3], v[216:219], v[200:203], v[0:3]
	v_mfma_f32_16x16x32_bf16 v[52:55], v[212:215], v[164:167], v[52:55]
	v_mfma_f32_16x16x32_bf16 v[48:51], v[220:223], v[164:167], v[48:51]
	v_mfma_f32_16x16x32_bf16 v[36:39], v[212:215], v[172:175], v[36:39]
	v_mfma_f32_16x16x32_bf16 v[32:35], v[220:223], v[172:175], v[32:35]
	v_mfma_f32_16x16x32_bf16 v[20:23], v[212:215], v[196:199], v[20:23]
	v_mfma_f32_16x16x32_bf16 v[16:19], v[220:223], v[196:199], v[16:19]
	v_mfma_f32_16x16x32_bf16 v[4:7], v[212:215], v[204:207], v[4:7]
	v_mfma_f32_16x16x32_bf16 v[0:3], v[220:223], v[204:207], v[0:3]
	s_barrier
	ds_read_b128 v[140:143], v226
	ds_read_b128 v[146:149], v226 offset:1024
	ds_read_b128 v[150:153], v226 offset:2048
	ds_read_b128 v[154:157], v226 offset:3072
	s_add_u32 s18, s28, 0x18000
	s_addc_u32 s19, s29, 0
	s_mov_b32 m0, s40
	ds_read_b128 v[158:161], v163 offset:32768
	ds_read_b128 v[164:167], v163 offset:33792
	ds_read_b128 v[168:171], v163 offset:34816
	ds_read_b128 v[172:175], v163 offset:35840
	ds_read_b128 v[176:179], v163 offset:36864
	ds_read_b128 v[196:199], v163 offset:37888
	ds_read_b128 v[200:203], v163 offset:38912
	global_load_lds_dwordx4 v128, s[18:19]
	s_mov_b32 m0, s41
	ds_read_b128 v[204:207], v163 offset:39936
	global_load_lds_dwordx4 v132, s[18:19]
	s_waitcnt lgkmcnt(8)
	s_barrier
	s_waitcnt lgkmcnt(0)
	v_mfma_f32_16x16x32_bf16 v[124:127], v[140:143], v[158:161], v[124:127]
	v_mfma_f32_16x16x32_bf16 v[120:123], v[150:153], v[158:161], v[120:123]
	v_mfma_f32_16x16x32_bf16 v[108:111], v[140:143], v[168:171], v[108:111]
	v_mfma_f32_16x16x32_bf16 v[104:107], v[150:153], v[168:171], v[104:107]
	v_mfma_f32_16x16x32_bf16 v[92:95], v[140:143], v[176:179], v[92:95]
	v_mfma_f32_16x16x32_bf16 v[88:91], v[150:153], v[176:179], v[88:91]
	v_mfma_f32_16x16x32_bf16 v[76:79], v[140:143], v[200:203], v[76:79]
	v_mfma_f32_16x16x32_bf16 v[72:75], v[150:153], v[200:203], v[72:75]
	v_mfma_f32_16x16x32_bf16 v[124:127], v[146:149], v[164:167], v[124:127]
	v_mfma_f32_16x16x32_bf16 v[120:123], v[154:157], v[164:167], v[120:123]
	v_mfma_f32_16x16x32_bf16 v[108:111], v[146:149], v[172:175], v[108:111]
	v_mfma_f32_16x16x32_bf16 v[104:107], v[154:157], v[172:175], v[104:107]
	v_mfma_f32_16x16x32_bf16 v[92:95], v[146:149], v[196:199], v[92:95]
	v_mfma_f32_16x16x32_bf16 v[88:91], v[154:157], v[196:199], v[88:91]
	v_mfma_f32_16x16x32_bf16 v[76:79], v[146:149], v[204:207], v[76:79]
	v_mfma_f32_16x16x32_bf16 v[72:75], v[154:157], v[204:207], v[72:75]
	s_barrier
	s_add_i32 s18, s35, 0x18000
	s_mov_b32 m0, s18
	ds_read_b128 v[208:211], v227
	ds_read_b128 v[212:215], v227 offset:1024
	ds_read_b128 v[216:219], v227 offset:2048
	global_load_lds_dwordx4 v130, vcc
	s_add_i32 m0, s18, 0x2000
	ds_read_b128 v[220:223], v227 offset:3072
	global_load_lds_dwordx4 v134, vcc
	s_barrier
	s_waitcnt lgkmcnt(0)
	v_mfma_f32_16x16x32_bf16 v[116:119], v[208:211], v[158:161], v[116:119]
	v_mfma_f32_16x16x32_bf16 v[112:115], v[216:219], v[158:161], v[112:115]
	v_mfma_f32_16x16x32_bf16 v[100:103], v[208:211], v[168:171], v[100:103]
	v_mfma_f32_16x16x32_bf16 v[96:99], v[216:219], v[168:171], v[96:99]
	v_mfma_f32_16x16x32_bf16 v[84:87], v[208:211], v[176:179], v[84:87]
	v_mfma_f32_16x16x32_bf16 v[80:83], v[216:219], v[176:179], v[80:83]
	v_mfma_f32_16x16x32_bf16 v[68:71], v[208:211], v[200:203], v[68:71]
	v_mfma_f32_16x16x32_bf16 v[64:67], v[216:219], v[200:203], v[64:67]
	v_mfma_f32_16x16x32_bf16 v[116:119], v[212:215], v[164:167], v[116:119]
	v_mfma_f32_16x16x32_bf16 v[112:115], v[220:223], v[164:167], v[112:115]
	v_mfma_f32_16x16x32_bf16 v[100:103], v[212:215], v[172:175], v[100:103]
	v_mfma_f32_16x16x32_bf16 v[96:99], v[220:223], v[172:175], v[96:99]
	v_mfma_f32_16x16x32_bf16 v[84:87], v[212:215], v[196:199], v[84:87]
	v_mfma_f32_16x16x32_bf16 v[80:83], v[220:223], v[196:199], v[80:83]
	v_mfma_f32_16x16x32_bf16 v[68:71], v[212:215], v[204:207], v[68:71]
	v_mfma_f32_16x16x32_bf16 v[64:67], v[220:223], v[204:207], v[64:67]
	s_mov_b32 m0, s44
	s_barrier
	ds_read_b128 v[158:161], v163 offset:49152
	ds_read_b128 v[164:167], v163 offset:50176
	ds_read_b128 v[168:171], v163 offset:51200
	ds_read_b128 v[172:175], v163 offset:52224
	ds_read_b128 v[176:179], v163 offset:53248
	ds_read_b128 v[196:199], v163 offset:54272
	ds_read_b128 v[200:203], v163 offset:55296
	global_load_lds_dwordx4 v128, s[100:101]
	s_mov_b32 m0, s45
	ds_read_b128 v[204:207], v163 offset:56320
	global_load_lds_dwordx4 v132, s[100:101]
	s_barrier
; #define PG8_STAGE(bufoff, gbase, voff) do { _Pragma("unroll") for (int _i = 0; _i < 2; ++_i) \
;     __builtin_amdgcn_global_load_lds((const unsigned*)((const char*)(gbase) + (voff)[_i]), (LAS unsigned*)(lds + (bufoff) + ldsw + _i * 8192), 16, 0, 0); } while (0)
; #define PG8_MMA(ai, bj, At, Bt) do { __builtin_amdgcn_s_setprio(1); _Pragma("unroll") for (int m = 0; m < 4; ++m) _Pragma("unroll") for (int n = 0; n < 2; ++n) _Pragma("unroll") for (int k = 0; k < 2; ++k) \
;     acc[ai][bj][m][n] = __builtin_amdgcn_mfma_f32_16x16x32_bf16(Bt[n][k], At[m][k], acc[ai][bj][m][n], 0, 0, 0); __builtin_amdgcn_s_setprio(0); } while (0)
; #define PG8_WAIT_V(n) asm volatile("s_waitcnt vmcnt(" #n ")" ::: "memory")
; #define PG8_WAIT_L(n) asm volatile("s_waitcnt lgkmcnt(" #n ")" ::: "memory")
; #define PG8_BAR __builtin_amdgcn_s_barrier()
; #define PG8_SCHED __builtin_amdgcn_sched_barrier(0)
; template <class Epi, class Sched>
; DI void gemm_phase(LAS unsigned char* lds, const Gemm g, const Sched& S, const Epi& E) {
;     ...
;       PG8_BAR; PG8_WAIT_L(0); PG8_MMA(1, 0, At, B0); PG8_BAR; PG8_SCHED;
;       PG8_STAGE(PG8_SB(1, 1), b3 + hstep, voffB);
;       PG8_WAIT_V(6); PG8_BAR; PG8_MMA(1, 1, At, B1); PG8_BAR;
;     }
;   DI void operator()(const f32x4 (&acc)[2][2][4][2], const pg8::Unit& u, int wr, int wc, int fr_, int fq_) const {
;     ...
;             } else if (EPI == EPI_UQ) {
;               if (n == 0) {
;                 const float sc = rinv * (0.10206207261596575f * LOG2E);
;                 const int gb = u.pn * 256 + bj * 128 + wc * 32;
;                 const int hd = gb / 96; const int within = gb - hd * 96;
;                 f32x4 a0 = v, a1 = acc[ai][bj][m][1];
;                 if (within == 64) rope_perm(a0, a1, fq, t_ & 63, tcos, tsin, token & (S_ - 1));
;                 st_bf8((u16*)(big + E_QMLA) + (size_t)token * 768 + gb + 8 * fq, a0, a1, sc);
;               }
	s_waitcnt lgkmcnt(0)
	v_mfma_f32_16x16x32_bf16 v[60:63], v[140:143], v[158:161], v[60:63]
	v_mfma_f32_16x16x32_bf16 v[56:59], v[150:153], v[158:161], v[56:59]
	v_mfma_f32_16x16x32_bf16 v[44:47], v[140:143], v[168:171], v[44:47]
	v_mfma_f32_16x16x32_bf16 v[40:43], v[150:153], v[168:171], v[40:43]
	v_mfma_f32_16x16x32_bf16 v[28:31], v[140:143], v[176:179], v[28:31]
	v_mfma_f32_16x16x32_bf16 v[24:27], v[150:153], v[176:179], v[24:27]
	v_mfma_f32_16x16x32_bf16 v[12:15], v[140:143], v[200:203], v[12:15]
	v_mfma_f32_16x16x32_bf16 v[8:11], v[150:153], v[200:203], v[8:11]
	v_mfma_f32_16x16x32_bf16 v[60:63], v[146:149], v[164:167], v[60:63]
	v_mfma_f32_16x16x32_bf16 v[56:59], v[154:157], v[164:167], v[56:59]
	v_mfma_f32_16x16x32_bf16 v[44:47], v[146:149], v[172:175], v[44:47]
	v_mfma_f32_16x16x32_bf16 v[40:43], v[154:157], v[172:175], v[40:43]
	v_mfma_f32_16x16x32_bf16 v[28:31], v[146:149], v[196:199], v[28:31]
	v_mfma_f32_16x16x32_bf16 v[24:27], v[154:157], v[196:199], v[24:27]
	v_mfma_f32_16x16x32_bf16 v[12:15], v[146:149], v[204:207], v[12:15]
	v_mfma_f32_16x16x32_bf16 v[8:11], v[154:157], v[204:207], v[8:11]
	s_barrier
	s_add_u32 s18, s22, 0x18080
	s_addc_u32 s19, s23, 0
	s_add_i32 s22, s35, 0x1c000
	s_mov_b32 m0, s22
	s_nop 0
	global_load_lds_dwordx4 v130, s[18:19]
	s_add_i32 m0, s22, 0x2000
	s_nop 0
	global_load_lds_dwordx4 v134, s[18:19]
	s_waitcnt vmcnt(6)
	s_barrier
	v_mfma_f32_16x16x32_bf16 v[52:55], v[208:211], v[158:161], v[52:55]
	v_mfma_f32_16x16x32_bf16 v[48:51], v[216:219], v[158:161], v[48:51]
	v_mfma_f32_16x16x32_bf16 v[36:39], v[208:211], v[168:171], v[36:39]
	v_mfma_f32_16x16x32_bf16 v[32:35], v[216:219], v[168:171], v[32:35]
	v_mfma_f32_16x16x32_bf16 v[20:23], v[208:211], v[176:179], v[20:23]
	v_mfma_f32_16x16x32_bf16 v[16:19], v[216:219], v[176:179], v[16:19]
	v_mfma_f32_16x16x32_bf16 v[4:7], v[208:211], v[200:203], v[4:7]
	v_mfma_f32_16x16x32_bf16 v[0:3], v[216:219], v[200:203], v[0:3]
	v_mfma_f32_16x16x32_bf16 v[52:55], v[212:215], v[164:167], v[52:55]
	v_mfma_f32_16x16x32_bf16 v[48:51], v[220:223], v[164:167], v[48:51]
	v_mfma_f32_16x16x32_bf16 v[36:39], v[212:215], v[172:175], v[36:39]
	v_mfma_f32_16x16x32_bf16 v[32:35], v[220:223], v[172:175], v[32:35]
	v_mfma_f32_16x16x32_bf16 v[20:23], v[212:215], v[196:199], v[20:23]
	v_mfma_f32_16x16x32_bf16 v[16:19], v[220:223], v[196:199], v[16:19]
	v_mfma_f32_16x16x32_bf16 v[4:7], v[212:215], v[204:207], v[4:7]
	v_mfma_f32_16x16x32_bf16 v[0:3], v[220:223], v[204:207], v[0:3]
	s_add_i32 s54, s54, 2
	s_add_u32 s52, s52, 0x100
	s_addc_u32 s53, s53, 0
	s_cmp_gt_u32 s54, 3
	s_mov_b64 s[18:19], s[20:21]
	s_barrier
	s_cbranch_scc0 .LBB0_1202
	v_mov_b32_e32 v140, v182
	s_lshl_b32 s19, s51, 10
	s_lshl_b32 s18, s49, 8
	s_or_b32 s18, s18, s43
	v_and_or_b32 v167, v140, 15, s42
	v_lshlrev_b32_e32 v141, 2, v140
	s_movk_i32 s20, 0x80
	s_add_i32 s19, s19, 0
	v_bitop3_b32 v164, v141, s20, v190 bitop3:0x6c
	v_lshl_add_u32 v141, v167, 2, s19
	s_mul_hi_i32 s19, s18, 0x2aaaaaab
	v_add_u32_e32 v166, 0x20000, v141
	s_lshr_b32 s20, s19, 31
	s_lshr_b32 s19, s19, 4
	s_lshl_b32 s50, s50, 8
	ds_read_b32 v144, v166
	s_add_i32 s19, s19, s20
	v_add_u32_e32 v165, s50, v167
	s_mulk_i32 s19, 0x60
	v_bfe_u32 v168, v140, 4, 2
	v_lshrrev_b32_e32 v140, 1, v140
	v_lshlrev_b32_e32 v141, 4, v165
	s_sub_i32 s19, s18, s19
	v_and_b32_e32 v140, 8, v140
	v_and_b32_e32 v141, 0xfcf0, v141
	s_cmp_eq_u32 s19, 64
	v_cmp_lt_u32_e64 s[78:79], 1, v168
	s_cselect_b64 s[20:21], -1, 0
	s_cmp_lg_u32 s19, 64
	v_lshlrev_b32_e32 v142, 2, v141
	v_lshlrev_b32_e32 v140, 2, v140
	s_cbranch_scc1 .LBB0_1209
	v_mov_b32_e32 v143, v145
	v_lshl_add_u64 v[146:147], s[12:13], 0, v[142:143]
	v_mov_b32_e32 v141, v145
	v_lshl_add_u64 v[152:153], s[14:15], 0, v[142:143]
	v_lshl_add_u64 v[146:147], v[146:147], 0, v[140:141]
	v_lshl_add_u64 v[152:153], v[152:153], 0, v[140:141]
	global_load_dwordx4 v[148:151], v[146:147], off
	global_load_dwordx4 v[154:157], v[152:153], off
	global_load_dwordx4 v[170:173], v[152:153], off offset:16
	global_load_dwordx4 v[174:177], v[146:147], off offset:16
	ds_bpermute_b32 v152, v164, v124
	ds_bpermute_b32 v160, v164, v120
	ds_bpermute_b32 v153, v164, v125
	ds_bpermute_b32 v161, v164, v121
	ds_bpermute_b32 v158, v164, v126
	ds_bpermute_b32 v178, v164, v122
	ds_bpermute_b32 v159, v164, v127
	ds_bpermute_b32 v179, v164, v123
	s_waitcnt vmcnt(0) lgkmcnt(0)
	v_pk_mul_f32 v[154:155], v[154:155], v[152:153]
	v_pk_mul_f32 v[146:147], v[126:127], v[150:151]
	v_pk_mul_f32 v[150:151], v[124:125], v[148:149]
	v_pk_mul_f32 v[158:159], v[156:157], v[158:159]
	v_pk_mul_f32 v[148:149], v[170:171], v[160:161]
	v_pk_mul_f32 v[152:153], v[172:173], v[178:179]
	v_pk_mul_f32 v[156:157], v[122:123], v[176:177]
	v_pk_mul_f32 v[160:161], v[120:121], v[174:175]
	s_and_saveexec_b64 s[22:23], s[78:79]
	s_xor_b64 s[22:23], exec, s[22:23]
	v_pk_add_f32 v[126:127], v[146:147], v[158:159]
	v_pk_add_f32 v[124:125], v[150:151], v[154:155]
	v_pk_add_f32 v[122:123], v[156:157], v[152:153]
	v_pk_add_f32 v[120:121], v[160:161], v[148:149]
	s_andn2_saveexec_b64 s[22:23], s[22:23]
	v_sub_f32_e32 v127, v147, v159
	v_sub_f32_e32 v126, v146, v158
	v_sub_f32_e32 v125, v151, v155
	v_sub_f32_e32 v124, v150, v154
	v_sub_f32_e32 v123, v157, v153
	v_sub_f32_e32 v122, v156, v152
	v_sub_f32_e32 v121, v161, v149
	v_sub_f32_e32 v120, v160, v148
	s_or_b64 exec, exec, s[22:23]

; #define PG8_STAGE(bufoff, gbase, voff) do { _Pragma("unroll") for (int _i = 0; _i < 2; ++_i) \
;     __builtin_amdgcn_global_load_lds((const unsigned*)((const char*)(gbase) + (voff)[_i]), (LAS unsigned*)(lds + (bufoff) + ldsw + _i * 8192), 16, 0, 0); } while (0)
; #define PG8_LDA(dst, b, h) do { _Pragma("unroll") for (int m = 0; m < 4; ++m) _Pragma("unroll") for (int k = 0; k < 2; ++k) dst[m][k] = *(const LAS bf16x8*)(lds + PG8_SA(b, h) + aoff + m * 2048 + k * 1024); } while (0)
; #define PG8_LDB(dst, b, h) do { _Pragma("unroll") for (int n = 0; n < 2; ++n) _Pragma("unroll") for (int k = 0; k < 2; ++k) dst[n][k] = *(const LAS bf16x8*)(lds + PG8_SB(b, h) + boff + n * 2048 + k * 1024); } while (0)
; #define PG8_MMA(ai, bj, At, Bt) do { __builtin_amdgcn_s_setprio(1); _Pragma("unroll") for (int m = 0; m < 4; ++m) _Pragma("unroll") for (int n = 0; n < 2; ++n) _Pragma("unroll") for (int k = 0; k < 2; ++k) \
;     acc[ai][bj][m][n] = __builtin_amdgcn_mfma_f32_16x16x32_bf16(Bt[n][k], At[m][k], acc[ai][bj][m][n], 0, 0, 0); __builtin_amdgcn_s_setprio(0); } while (0)
; #define PG8_BAR __builtin_amdgcn_s_barrier()
; template <class Epi, class Sched>
; DI void gemm_phase(LAS unsigned char* lds, const Gemm g, const Sched& S, const Epi& E) {
;     ...
;     const bool has_next = S.next(ui + 1, nxt);
;     const char* nA = has_next ? (const char*)g.A + (size_t)nxt.pm * tstep : cA; const char* nB = has_next ? (const char*)g.Bt + (size_t)nxt.pn * tstep : cB;
; #pragma unroll 1
;     for (int t = 0; t < nt; t += 2) {
;       const bool last = (t == nt - 2);
;       const char* a1 = cA + (size_t)(t + 1) * kstep;
;       const char* a2 = last ? nA : cA + (size_t)(t + 2) * kstep; const char* b2 = last ? nB : cB + (size_t)(t + 2) * kstep;
;       const char* a3 = a2 + kstep; const char* b3 = b2 + kstep;
;       PG8_LDB(B0, 0, 0); PG8_SCHED; PG8_LDA(At, 0, 0); PG8_STAGE(PG8_SA(1, 1), a1 + hstep, voffA);
;       PG8_WAIT_L(8); PG8_BAR; PG8_WAIT_L(0); PG8_MMA(0, 0, At, B0); PG8_BAR; PG8_SCHED;
;       PG8_LDB(B1, 0, 1); PG8_STAGE(PG8_SB(0, 0), b2, voffB);
;       PG8_BAR; PG8_WAIT_L(0); PG8_MMA(0, 1, At, B1); PG8_BAR;
;       PG8_LDA(At, 0, 1); PG8_STAGE(PG8_SA(0, 0), a2, voffA);
;       PG8_BAR; PG8_WAIT_L(0); PG8_MMA(1, 0, At, B0); PG8_BAR; PG8_SCHED;
;       PG8_STAGE(PG8_SB(0, 1), b2 + hstep, voffB);
;       PG8_WAIT_V(6); PG8_BAR; PG8_MMA(1, 1, At, B1); PG8_BAR;
.LBB0_1346:
	s_add_u32 s48, s28, s40
	s_addc_u32 s49, s29, s41
	s_add_u32 s44, s48, 0x100
	s_addc_u32 s45, s49, 0
	s_and_b64 s[42:43], s[36:37], exec
	s_cselect_b32 s45, s15, s45
	s_cselect_b32 s44, s21, s44
	s_add_u32 s40, s22, s40
	s_addc_u32 s41, s23, s41
	s_add_u32 s40, s40, 0x100
	s_addc_u32 s41, s41, 0
	s_and_b64 s[36:37], s[36:37], exec
	s_cselect_b32 s47, s13, s41
	s_cselect_b32 s46, s24, s40
	s_add_u32 s48, s48, 0x10080
	s_addc_u32 s49, s49, 0
	s_add_i32 s74, s51, 0x10000
	s_add_i32 m0, s56, 0xc000
	s_add_i32 s75, s56, 0xe000
	s_add_i32 s72, s74, 0x2000
	s_add_u32 s42, s46, 0x10000
	s_addc_u32 s43, s47, 0
	s_add_i32 s69, s51, 0x14000
	ds_read_b128 v[136:139], v220
	ds_read_b128 v[146:149], v220 offset:1024
	ds_read_b128 v[150:153], v220 offset:2048
	ds_read_b128 v[154:157], v220 offset:3072
	s_add_i32 s68, s69, 0x2000
	s_add_u32 s40, s44, 0x10000
	s_addc_u32 s41, s45, 0
	s_add_i32 s66, s51, 0x18000
	s_add_i32 s64, s66, 0x2000
	s_add_u32 s36, s46, 0x10080
	s_addc_u32 s37, s47, 0
	s_add_i32 s71, s51, 0x1c000
	s_add_i32 s70, s71, 0x2000
	ds_read_b128 v[158:161], v143
	ds_read_b128 v[162:165], v143 offset:1024
	ds_read_b128 v[166:169], v143 offset:2048
	ds_read_b128 v[170:173], v143 offset:3072
	ds_read_b128 v[174:177], v143 offset:4096
	ds_read_b128 v[178:181], v143 offset:5120
	ds_read_b128 v[196:199], v143 offset:6144
	global_load_lds_dwordx4 v128, s[48:49]
	s_mov_b32 m0, s75
	ds_read_b128 v[200:203], v143 offset:7168
	global_load_lds_dwordx4 v132, s[48:49]
	s_waitcnt lgkmcnt(8)
	s_barrier
	s_waitcnt lgkmcnt(0)
	v_mfma_f32_16x16x32_bf16 v[124:127], v[136:139], v[158:161], v[124:127]
	v_mfma_f32_16x16x32_bf16 v[120:123], v[150:153], v[158:161], v[120:123]
	v_mfma_f32_16x16x32_bf16 v[108:111], v[136:139], v[166:169], v[108:111]
	v_mfma_f32_16x16x32_bf16 v[104:107], v[150:153], v[166:169], v[104:107]
	v_mfma_f32_16x16x32_bf16 v[92:95], v[136:139], v[174:177], v[92:95]
	v_mfma_f32_16x16x32_bf16 v[88:91], v[150:153], v[174:177], v[88:91]
	v_mfma_f32_16x16x32_bf16 v[76:79], v[136:139], v[196:199], v[76:79]
	v_mfma_f32_16x16x32_bf16 v[72:75], v[150:153], v[196:199], v[72:75]
	v_mfma_f32_16x16x32_bf16 v[124:127], v[146:149], v[162:165], v[124:127]
	v_mfma_f32_16x16x32_bf16 v[120:123], v[154:157], v[162:165], v[120:123]
	v_mfma_f32_16x16x32_bf16 v[108:111], v[146:149], v[170:173], v[108:111]
	v_mfma_f32_16x16x32_bf16 v[104:107], v[154:157], v[170:173], v[104:107]
	v_mfma_f32_16x16x32_bf16 v[92:95], v[146:149], v[178:181], v[92:95]
	v_mfma_f32_16x16x32_bf16 v[88:91], v[154:157], v[178:181], v[88:91]
	v_mfma_f32_16x16x32_bf16 v[76:79], v[146:149], v[200:203], v[76:79]
	v_mfma_f32_16x16x32_bf16 v[72:75], v[154:157], v[200:203], v[72:75]
	s_barrier
	s_mov_b32 m0, s74
	ds_read_b128 v[204:207], v221
	ds_read_b128 v[208:211], v221 offset:1024
	ds_read_b128 v[212:215], v221 offset:2048
	s_add_u32 vcc_lo, s46, s0
	s_addc_u32 vcc_hi, s47, s1
	global_load_lds_dwordx4 v130, s[46:47]
	s_mov_b32 m0, s72
	ds_read_b128 v[216:219], v221 offset:3072
	global_load_lds_dwordx4 v134, s[46:47]
	s_barrier
	s_waitcnt lgkmcnt(0)
	v_mfma_f32_16x16x32_bf16 v[116:119], v[204:207], v[158:161], v[116:119]
	v_mfma_f32_16x16x32_bf16 v[112:115], v[212:215], v[158:161], v[112:115]
	v_mfma_f32_16x16x32_bf16 v[100:103], v[204:207], v[166:169], v[100:103]
	v_mfma_f32_16x16x32_bf16 v[96:99], v[212:215], v[166:169], v[96:99]
	v_mfma_f32_16x16x32_bf16 v[84:87], v[204:207], v[174:177], v[84:87]
	v_mfma_f32_16x16x32_bf16 v[80:83], v[212:215], v[174:177], v[80:83]
	v_mfma_f32_16x16x32_bf16 v[68:71], v[204:207], v[196:199], v[68:71]
	v_mfma_f32_16x16x32_bf16 v[64:67], v[212:215], v[196:199], v[64:67]
	v_mfma_f32_16x16x32_bf16 v[116:119], v[208:211], v[162:165], v[116:119]
	v_mfma_f32_16x16x32_bf16 v[112:115], v[216:219], v[162:165], v[112:115]
	v_mfma_f32_16x16x32_bf16 v[100:103], v[208:211], v[170:173], v[100:103]
	v_mfma_f32_16x16x32_bf16 v[96:99], v[216:219], v[170:173], v[96:99]
	v_mfma_f32_16x16x32_bf16 v[84:87], v[208:211], v[178:181], v[84:87]
	v_mfma_f32_16x16x32_bf16 v[80:83], v[216:219], v[178:181], v[80:83]
	v_mfma_f32_16x16x32_bf16 v[68:71], v[208:211], v[200:203], v[68:71]
	v_mfma_f32_16x16x32_bf16 v[64:67], v[216:219], v[200:203], v[64:67]
	s_mov_b32 m0, s56
	s_add_u32 s100, s44, s0
	s_addc_u32 s101, s45, s1
	s_barrier
	ds_read_b128 v[158:161], v143 offset:16384
	ds_read_b128 v[162:165], v143 offset:17408
	ds_read_b128 v[166:169], v143 offset:18432
	ds_read_b128 v[170:173], v143 offset:19456
	ds_read_b128 v[174:177], v143 offset:20480
	ds_read_b128 v[178:181], v143 offset:21504
	ds_read_b128 v[196:199], v143 offset:22528
	global_load_lds_dwordx4 v128, s[44:45]
	s_mov_b32 m0, s57
	ds_read_b128 v[200:203], v143 offset:23552
	global_load_lds_dwordx4 v132, s[44:45]
	s_barrier
	s_waitcnt lgkmcnt(0)
	v_mfma_f32_16x16x32_bf16 v[60:63], v[136:139], v[158:161], v[60:63]
	v_mfma_f32_16x16x32_bf16 v[56:59], v[150:153], v[158:161], v[56:59]
	v_mfma_f32_16x16x32_bf16 v[44:47], v[136:139], v[166:169], v[44:47]
	v_mfma_f32_16x16x32_bf16 v[40:43], v[150:153], v[166:169], v[40:43]
	v_mfma_f32_16x16x32_bf16 v[28:31], v[136:139], v[174:177], v[28:31]
	v_mfma_f32_16x16x32_bf16 v[24:27], v[150:153], v[174:177], v[24:27]
	v_mfma_f32_16x16x32_bf16 v[12:15], v[136:139], v[196:199], v[12:15]
	v_mfma_f32_16x16x32_bf16 v[8:11], v[150:153], v[196:199], v[8:11]
	v_mfma_f32_16x16x32_bf16 v[60:63], v[146:149], v[162:165], v[60:63]
	v_mfma_f32_16x16x32_bf16 v[56:59], v[154:157], v[162:165], v[56:59]
	v_mfma_f32_16x16x32_bf16 v[44:47], v[146:149], v[170:173], v[44:47]
	v_mfma_f32_16x16x32_bf16 v[40:43], v[154:157], v[170:173], v[40:43]
	v_mfma_f32_16x16x32_bf16 v[28:31], v[146:149], v[178:181], v[28:31]
	v_mfma_f32_16x16x32_bf16 v[24:27], v[154:157], v[178:181], v[24:27]
	v_mfma_f32_16x16x32_bf16 v[12:15], v[146:149], v[200:203], v[12:15]
	v_mfma_f32_16x16x32_bf16 v[8:11], v[154:157], v[200:203], v[8:11]
	s_barrier
; #define PG8_STAGE(bufoff, gbase, voff) do { _Pragma("unroll") for (int _i = 0; _i < 2; ++_i) \
;     __builtin_amdgcn_global_load_lds((const unsigned*)((const char*)(gbase) + (voff)[_i]), (LAS unsigned*)(lds + (bufoff) + ldsw + _i * 8192), 16, 0, 0); } while (0)
; #define PG8_LDA(dst, b, h) do { _Pragma("unroll") for (int m = 0; m < 4; ++m) _Pragma("unroll") for (int k = 0; k < 2; ++k) dst[m][k] = *(const LAS bf16x8*)(lds + PG8_SA(b, h) + aoff + m * 2048 + k * 1024); } while (0)
; #define PG8_LDB(dst, b, h) do { _Pragma("unroll") for (int n = 0; n < 2; ++n) _Pragma("unroll") for (int k = 0; k < 2; ++k) dst[n][k] = *(const LAS bf16x8*)(lds + PG8_SB(b, h) + boff + n * 2048 + k * 1024); } while (0)
; #define PG8_MMA(ai, bj, At, Bt) do { __builtin_amdgcn_s_setprio(1); _Pragma("unroll") for (int m = 0; m < 4; ++m) _Pragma("unroll") for (int n = 0; n < 2; ++n) _Pragma("unroll") for (int k = 0; k < 2; ++k) \
;     acc[ai][bj][m][n] = __builtin_amdgcn_mfma_f32_16x16x32_bf16(Bt[n][k], At[m][k], acc[ai][bj][m][n], 0, 0, 0); __builtin_amdgcn_s_setprio(0); } while (0)
; #define PG8_WAIT_V(n) asm volatile("s_waitcnt vmcnt(" #n ")" ::: "memory")
; #define PG8_WAIT_L(n) asm volatile("s_waitcnt lgkmcnt(" #n ")" ::: "memory")
; #define PG8_BAR __builtin_amdgcn_s_barrier()
; #define PG8_SCHED __builtin_amdgcn_sched_barrier(0)
; template <class Epi, class Sched>
; DI void gemm_phase(LAS unsigned char* lds, const Gemm g, const Sched& S, const Epi& E) {
;     ...
;       PG8_WAIT_V(6); PG8_BAR; PG8_MMA(1, 1, At, B1); PG8_BAR;
;       PG8_LDB(B0, 1, 0); PG8_SCHED; PG8_LDA(At, 1, 0); PG8_STAGE(PG8_SA(0, 1), a2 + hstep, voffA);
;       PG8_WAIT_L(8); PG8_BAR; PG8_WAIT_L(0); PG8_MMA(0, 0, At, B0); PG8_BAR; PG8_SCHED;
;       PG8_LDB(B1, 1, 1); PG8_STAGE(PG8_SB(1, 0), b3, voffB);
;       PG8_BAR; PG8_WAIT_L(0); PG8_MMA(0, 1, At, B1); PG8_BAR;
;       PG8_LDA(At, 1, 1); PG8_STAGE(PG8_SA(1, 0), a3, voffA);
;       PG8_BAR; PG8_WAIT_L(0); PG8_MMA(1, 0, At, B0); PG8_BAR; PG8_SCHED;
	s_mov_b32 m0, s69
	s_nop 0
	global_load_lds_dwordx4 v130, s[42:43]
	s_mov_b32 m0, s68
	s_nop 0
	global_load_lds_dwordx4 v134, s[42:43]
	s_waitcnt vmcnt(6)
	s_barrier
	v_mfma_f32_16x16x32_bf16 v[52:55], v[204:207], v[158:161], v[52:55]
	v_mfma_f32_16x16x32_bf16 v[48:51], v[212:215], v[158:161], v[48:51]
	v_mfma_f32_16x16x32_bf16 v[36:39], v[204:207], v[166:169], v[36:39]
	v_mfma_f32_16x16x32_bf16 v[32:35], v[212:215], v[166:169], v[32:35]
	v_mfma_f32_16x16x32_bf16 v[20:23], v[204:207], v[174:177], v[20:23]
	v_mfma_f32_16x16x32_bf16 v[16:19], v[212:215], v[174:177], v[16:19]
	v_mfma_f32_16x16x32_bf16 v[4:7], v[204:207], v[196:199], v[4:7]
	v_mfma_f32_16x16x32_bf16 v[0:3], v[212:215], v[196:199], v[0:3]
	v_mfma_f32_16x16x32_bf16 v[52:55], v[208:211], v[162:165], v[52:55]
	v_mfma_f32_16x16x32_bf16 v[48:51], v[216:219], v[162:165], v[48:51]
	v_mfma_f32_16x16x32_bf16 v[36:39], v[208:211], v[170:173], v[36:39]
	v_mfma_f32_16x16x32_bf16 v[32:35], v[216:219], v[170:173], v[32:35]
	v_mfma_f32_16x16x32_bf16 v[20:23], v[208:211], v[178:181], v[20:23]
	v_mfma_f32_16x16x32_bf16 v[16:19], v[216:219], v[178:181], v[16:19]
	v_mfma_f32_16x16x32_bf16 v[4:7], v[208:211], v[200:203], v[4:7]
	v_mfma_f32_16x16x32_bf16 v[0:3], v[216:219], v[200:203], v[0:3]
	s_barrier
	ds_read_b128 v[136:139], v222
	ds_read_b128 v[146:149], v222 offset:1024
	ds_read_b128 v[150:153], v222 offset:2048
	ds_read_b128 v[154:157], v222 offset:3072
	s_mov_b32 m0, s58
	ds_read_b128 v[158:161], v143 offset:32768
	ds_read_b128 v[162:165], v143 offset:33792
	ds_read_b128 v[166:169], v143 offset:34816
	ds_read_b128 v[170:173], v143 offset:35840
	ds_read_b128 v[174:177], v143 offset:36864
	ds_read_b128 v[178:181], v143 offset:37888
	ds_read_b128 v[196:199], v143 offset:38912
	global_load_lds_dwordx4 v128, s[40:41]
	s_mov_b32 m0, s59
	ds_read_b128 v[200:203], v143 offset:39936
	global_load_lds_dwordx4 v132, s[40:41]
	s_waitcnt lgkmcnt(8)
	s_barrier
	s_waitcnt lgkmcnt(0)
	v_mfma_f32_16x16x32_bf16 v[124:127], v[136:139], v[158:161], v[124:127]
	v_mfma_f32_16x16x32_bf16 v[120:123], v[150:153], v[158:161], v[120:123]
	v_mfma_f32_16x16x32_bf16 v[108:111], v[136:139], v[166:169], v[108:111]
	v_mfma_f32_16x16x32_bf16 v[104:107], v[150:153], v[166:169], v[104:107]
	v_mfma_f32_16x16x32_bf16 v[92:95], v[136:139], v[174:177], v[92:95]
	v_mfma_f32_16x16x32_bf16 v[88:91], v[150:153], v[174:177], v[88:91]
	v_mfma_f32_16x16x32_bf16 v[76:79], v[136:139], v[196:199], v[76:79]
	v_mfma_f32_16x16x32_bf16 v[72:75], v[150:153], v[196:199], v[72:75]
	v_mfma_f32_16x16x32_bf16 v[124:127], v[146:149], v[162:165], v[124:127]
	v_mfma_f32_16x16x32_bf16 v[120:123], v[154:157], v[162:165], v[120:123]
	v_mfma_f32_16x16x32_bf16 v[108:111], v[146:149], v[170:173], v[108:111]
	v_mfma_f32_16x16x32_bf16 v[104:107], v[154:157], v[170:173], v[104:107]
	v_mfma_f32_16x16x32_bf16 v[92:95], v[146:149], v[178:181], v[92:95]
	v_mfma_f32_16x16x32_bf16 v[88:91], v[154:157], v[178:181], v[88:91]
	v_mfma_f32_16x16x32_bf16 v[76:79], v[146:149], v[200:203], v[76:79]
	v_mfma_f32_16x16x32_bf16 v[72:75], v[154:157], v[200:203], v[72:75]
	s_barrier
	s_mov_b32 m0, s66
	ds_read_b128 v[204:207], v223
	ds_read_b128 v[208:211], v223 offset:1024
	ds_read_b128 v[212:215], v223 offset:2048
	global_load_lds_dwordx4 v130, vcc
	s_mov_b32 m0, s64
	ds_read_b128 v[216:219], v223 offset:3072
	global_load_lds_dwordx4 v134, vcc
	s_barrier
	s_waitcnt lgkmcnt(0)
	v_mfma_f32_16x16x32_bf16 v[116:119], v[204:207], v[158:161], v[116:119]
	v_mfma_f32_16x16x32_bf16 v[112:115], v[212:215], v[158:161], v[112:115]
	v_mfma_f32_16x16x32_bf16 v[100:103], v[204:207], v[166:169], v[100:103]
	v_mfma_f32_16x16x32_bf16 v[96:99], v[212:215], v[166:169], v[96:99]
	v_mfma_f32_16x16x32_bf16 v[84:87], v[204:207], v[174:177], v[84:87]
	v_mfma_f32_16x16x32_bf16 v[80:83], v[212:215], v[174:177], v[80:83]
	v_mfma_f32_16x16x32_bf16 v[68:71], v[204:207], v[196:199], v[68:71]
	v_mfma_f32_16x16x32_bf16 v[64:67], v[212:215], v[196:199], v[64:67]
	v_mfma_f32_16x16x32_bf16 v[116:119], v[208:211], v[162:165], v[116:119]
	v_mfma_f32_16x16x32_bf16 v[112:115], v[216:219], v[162:165], v[112:115]
	v_mfma_f32_16x16x32_bf16 v[100:103], v[208:211], v[170:173], v[100:103]
	v_mfma_f32_16x16x32_bf16 v[96:99], v[216:219], v[170:173], v[96:99]
	v_mfma_f32_16x16x32_bf16 v[84:87], v[208:211], v[178:181], v[84:87]
	v_mfma_f32_16x16x32_bf16 v[80:83], v[216:219], v[178:181], v[80:83]
	v_mfma_f32_16x16x32_bf16 v[68:71], v[208:211], v[200:203], v[68:71]
	v_mfma_f32_16x16x32_bf16 v[64:67], v[216:219], v[200:203], v[64:67]
	s_mov_b32 m0, s62
	s_barrier
; #define PG8_STAGE(bufoff, gbase, voff) do { _Pragma("unroll") for (int _i = 0; _i < 2; ++_i) \
;     __builtin_amdgcn_global_load_lds((const unsigned*)((const char*)(gbase) + (voff)[_i]), (LAS unsigned*)(lds + (bufoff) + ldsw + _i * 8192), 16, 0, 0); } while (0)
; #define PG8_MMA(ai, bj, At, Bt) do { __builtin_amdgcn_s_setprio(1); _Pragma("unroll") for (int m = 0; m < 4; ++m) _Pragma("unroll") for (int n = 0; n < 2; ++n) _Pragma("unroll") for (int k = 0; k < 2; ++k) \
;     acc[ai][bj][m][n] = __builtin_amdgcn_mfma_f32_16x16x32_bf16(Bt[n][k], At[m][k], acc[ai][bj][m][n], 0, 0, 0); __builtin_amdgcn_s_setprio(0); } while (0)
; #define PG8_WAIT_V(n) asm volatile("s_waitcnt vmcnt(" #n ")" ::: "memory")
; #define PG8_WAIT_L(n) asm volatile("s_waitcnt lgkmcnt(" #n ")" ::: "memory")
; #define PG8_BAR __builtin_amdgcn_s_barrier()
; #define PG8_SCHED __builtin_amdgcn_sched_barrier(0)
; template <class Epi, class Sched>
; DI void gemm_phase(LAS unsigned char* lds, const Gemm g, const Sched& S, const Epi& E) {
;     ...
;       PG8_BAR; PG8_WAIT_L(0); PG8_MMA(1, 0, At, B0); PG8_BAR; PG8_SCHED;
;       PG8_STAGE(PG8_SB(1, 1), b3 + hstep, voffB);
;       PG8_WAIT_V(6); PG8_BAR; PG8_MMA(1, 1, At, B1); PG8_BAR;
;     }
;   DI void operator()(const f32x4 (&acc)[2][2][4][2], const pg8::Unit& u, int wr, int wc, int fr_, int fq_) const {
;     ...
;             } else if (EPI == EPI_UKV) {
;               if (n == 0) {
;                 const int gb = u.pn * 256 + bj * 128 + wc * 32;
;                 const int hd = gb >> 7, within = (gb & 127) + 8 * fq;
;                 const f32x4 v1 = acc[ai][bj][m][1];
;                 if (within < 64) st_bf8((u16*)(big + E_KNOPE) + (size_t)token * 512 + hd * 64 + within, v, v1, rinv);
;                 else st_bf8((u16*)(big + E_VMLAT) + (size_t)token * 512 + hd * 64 + (within - 64), v, v1, rinv);
;               }
	ds_read_b128 v[158:161], v143 offset:49152
	ds_read_b128 v[162:165], v143 offset:50176
	ds_read_b128 v[166:169], v143 offset:51200
	ds_read_b128 v[170:173], v143 offset:52224
	ds_read_b128 v[174:177], v143 offset:53248
	ds_read_b128 v[178:181], v143 offset:54272
	ds_read_b128 v[196:199], v143 offset:55296
	global_load_lds_dwordx4 v128, s[100:101]
	s_mov_b32 m0, s63
	ds_read_b128 v[200:203], v143 offset:56320
	global_load_lds_dwordx4 v132, s[100:101]
	s_barrier
	s_waitcnt lgkmcnt(0)
	v_mfma_f32_16x16x32_bf16 v[60:63], v[136:139], v[158:161], v[60:63]
	v_mfma_f32_16x16x32_bf16 v[56:59], v[150:153], v[158:161], v[56:59]
	v_mfma_f32_16x16x32_bf16 v[44:47], v[136:139], v[166:169], v[44:47]
	v_mfma_f32_16x16x32_bf16 v[40:43], v[150:153], v[166:169], v[40:43]
	v_mfma_f32_16x16x32_bf16 v[28:31], v[136:139], v[174:177], v[28:31]
	v_mfma_f32_16x16x32_bf16 v[24:27], v[150:153], v[174:177], v[24:27]
	v_mfma_f32_16x16x32_bf16 v[12:15], v[136:139], v[196:199], v[12:15]
	v_mfma_f32_16x16x32_bf16 v[8:11], v[150:153], v[196:199], v[8:11]
	v_mfma_f32_16x16x32_bf16 v[60:63], v[146:149], v[162:165], v[60:63]
	v_mfma_f32_16x16x32_bf16 v[56:59], v[154:157], v[162:165], v[56:59]
	v_mfma_f32_16x16x32_bf16 v[44:47], v[146:149], v[170:173], v[44:47]
	v_mfma_f32_16x16x32_bf16 v[40:43], v[154:157], v[170:173], v[40:43]
	v_mfma_f32_16x16x32_bf16 v[28:31], v[146:149], v[178:181], v[28:31]
	v_mfma_f32_16x16x32_bf16 v[24:27], v[154:157], v[178:181], v[24:27]
	v_mfma_f32_16x16x32_bf16 v[12:15], v[146:149], v[200:203], v[12:15]
	v_mfma_f32_16x16x32_bf16 v[8:11], v[154:157], v[200:203], v[8:11]
	s_barrier
	s_mov_b32 m0, s71
	s_nop 0
	global_load_lds_dwordx4 v130, s[36:37]
	s_mov_b32 m0, s70
	s_nop 0
	global_load_lds_dwordx4 v134, s[36:37]
	s_waitcnt vmcnt(6)
	s_barrier
	v_mfma_f32_16x16x32_bf16 v[52:55], v[204:207], v[158:161], v[52:55]
	v_mfma_f32_16x16x32_bf16 v[48:51], v[212:215], v[158:161], v[48:51]
	v_mfma_f32_16x16x32_bf16 v[36:39], v[204:207], v[166:169], v[36:39]
	v_mfma_f32_16x16x32_bf16 v[32:35], v[212:215], v[166:169], v[32:35]
	v_mfma_f32_16x16x32_bf16 v[20:23], v[204:207], v[174:177], v[20:23]
	v_mfma_f32_16x16x32_bf16 v[16:19], v[212:215], v[174:177], v[16:19]
	v_mfma_f32_16x16x32_bf16 v[4:7], v[204:207], v[196:199], v[4:7]
	v_mfma_f32_16x16x32_bf16 v[0:3], v[212:215], v[196:199], v[0:3]
	v_mfma_f32_16x16x32_bf16 v[52:55], v[208:211], v[162:165], v[52:55]
	v_mfma_f32_16x16x32_bf16 v[48:51], v[216:219], v[162:165], v[48:51]
	v_mfma_f32_16x16x32_bf16 v[36:39], v[208:211], v[170:173], v[36:39]
	v_mfma_f32_16x16x32_bf16 v[32:35], v[216:219], v[170:173], v[32:35]
	v_mfma_f32_16x16x32_bf16 v[20:23], v[208:211], v[178:181], v[20:23]
	v_mfma_f32_16x16x32_bf16 v[16:19], v[216:219], v[178:181], v[16:19]
	v_mfma_f32_16x16x32_bf16 v[4:7], v[208:211], v[200:203], v[4:7]
	v_mfma_f32_16x16x32_bf16 v[0:3], v[216:219], v[200:203], v[0:3]
	s_andn2_b64 vcc, exec, s[34:35]
	s_mov_b64 s[36:37], -1
	s_mov_b64 s[34:35], 0
	s_mov_b64 s[40:41], 0x100
	s_barrier
	s_cbranch_vccz .LBB0_1346
	v_mov_b32_e32 v136, v182
	s_lshl_b32 s3, s3, 10
	s_add_i32 s3, s3, 0
	v_and_or_b32 v147, v136, 15, s60
	v_lshl_add_u32 v137, v147, 2, s3
	v_add_u32_e32 v146, 0x20000, v137
	ds_read_b32 v138, v146
	s_lshl_b32 s13, s20, 8
	v_lshrrev_b32_e32 v136, 1, v136
	v_and_or_b32 v139, v136, 24, s61
	v_add_u32_e32 v136, s13, v147
	v_ashrrev_i32_e32 v137, 31, v136
	s_waitcnt lgkmcnt(0)
	v_pk_mul_f32 v[124:125], v[124:125], v[138:139] op_sel_hi:[1,0]
	v_pk_mul_f32 v[126:127], v[126:127], v[138:139] op_sel_hi:[1,0]
	v_pk_mul_f32 v[120:121], v[120:121], v[138:139] op_sel_hi:[1,0]
	v_lshlrev_b64 v[140:141], 10, v[136:137]
	s_lshl_b32 s20, s2, 7
	v_cvt_pk_bf16_f32 v124, v124, v125
	v_cvt_pk_bf16_f32 v125, v126, v127
	v_cvt_pk_bf16_f32 v126, v120, v121
	v_pk_mul_f32 v[120:121], v[122:123], v[138:139] op_sel_hi:[1,0]
	s_ashr_i32 s21, s20, 31
	v_cvt_pk_bf16_f32 v127, v120, v121
	v_lshl_add_u64 v[120:121], s[6:7], 0, v[140:141]
	s_mov_b64 s[2:3], -1
	s_and_b64 vcc, exec, s[4:5]
	v_lshl_add_u64 v[120:121], s[20:21], 1, v[120:121]
	v_lshlrev_b32_e32 v144, 1, v139
	s_cbranch_vccz .LBB0_1349
	v_lshl_add_u64 v[122:123], v[120:121], 0, v[144:145]
	v_add_co_u32_e32 v122, vcc, 0xd9ff000, v122
	s_mov_b64 s[2:3], 0
	s_nop 0
	v_addc_co_u32_e32 v123, vcc, 0, v123, vcc
	global_store_dwordx4 v[122:123], v[124:127], off offset:3968

; #define PG8_STAGE(bufoff, gbase, voff) do { _Pragma("unroll") for (int _i = 0; _i < 2; ++_i) \
;     __builtin_amdgcn_global_load_lds((const unsigned*)((const char*)(gbase) + (voff)[_i]), (LAS unsigned*)(lds + (bufoff) + ldsw + _i * 8192), 16, 0, 0); } while (0)
; #define PG8_LDA(dst, b, h) do { _Pragma("unroll") for (int m = 0; m < 4; ++m) _Pragma("unroll") for (int k = 0; k < 2; ++k) dst[m][k] = *(const LAS bf16x8*)(lds + PG8_SA(b, h) + aoff + m * 2048 + k * 1024); } while (0)
; #define PG8_LDB(dst, b, h) do { _Pragma("unroll") for (int n = 0; n < 2; ++n) _Pragma("unroll") for (int k = 0; k < 2; ++k) dst[n][k] = *(const LAS bf16x8*)(lds + PG8_SB(b, h) + boff + n * 2048 + k * 1024); } while (0)
; #define PG8_MMA(ai, bj, At, Bt) do { __builtin_amdgcn_s_setprio(1); _Pragma("unroll") for (int m = 0; m < 4; ++m) _Pragma("unroll") for (int n = 0; n < 2; ++n) _Pragma("unroll") for (int k = 0; k < 2; ++k) \
;     acc[ai][bj][m][n] = __builtin_amdgcn_mfma_f32_16x16x32_bf16(Bt[n][k], At[m][k], acc[ai][bj][m][n], 0, 0, 0); __builtin_amdgcn_s_setprio(0); } while (0)
; #define PG8_WAIT_V(n) asm volatile("s_waitcnt vmcnt(" #n ")" ::: "memory")
; #define PG8_WAIT_L(n) asm volatile("s_waitcnt lgkmcnt(" #n ")" ::: "memory")
; #define PG8_BAR __builtin_amdgcn_s_barrier()
; #define PG8_SCHED __builtin_amdgcn_sched_barrier(0)
; template <class Epi, class Sched>
; DI void gemm_phase(LAS unsigned char* lds, const Gemm g, const Sched& S, const Epi& E) {
;     ...
;     for (int t = 0; t < nt; t += 2) {
;       const bool last = (t == nt - 2);
;       const char* a1 = cA + (size_t)(t + 1) * kstep;
;       const char* a2 = last ? nA : cA + (size_t)(t + 2) * kstep; const char* b2 = last ? nB : cB + (size_t)(t + 2) * kstep;
;       const char* a3 = a2 + kstep; const char* b3 = b2 + kstep;
;       PG8_LDB(B0, 0, 0); PG8_SCHED; PG8_LDA(At, 0, 0); PG8_STAGE(PG8_SA(1, 1), a1 + hstep, voffA);
;       PG8_WAIT_L(8); PG8_BAR; PG8_WAIT_L(0); PG8_MMA(0, 0, At, B0); PG8_BAR; PG8_SCHED;
;       PG8_LDB(B1, 0, 1); PG8_STAGE(PG8_SB(0, 0), b2, voffB);
;       PG8_BAR; PG8_WAIT_L(0); PG8_MMA(0, 1, At, B1); PG8_BAR;
;       PG8_LDA(At, 0, 1); PG8_STAGE(PG8_SA(0, 0), a2, voffA);
;       PG8_BAR; PG8_WAIT_L(0); PG8_MMA(1, 0, At, B0); PG8_BAR; PG8_SCHED;
;       PG8_STAGE(PG8_SB(0, 1), b2 + hstep, voffB);
;       PG8_WAIT_V(6); PG8_BAR; PG8_MMA(1, 1, At, B1); PG8_BAR;
.LBB0_1644:
	s_add_u32 s4, s2, 0xfffc0080
	s_addc_u32 s5, s3, -1
	ds_read_b128 v[128:131], v224
	ds_read_b128 v[132:135], v224 offset:1024
	ds_read_b128 v[148:151], v224 offset:2048
	ds_read_b128 v[152:155], v224 offset:3072
	s_cmp_eq_u32 s54, 12
	s_cselect_b32 s29, s19, s5
	s_cselect_b32 s28, s35, s4
	s_cselect_b32 s5, s17, s53
	s_cselect_b32 s4, s51, s52
	s_add_i32 m0, s41, 0xc000
	ds_read_b128 v[160:163], v159
	ds_read_b128 v[164:167], v159 offset:1024
	ds_read_b128 v[168:171], v159 offset:2048
	ds_read_b128 v[172:175], v159 offset:3072
	ds_read_b128 v[176:179], v159 offset:4096
	ds_read_b128 v[196:199], v159 offset:5120
	ds_read_b128 v[200:203], v159 offset:6144
	global_load_lds_dwordx4 v142, s[2:3]
	s_add_i32 m0, s41, 0xe000
	ds_read_b128 v[204:207], v159 offset:7168
	global_load_lds_dwordx4 v146, s[2:3]
	s_waitcnt lgkmcnt(8)
	s_barrier
	s_waitcnt lgkmcnt(0)
	v_mfma_f32_16x16x32_bf16 v[124:127], v[128:131], v[160:163], v[124:127]
	v_mfma_f32_16x16x32_bf16 v[120:123], v[148:151], v[160:163], v[120:123]
	v_mfma_f32_16x16x32_bf16 v[108:111], v[128:131], v[168:171], v[108:111]
	v_mfma_f32_16x16x32_bf16 v[104:107], v[148:151], v[168:171], v[104:107]
	v_mfma_f32_16x16x32_bf16 v[92:95], v[128:131], v[176:179], v[92:95]
	v_mfma_f32_16x16x32_bf16 v[88:91], v[148:151], v[176:179], v[88:91]
	v_mfma_f32_16x16x32_bf16 v[76:79], v[128:131], v[200:203], v[76:79]
	v_mfma_f32_16x16x32_bf16 v[72:75], v[148:151], v[200:203], v[72:75]
	v_mfma_f32_16x16x32_bf16 v[124:127], v[132:135], v[164:167], v[124:127]
	v_mfma_f32_16x16x32_bf16 v[120:123], v[152:155], v[164:167], v[120:123]
	v_mfma_f32_16x16x32_bf16 v[108:111], v[132:135], v[172:175], v[108:111]
	v_mfma_f32_16x16x32_bf16 v[104:107], v[152:155], v[172:175], v[104:107]
	v_mfma_f32_16x16x32_bf16 v[92:95], v[132:135], v[196:199], v[92:95]
	v_mfma_f32_16x16x32_bf16 v[88:91], v[152:155], v[196:199], v[88:91]
	v_mfma_f32_16x16x32_bf16 v[76:79], v[132:135], v[204:207], v[76:79]
	v_mfma_f32_16x16x32_bf16 v[72:75], v[152:155], v[204:207], v[72:75]
	s_barrier
	s_add_i32 s55, s40, 0x10000
	ds_read_b128 v[208:211], v225
	ds_read_b128 v[212:215], v225 offset:1024
	s_add_u32 vcc_lo, s4, s0
	s_addc_u32 vcc_hi, s5, s1
	s_mov_b32 m0, s55
	ds_read_b128 v[220:223], v225 offset:3072
	global_load_lds_dwordx4 v144, s[4:5]
	s_add_i32 m0, s55, 0x2000
	ds_read_b128 v[216:219], v225 offset:2048
	global_load_lds_dwordx4 v136, s[4:5]
	s_barrier
	s_waitcnt lgkmcnt(0)
	v_mfma_f32_16x16x32_bf16 v[116:119], v[208:211], v[160:163], v[116:119]
	v_mfma_f32_16x16x32_bf16 v[112:115], v[216:219], v[160:163], v[112:115]
	v_mfma_f32_16x16x32_bf16 v[100:103], v[208:211], v[168:171], v[100:103]
	v_mfma_f32_16x16x32_bf16 v[96:99], v[216:219], v[168:171], v[96:99]
	v_mfma_f32_16x16x32_bf16 v[84:87], v[208:211], v[176:179], v[84:87]
	v_mfma_f32_16x16x32_bf16 v[80:83], v[216:219], v[176:179], v[80:83]
	v_mfma_f32_16x16x32_bf16 v[68:71], v[208:211], v[200:203], v[68:71]
	v_mfma_f32_16x16x32_bf16 v[64:67], v[216:219], v[200:203], v[64:67]
	v_mfma_f32_16x16x32_bf16 v[116:119], v[212:215], v[164:167], v[116:119]
	v_mfma_f32_16x16x32_bf16 v[112:115], v[220:223], v[164:167], v[112:115]
	v_mfma_f32_16x16x32_bf16 v[100:103], v[212:215], v[172:175], v[100:103]
	v_mfma_f32_16x16x32_bf16 v[96:99], v[220:223], v[172:175], v[96:99]
	v_mfma_f32_16x16x32_bf16 v[84:87], v[212:215], v[196:199], v[84:87]
	v_mfma_f32_16x16x32_bf16 v[80:83], v[220:223], v[196:199], v[80:83]
	v_mfma_f32_16x16x32_bf16 v[68:71], v[212:215], v[204:207], v[68:71]
	v_mfma_f32_16x16x32_bf16 v[64:67], v[220:223], v[204:207], v[64:67]
	s_mov_b32 m0, s41
	s_add_u32 s100, s28, s0
	s_addc_u32 s101, s29, s1
	s_barrier
	ds_read_b128 v[160:163], v159 offset:16384
	ds_read_b128 v[164:167], v159 offset:17408
	ds_read_b128 v[168:171], v159 offset:18432
	ds_read_b128 v[172:175], v159 offset:19456
	ds_read_b128 v[176:179], v159 offset:20480
	ds_read_b128 v[196:199], v159 offset:21504
	ds_read_b128 v[200:203], v159 offset:22528
	global_load_lds_dwordx4 v140, s[28:29]
	s_mov_b32 m0, s42
	ds_read_b128 v[204:207], v159 offset:23552
	global_load_lds_dwordx4 v138, s[28:29]
	s_barrier
	s_waitcnt lgkmcnt(0)
	v_mfma_f32_16x16x32_bf16 v[60:63], v[128:131], v[160:163], v[60:63]
	v_mfma_f32_16x16x32_bf16 v[56:59], v[148:151], v[160:163], v[56:59]
	v_mfma_f32_16x16x32_bf16 v[44:47], v[128:131], v[168:171], v[44:47]
	v_mfma_f32_16x16x32_bf16 v[40:43], v[148:151], v[168:171], v[40:43]
	v_mfma_f32_16x16x32_bf16 v[28:31], v[128:131], v[176:179], v[28:31]
	v_mfma_f32_16x16x32_bf16 v[24:27], v[148:151], v[176:179], v[24:27]
	v_mfma_f32_16x16x32_bf16 v[12:15], v[128:131], v[200:203], v[12:15]
	v_mfma_f32_16x16x32_bf16 v[8:11], v[148:151], v[200:203], v[8:11]
	v_mfma_f32_16x16x32_bf16 v[60:63], v[132:135], v[164:167], v[60:63]
	v_mfma_f32_16x16x32_bf16 v[56:59], v[152:155], v[164:167], v[56:59]
	v_mfma_f32_16x16x32_bf16 v[44:47], v[132:135], v[172:175], v[44:47]
	v_mfma_f32_16x16x32_bf16 v[40:43], v[152:155], v[172:175], v[40:43]
	v_mfma_f32_16x16x32_bf16 v[28:31], v[132:135], v[196:199], v[28:31]
	v_mfma_f32_16x16x32_bf16 v[24:27], v[152:155], v[196:199], v[24:27]
	v_mfma_f32_16x16x32_bf16 v[12:15], v[132:135], v[204:207], v[12:15]
	v_mfma_f32_16x16x32_bf16 v[8:11], v[152:155], v[204:207], v[8:11]
	s_barrier
	s_add_u32 s56, s4, 0x40000
	s_addc_u32 s57, s5, 0
	s_add_i32 s55, s40, 0x14000
	s_mov_b32 m0, s55
	s_nop 0
	global_load_lds_dwordx4 v144, s[56:57]
	s_add_i32 m0, s55, 0x2000
	s_nop 0
	global_load_lds_dwordx4 v136, s[56:57]
	s_waitcnt vmcnt(6)
	s_barrier
; #define PG8_STAGE(bufoff, gbase, voff) do { _Pragma("unroll") for (int _i = 0; _i < 2; ++_i) \
;     __builtin_amdgcn_global_load_lds((const unsigned*)((const char*)(gbase) + (voff)[_i]), (LAS unsigned*)(lds + (bufoff) + ldsw + _i * 8192), 16, 0, 0); } while (0)
; #define PG8_LDA(dst, b, h) do { _Pragma("unroll") for (int m = 0; m < 4; ++m) _Pragma("unroll") for (int k = 0; k < 2; ++k) dst[m][k] = *(const LAS bf16x8*)(lds + PG8_SA(b, h) + aoff + m * 2048 + k * 1024); } while (0)
; #define PG8_LDB(dst, b, h) do { _Pragma("unroll") for (int n = 0; n < 2; ++n) _Pragma("unroll") for (int k = 0; k < 2; ++k) dst[n][k] = *(const LAS bf16x8*)(lds + PG8_SB(b, h) + boff + n * 2048 + k * 1024); } while (0)
; #define PG8_MMA(ai, bj, At, Bt) do { __builtin_amdgcn_s_setprio(1); _Pragma("unroll") for (int m = 0; m < 4; ++m) _Pragma("unroll") for (int n = 0; n < 2; ++n) _Pragma("unroll") for (int k = 0; k < 2; ++k) \
;     acc[ai][bj][m][n] = __builtin_amdgcn_mfma_f32_16x16x32_bf16(Bt[n][k], At[m][k], acc[ai][bj][m][n], 0, 0, 0); __builtin_amdgcn_s_setprio(0); } while (0)
; #define PG8_WAIT_V(n) asm volatile("s_waitcnt vmcnt(" #n ")" ::: "memory")
; #define PG8_WAIT_L(n) asm volatile("s_waitcnt lgkmcnt(" #n ")" ::: "memory")
; #define PG8_BAR __builtin_amdgcn_s_barrier()
; #define PG8_SCHED __builtin_amdgcn_sched_barrier(0)
; template <class Epi, class Sched>
; DI void gemm_phase(LAS unsigned char* lds, const Gemm g, const Sched& S, const Epi& E) {
;     ...
;       PG8_WAIT_V(6); PG8_BAR; PG8_MMA(1, 1, At, B1); PG8_BAR;
;       PG8_LDB(B0, 1, 0); PG8_SCHED; PG8_LDA(At, 1, 0); PG8_STAGE(PG8_SA(0, 1), a2 + hstep, voffA);
;       PG8_WAIT_L(8); PG8_BAR; PG8_WAIT_L(0); PG8_MMA(0, 0, At, B0); PG8_BAR; PG8_SCHED;
;       PG8_LDB(B1, 1, 1); PG8_STAGE(PG8_SB(1, 0), b3, voffB);
;       PG8_BAR; PG8_WAIT_L(0); PG8_MMA(0, 1, At, B1); PG8_BAR;
;       PG8_LDA(At, 1, 1); PG8_STAGE(PG8_SA(1, 0), a3, voffA);
;       PG8_BAR; PG8_WAIT_L(0); PG8_MMA(1, 0, At, B0); PG8_BAR; PG8_SCHED;
	v_mfma_f32_16x16x32_bf16 v[52:55], v[208:211], v[160:163], v[52:55]
	v_mfma_f32_16x16x32_bf16 v[48:51], v[216:219], v[160:163], v[48:51]
	v_mfma_f32_16x16x32_bf16 v[36:39], v[208:211], v[168:171], v[36:39]
	v_mfma_f32_16x16x32_bf16 v[32:35], v[216:219], v[168:171], v[32:35]
	v_mfma_f32_16x16x32_bf16 v[20:23], v[208:211], v[176:179], v[20:23]
	v_mfma_f32_16x16x32_bf16 v[16:19], v[216:219], v[176:179], v[16:19]
	v_mfma_f32_16x16x32_bf16 v[4:7], v[208:211], v[200:203], v[4:7]
	v_mfma_f32_16x16x32_bf16 v[0:3], v[216:219], v[200:203], v[0:3]
	v_mfma_f32_16x16x32_bf16 v[52:55], v[212:215], v[164:167], v[52:55]
	v_mfma_f32_16x16x32_bf16 v[48:51], v[220:223], v[164:167], v[48:51]
	v_mfma_f32_16x16x32_bf16 v[36:39], v[212:215], v[172:175], v[36:39]
	v_mfma_f32_16x16x32_bf16 v[32:35], v[220:223], v[172:175], v[32:35]
	v_mfma_f32_16x16x32_bf16 v[20:23], v[212:215], v[196:199], v[20:23]
	v_mfma_f32_16x16x32_bf16 v[16:19], v[220:223], v[196:199], v[16:19]
	v_mfma_f32_16x16x32_bf16 v[4:7], v[212:215], v[204:207], v[4:7]
	v_mfma_f32_16x16x32_bf16 v[0:3], v[220:223], v[204:207], v[0:3]
	s_barrier
	ds_read_b128 v[128:131], v226
	ds_read_b128 v[132:135], v226 offset:1024
	ds_read_b128 v[148:151], v226 offset:2048
	ds_read_b128 v[152:155], v226 offset:3072
	s_add_u32 s28, s28, 0x40000
	s_addc_u32 s29, s29, 0
	s_mov_b32 m0, s43
	ds_read_b128 v[160:163], v159 offset:32768
	ds_read_b128 v[164:167], v159 offset:33792
	ds_read_b128 v[168:171], v159 offset:34816
	ds_read_b128 v[172:175], v159 offset:35840
	ds_read_b128 v[176:179], v159 offset:36864
	ds_read_b128 v[196:199], v159 offset:37888
	ds_read_b128 v[200:203], v159 offset:38912
	global_load_lds_dwordx4 v140, s[28:29]
	s_mov_b32 m0, s44
	ds_read_b128 v[204:207], v159 offset:39936
	global_load_lds_dwordx4 v138, s[28:29]
	s_waitcnt lgkmcnt(8)
	s_barrier
	s_waitcnt lgkmcnt(0)
	v_mfma_f32_16x16x32_bf16 v[124:127], v[128:131], v[160:163], v[124:127]
	v_mfma_f32_16x16x32_bf16 v[120:123], v[148:151], v[160:163], v[120:123]
	v_mfma_f32_16x16x32_bf16 v[108:111], v[128:131], v[168:171], v[108:111]
	v_mfma_f32_16x16x32_bf16 v[104:107], v[148:151], v[168:171], v[104:107]
	v_mfma_f32_16x16x32_bf16 v[92:95], v[128:131], v[176:179], v[92:95]
	v_mfma_f32_16x16x32_bf16 v[88:91], v[148:151], v[176:179], v[88:91]
	v_mfma_f32_16x16x32_bf16 v[76:79], v[128:131], v[200:203], v[76:79]
	v_mfma_f32_16x16x32_bf16 v[72:75], v[148:151], v[200:203], v[72:75]
	v_mfma_f32_16x16x32_bf16 v[124:127], v[132:135], v[164:167], v[124:127]
	v_mfma_f32_16x16x32_bf16 v[120:123], v[152:155], v[164:167], v[120:123]
	v_mfma_f32_16x16x32_bf16 v[108:111], v[132:135], v[172:175], v[108:111]
	v_mfma_f32_16x16x32_bf16 v[104:107], v[152:155], v[172:175], v[104:107]
	v_mfma_f32_16x16x32_bf16 v[92:95], v[132:135], v[196:199], v[92:95]
	v_mfma_f32_16x16x32_bf16 v[88:91], v[152:155], v[196:199], v[88:91]
	v_mfma_f32_16x16x32_bf16 v[76:79], v[132:135], v[204:207], v[76:79]
	v_mfma_f32_16x16x32_bf16 v[72:75], v[152:155], v[204:207], v[72:75]
	s_barrier
	s_add_i32 s29, s40, 0x18000
	s_mov_b32 m0, s29
	ds_read_b128 v[208:211], v227
	ds_read_b128 v[212:215], v227 offset:1024
	ds_read_b128 v[216:219], v227 offset:2048
	global_load_lds_dwordx4 v144, vcc
	s_add_i32 m0, s29, 0x2000
	ds_read_b128 v[220:223], v227 offset:3072
	global_load_lds_dwordx4 v136, vcc
	s_barrier
	s_waitcnt lgkmcnt(0)
	v_mfma_f32_16x16x32_bf16 v[116:119], v[208:211], v[160:163], v[116:119]
	v_mfma_f32_16x16x32_bf16 v[112:115], v[216:219], v[160:163], v[112:115]
	v_mfma_f32_16x16x32_bf16 v[100:103], v[208:211], v[168:171], v[100:103]
	v_mfma_f32_16x16x32_bf16 v[96:99], v[216:219], v[168:171], v[96:99]
	v_mfma_f32_16x16x32_bf16 v[84:87], v[208:211], v[176:179], v[84:87]
	v_mfma_f32_16x16x32_bf16 v[80:83], v[216:219], v[176:179], v[80:83]
	v_mfma_f32_16x16x32_bf16 v[68:71], v[208:211], v[200:203], v[68:71]
	v_mfma_f32_16x16x32_bf16 v[64:67], v[216:219], v[200:203], v[64:67]
	v_mfma_f32_16x16x32_bf16 v[116:119], v[212:215], v[164:167], v[116:119]
	v_mfma_f32_16x16x32_bf16 v[112:115], v[220:223], v[164:167], v[112:115]
	v_mfma_f32_16x16x32_bf16 v[100:103], v[212:215], v[172:175], v[100:103]
	v_mfma_f32_16x16x32_bf16 v[96:99], v[220:223], v[172:175], v[96:99]
	v_mfma_f32_16x16x32_bf16 v[84:87], v[212:215], v[196:199], v[84:87]
	v_mfma_f32_16x16x32_bf16 v[80:83], v[220:223], v[196:199], v[80:83]
	v_mfma_f32_16x16x32_bf16 v[68:71], v[212:215], v[204:207], v[68:71]
	v_mfma_f32_16x16x32_bf16 v[64:67], v[220:223], v[204:207], v[64:67]
	s_mov_b32 m0, s49
	s_barrier
; DI float bf2f(unsigned v) { return __uint_as_float(v << 16); }
; #define PG8_STAGE(bufoff, gbase, voff) do { _Pragma("unroll") for (int _i = 0; _i < 2; ++_i) \
;     __builtin_amdgcn_global_load_lds((const unsigned*)((const char*)(gbase) + (voff)[_i]), (LAS unsigned*)(lds + (bufoff) + ldsw + _i * 8192), 16, 0, 0); } while (0)
; #define PG8_MMA(ai, bj, At, Bt) do { __builtin_amdgcn_s_setprio(1); _Pragma("unroll") for (int m = 0; m < 4; ++m) _Pragma("unroll") for (int n = 0; n < 2; ++n) _Pragma("unroll") for (int k = 0; k < 2; ++k) \
;     acc[ai][bj][m][n] = __builtin_amdgcn_mfma_f32_16x16x32_bf16(Bt[n][k], At[m][k], acc[ai][bj][m][n], 0, 0, 0); __builtin_amdgcn_s_setprio(0); } while (0)
; #define PG8_WAIT_V(n) asm volatile("s_waitcnt vmcnt(" #n ")" ::: "memory")
; #define PG8_WAIT_L(n) asm volatile("s_waitcnt lgkmcnt(" #n ")" ::: "memory")
; #define PG8_BAR __builtin_amdgcn_s_barrier()
; template <class Epi, class Sched>
; DI void gemm_phase(LAS unsigned char* lds, const Gemm g, const Sched& S, const Epi& E) {
;     ...
;       PG8_BAR; PG8_WAIT_L(0); PG8_MMA(1, 0, At, B0); PG8_BAR; PG8_SCHED;
;       PG8_STAGE(PG8_SB(1, 1), b3 + hstep, voffB);
;       PG8_WAIT_V(6); PG8_BAR; PG8_MMA(1, 1, At, B1); PG8_BAR;
;     }
;   DI void operator()(const f32x4 (&acc)[2][2][4][2], const pg8::Unit& u, int wr, int wc, int fr_, int fq_) const {
;     ...
;             } else if (EPI == EPI_RESID) {
;               if (n == 0) {
;                 const int f8 = u.pn * 256 + bj * 128 + wc * 32 + 8 * fq;
;                 const f32x4 v1 = acc[ai][bj][m][1];
;                 f32x4 r0, r1;
;                 if (rsrc) {
;                   r0 = *(const f32x4*)(rsrc + (size_t)token * 1024 + f8); r1 = *(const f32x4*)(rsrc + (size_t)token * 1024 + f8 + 4);
;                 } else {
;                   const u32x4 xu = *(const u32x4*)(xr + (size_t)token * 1024 + f8);
;                   r0 = (f32x4){bf2f(xu.x & 0xffffu), bf2f(xu.x >> 16), bf2f(xu.y & 0xffffu), bf2f(xu.y >> 16)};
;                   r1 = (f32x4){bf2f(xu.z & 0xffffu), bf2f(xu.z >> 16), bf2f(xu.w & 0xffffu), bf2f(xu.w >> 16)};
;                 }
;                 r0 += v; r1 += v1;
;                 st_bf8(xr + (size_t)token * 1024 + f8, r0, r1, 1.f);
;                 ssq += r0[0] * r0[0] + r0[1] * r0[1] + r0[2] * r0[2] + r0[3] * r0[3] + r1[0] * r1[0] + r1[1] * r1[1] + r1[2] * r1[2] + r1[3] * r1[3];
	ds_read_b128 v[160:163], v159 offset:49152
	ds_read_b128 v[164:167], v159 offset:50176
	ds_read_b128 v[168:171], v159 offset:51200
	ds_read_b128 v[172:175], v159 offset:52224
	ds_read_b128 v[176:179], v159 offset:53248
	ds_read_b128 v[196:199], v159 offset:54272
	ds_read_b128 v[200:203], v159 offset:55296
	global_load_lds_dwordx4 v140, s[100:101]
	s_mov_b32 m0, s50
	ds_read_b128 v[204:207], v159 offset:56320
	global_load_lds_dwordx4 v138, s[100:101]
	s_barrier
	s_waitcnt lgkmcnt(0)
	v_mfma_f32_16x16x32_bf16 v[60:63], v[128:131], v[160:163], v[60:63]
	v_mfma_f32_16x16x32_bf16 v[56:59], v[148:151], v[160:163], v[56:59]
	v_mfma_f32_16x16x32_bf16 v[44:47], v[128:131], v[168:171], v[44:47]
	v_mfma_f32_16x16x32_bf16 v[40:43], v[148:151], v[168:171], v[40:43]
	v_mfma_f32_16x16x32_bf16 v[28:31], v[128:131], v[176:179], v[28:31]
	v_mfma_f32_16x16x32_bf16 v[24:27], v[148:151], v[176:179], v[24:27]
	v_mfma_f32_16x16x32_bf16 v[12:15], v[128:131], v[200:203], v[12:15]
	v_mfma_f32_16x16x32_bf16 v[8:11], v[148:151], v[200:203], v[8:11]
	v_mfma_f32_16x16x32_bf16 v[60:63], v[132:135], v[164:167], v[60:63]
	v_mfma_f32_16x16x32_bf16 v[56:59], v[152:155], v[164:167], v[56:59]
	v_mfma_f32_16x16x32_bf16 v[44:47], v[132:135], v[172:175], v[44:47]
	v_mfma_f32_16x16x32_bf16 v[40:43], v[152:155], v[172:175], v[40:43]
	v_mfma_f32_16x16x32_bf16 v[28:31], v[132:135], v[196:199], v[28:31]
	v_mfma_f32_16x16x32_bf16 v[24:27], v[152:155], v[196:199], v[24:27]
	v_mfma_f32_16x16x32_bf16 v[12:15], v[132:135], v[204:207], v[12:15]
	v_mfma_f32_16x16x32_bf16 v[8:11], v[152:155], v[204:207], v[8:11]
	s_barrier
	s_add_u32 s4, s4, 0x40080
	s_addc_u32 s5, s5, 0
	s_add_i32 s28, s40, 0x1c000
	s_mov_b32 m0, s28
	s_nop 0
	global_load_lds_dwordx4 v144, s[4:5]
	s_add_i32 m0, s28, 0x2000
	s_nop 0
	global_load_lds_dwordx4 v136, s[4:5]
	s_waitcnt vmcnt(6)
	s_barrier
	v_mfma_f32_16x16x32_bf16 v[52:55], v[208:211], v[160:163], v[52:55]
	v_mfma_f32_16x16x32_bf16 v[48:51], v[216:219], v[160:163], v[48:51]
	v_mfma_f32_16x16x32_bf16 v[36:39], v[208:211], v[168:171], v[36:39]
	v_mfma_f32_16x16x32_bf16 v[32:35], v[216:219], v[168:171], v[32:35]
	v_mfma_f32_16x16x32_bf16 v[20:23], v[208:211], v[176:179], v[20:23]
	v_mfma_f32_16x16x32_bf16 v[16:19], v[216:219], v[176:179], v[16:19]
	v_mfma_f32_16x16x32_bf16 v[4:7], v[208:211], v[200:203], v[4:7]
	v_mfma_f32_16x16x32_bf16 v[0:3], v[216:219], v[200:203], v[0:3]
	v_mfma_f32_16x16x32_bf16 v[52:55], v[212:215], v[164:167], v[52:55]
	v_mfma_f32_16x16x32_bf16 v[48:51], v[220:223], v[164:167], v[48:51]
	v_mfma_f32_16x16x32_bf16 v[36:39], v[212:215], v[172:175], v[36:39]
	v_mfma_f32_16x16x32_bf16 v[32:35], v[220:223], v[172:175], v[32:35]
	v_mfma_f32_16x16x32_bf16 v[20:23], v[212:215], v[196:199], v[20:23]
	v_mfma_f32_16x16x32_bf16 v[16:19], v[220:223], v[196:199], v[16:19]
	v_mfma_f32_16x16x32_bf16 v[4:7], v[212:215], v[204:207], v[4:7]
	v_mfma_f32_16x16x32_bf16 v[0:3], v[220:223], v[204:207], v[0:3]
	s_add_i32 s54, s54, 2
	s_add_u32 s2, s2, 0x100
	s_addc_u32 s3, s3, 0
	s_add_u32 s52, s52, 0x100
	s_addc_u32 s53, s53, 0
	s_cmp_gt_u32 s54, 13
	s_barrier
	s_cbranch_scc0 .LBB0_1644
	s_lshl_b32 s2, s34, 8
	v_mov_b32_e32 v161, v182
	s_add_i32 s2, s2, s47
	v_cndmask_b32_e64 v130, 0, 1, s[14:15]
	v_and_or_b32 v150, v161, 15, s2
	s_lshl_b32 s2, s24, 8
	v_bfe_u32 v160, v161, 4, 2
	s_or_b32 s2, s2, s48
	v_ashrrev_i32_e32 v151, 31, v150
	v_lshl_or_b32 v148, v160, 3, s2
	v_lshlrev_b64 v[128:129], 12, v[150:151]
	v_ashrrev_i32_e32 v149, 31, v148
	v_lshl_add_u64 v[128:129], s[6:7], 0, v[128:129]
	v_cmp_ne_u32_e64 s[2:3], 1, v130
	s_andn2_b64 vcc, exec, s[14:15]
	v_lshl_add_u64 v[154:155], v[148:149], 2, v[128:129]
	s_cbranch_vccnz .LBB0_1647
	global_load_dwordx4 v[132:135], v[154:155], off offset:16
	global_load_dwordx4 v[128:131], v[154:155], off
	s_mov_b64 s[4:5], 0
	s_branch .LBB0_1648

; #define PG8_STAGE(bufoff, gbase, voff) do { _Pragma("unroll") for (int _i = 0; _i < 2; ++_i) \
;     __builtin_amdgcn_global_load_lds((const unsigned*)((const char*)(gbase) + (voff)[_i]), (LAS unsigned*)(lds + (bufoff) + ldsw + _i * 8192), 16, 0, 0); } while (0)
; #define PG8_LDA(dst, b, h) do { _Pragma("unroll") for (int m = 0; m < 4; ++m) _Pragma("unroll") for (int k = 0; k < 2; ++k) dst[m][k] = *(const LAS bf16x8*)(lds + PG8_SA(b, h) + aoff + m * 2048 + k * 1024); } while (0)
; #define PG8_LDB(dst, b, h) do { _Pragma("unroll") for (int n = 0; n < 2; ++n) _Pragma("unroll") for (int k = 0; k < 2; ++k) dst[n][k] = *(const LAS bf16x8*)(lds + PG8_SB(b, h) + boff + n * 2048 + k * 1024); } while (0)
; #define PG8_MMA(ai, bj, At, Bt) do { __builtin_amdgcn_s_setprio(1); _Pragma("unroll") for (int m = 0; m < 4; ++m) _Pragma("unroll") for (int n = 0; n < 2; ++n) _Pragma("unroll") for (int k = 0; k < 2; ++k) \
;     acc[ai][bj][m][n] = __builtin_amdgcn_mfma_f32_16x16x32_bf16(Bt[n][k], At[m][k], acc[ai][bj][m][n], 0, 0, 0); __builtin_amdgcn_s_setprio(0); } while (0)
; #define PG8_WAIT_V(n) asm volatile("s_waitcnt vmcnt(" #n ")" ::: "memory")
; #define PG8_WAIT_L(n) asm volatile("s_waitcnt lgkmcnt(" #n ")" ::: "memory")
; #define PG8_BAR __builtin_amdgcn_s_barrier()
; #define PG8_SCHED __builtin_amdgcn_sched_barrier(0)
; template <class Epi, class Sched>
; DI void gemm_phase(LAS unsigned char* lds, const Gemm g, const Sched& S, const Epi& E) {
;     ...
;     for (int t = 0; t < nt; t += 2) {
;       const bool last = (t == nt - 2);
;       const char* a1 = cA + (size_t)(t + 1) * kstep;
;       const char* a2 = last ? nA : cA + (size_t)(t + 2) * kstep; const char* b2 = last ? nB : cB + (size_t)(t + 2) * kstep;
;       const char* a3 = a2 + kstep; const char* b3 = b2 + kstep;
;       PG8_LDB(B0, 0, 0); PG8_SCHED; PG8_LDA(At, 0, 0); PG8_STAGE(PG8_SA(1, 1), a1 + hstep, voffA);
;       PG8_WAIT_L(8); PG8_BAR; PG8_WAIT_L(0); PG8_MMA(0, 0, At, B0); PG8_BAR; PG8_SCHED;
;       PG8_LDB(B1, 0, 1); PG8_STAGE(PG8_SB(0, 0), b2, voffB);
;       PG8_BAR; PG8_WAIT_L(0); PG8_MMA(0, 1, At, B1); PG8_BAR;
;       PG8_LDA(At, 0, 1); PG8_STAGE(PG8_SA(0, 0), a2, voffA);
;       PG8_BAR; PG8_WAIT_L(0); PG8_MMA(1, 0, At, B0); PG8_BAR; PG8_SCHED;
;       PG8_STAGE(PG8_SB(0, 1), b2 + hstep, voffB);
;       PG8_WAIT_V(6); PG8_BAR; PG8_MMA(1, 1, At, B1); PG8_BAR;
.LBB0_1829:
	s_add_u32 s16, s14, 0xfffc0080
	s_addc_u32 s17, s15, -1
	ds_read_b128 v[146:149], v224
	ds_read_b128 v[150:153], v224 offset:1024
	ds_read_b128 v[154:157], v224 offset:2048
	ds_read_b128 v[158:161], v224 offset:3072
	s_cmp_eq_u32 s50, 12
	s_cselect_b32 s19, s7, s17
	s_cselect_b32 s18, s46, s16
	s_cselect_b32 s17, s5, s49
	s_cselect_b32 s16, s47, s48
	s_add_i32 m0, s29, 0xc000
	ds_read_b128 v[162:165], v143
	ds_read_b128 v[166:169], v143 offset:1024
	ds_read_b128 v[170:173], v143 offset:2048
	ds_read_b128 v[174:177], v143 offset:3072
	ds_read_b128 v[178:181], v143 offset:4096
	ds_read_b128 v[196:199], v143 offset:5120
	ds_read_b128 v[200:203], v143 offset:6144
	global_load_lds_dwordx4 v136, s[14:15]
	s_add_i32 m0, s29, 0xe000
	ds_read_b128 v[204:207], v143 offset:7168
	global_load_lds_dwordx4 v138, s[14:15]
	s_waitcnt lgkmcnt(8)
	s_barrier
	s_waitcnt lgkmcnt(0)
	v_mfma_f32_16x16x32_bf16 v[124:127], v[146:149], v[162:165], v[124:127]
	v_mfma_f32_16x16x32_bf16 v[120:123], v[154:157], v[162:165], v[120:123]
	v_mfma_f32_16x16x32_bf16 v[112:115], v[146:149], v[170:173], v[112:115]
	v_mfma_f32_16x16x32_bf16 v[104:107], v[154:157], v[170:173], v[104:107]
	v_mfma_f32_16x16x32_bf16 v[92:95], v[146:149], v[178:181], v[92:95]
	v_mfma_f32_16x16x32_bf16 v[88:91], v[154:157], v[178:181], v[88:91]
	v_mfma_f32_16x16x32_bf16 v[80:83], v[146:149], v[200:203], v[80:83]
	v_mfma_f32_16x16x32_bf16 v[72:75], v[154:157], v[200:203], v[72:75]
	v_mfma_f32_16x16x32_bf16 v[124:127], v[150:153], v[166:169], v[124:127]
	v_mfma_f32_16x16x32_bf16 v[120:123], v[158:161], v[166:169], v[120:123]
	v_mfma_f32_16x16x32_bf16 v[112:115], v[150:153], v[174:177], v[112:115]
	v_mfma_f32_16x16x32_bf16 v[104:107], v[158:161], v[174:177], v[104:107]
	v_mfma_f32_16x16x32_bf16 v[92:95], v[150:153], v[196:199], v[92:95]
	v_mfma_f32_16x16x32_bf16 v[88:91], v[158:161], v[196:199], v[88:91]
	v_mfma_f32_16x16x32_bf16 v[80:83], v[150:153], v[204:207], v[80:83]
	v_mfma_f32_16x16x32_bf16 v[72:75], v[158:161], v[204:207], v[72:75]
	s_barrier
	s_add_i32 s51, s20, 0x10000
	ds_read_b128 v[208:211], v225
	ds_read_b128 v[212:215], v225 offset:1024
	s_add_u32 vcc_lo, s16, s0
	s_addc_u32 vcc_hi, s17, s1
	s_mov_b32 m0, s51
	ds_read_b128 v[220:223], v225 offset:3072
	global_load_lds_dwordx4 v132, s[16:17]
	s_add_i32 m0, s51, 0x2000
	ds_read_b128 v[216:219], v225 offset:2048
	global_load_lds_dwordx4 v128, s[16:17]
	s_barrier
	s_waitcnt lgkmcnt(0)
	v_mfma_f32_16x16x32_bf16 v[116:119], v[208:211], v[162:165], v[116:119]
	v_mfma_f32_16x16x32_bf16 v[108:111], v[216:219], v[162:165], v[108:111]
	v_mfma_f32_16x16x32_bf16 v[100:103], v[208:211], v[170:173], v[100:103]
	v_mfma_f32_16x16x32_bf16 v[96:99], v[216:219], v[170:173], v[96:99]
	v_mfma_f32_16x16x32_bf16 v[84:87], v[208:211], v[178:181], v[84:87]
	v_mfma_f32_16x16x32_bf16 v[76:79], v[216:219], v[178:181], v[76:79]
	v_mfma_f32_16x16x32_bf16 v[68:71], v[208:211], v[200:203], v[68:71]
	v_mfma_f32_16x16x32_bf16 v[64:67], v[216:219], v[200:203], v[64:67]
	v_mfma_f32_16x16x32_bf16 v[116:119], v[212:215], v[166:169], v[116:119]
	v_mfma_f32_16x16x32_bf16 v[108:111], v[220:223], v[166:169], v[108:111]
	v_mfma_f32_16x16x32_bf16 v[100:103], v[212:215], v[174:177], v[100:103]
	v_mfma_f32_16x16x32_bf16 v[96:99], v[220:223], v[174:177], v[96:99]
	v_mfma_f32_16x16x32_bf16 v[84:87], v[212:215], v[196:199], v[84:87]
	v_mfma_f32_16x16x32_bf16 v[76:79], v[220:223], v[196:199], v[76:79]
	v_mfma_f32_16x16x32_bf16 v[68:71], v[212:215], v[204:207], v[68:71]
	v_mfma_f32_16x16x32_bf16 v[64:67], v[220:223], v[204:207], v[64:67]
	s_mov_b32 m0, s29
	s_add_u32 s100, s18, s0
	s_addc_u32 s101, s19, s1
	s_barrier
	ds_read_b128 v[162:165], v143 offset:16384
	ds_read_b128 v[166:169], v143 offset:17408
	ds_read_b128 v[170:173], v143 offset:18432
	ds_read_b128 v[174:177], v143 offset:19456
	ds_read_b128 v[178:181], v143 offset:20480
	ds_read_b128 v[196:199], v143 offset:21504
	ds_read_b128 v[200:203], v143 offset:22528
	global_load_lds_dwordx4 v134, s[18:19]
	s_mov_b32 m0, s34
	ds_read_b128 v[204:207], v143 offset:23552
	global_load_lds_dwordx4 v130, s[18:19]
	s_barrier
	s_waitcnt lgkmcnt(0)
	v_mfma_f32_16x16x32_bf16 v[60:63], v[146:149], v[162:165], v[60:63]
	v_mfma_f32_16x16x32_bf16 v[56:59], v[154:157], v[162:165], v[56:59]
	v_mfma_f32_16x16x32_bf16 v[48:51], v[146:149], v[170:173], v[48:51]
	v_mfma_f32_16x16x32_bf16 v[40:43], v[154:157], v[170:173], v[40:43]
	v_mfma_f32_16x16x32_bf16 v[28:31], v[146:149], v[178:181], v[28:31]
	v_mfma_f32_16x16x32_bf16 v[24:27], v[154:157], v[178:181], v[24:27]
	v_mfma_f32_16x16x32_bf16 v[16:19], v[146:149], v[200:203], v[16:19]
	v_mfma_f32_16x16x32_bf16 v[8:11], v[154:157], v[200:203], v[8:11]
	v_mfma_f32_16x16x32_bf16 v[60:63], v[150:153], v[166:169], v[60:63]
	v_mfma_f32_16x16x32_bf16 v[56:59], v[158:161], v[166:169], v[56:59]
	v_mfma_f32_16x16x32_bf16 v[48:51], v[150:153], v[174:177], v[48:51]
	v_mfma_f32_16x16x32_bf16 v[40:43], v[158:161], v[174:177], v[40:43]
	v_mfma_f32_16x16x32_bf16 v[28:31], v[150:153], v[196:199], v[28:31]
	v_mfma_f32_16x16x32_bf16 v[24:27], v[158:161], v[196:199], v[24:27]
	v_mfma_f32_16x16x32_bf16 v[16:19], v[150:153], v[204:207], v[16:19]
	v_mfma_f32_16x16x32_bf16 v[8:11], v[158:161], v[204:207], v[8:11]
	s_barrier
	s_add_u32 s52, s16, 0x40000
	s_addc_u32 s53, s17, 0
	s_add_i32 s51, s20, 0x14000
	s_mov_b32 m0, s51
	s_nop 0
	global_load_lds_dwordx4 v132, s[52:53]
	s_add_i32 m0, s51, 0x2000
	s_nop 0
	global_load_lds_dwordx4 v128, s[52:53]
	s_waitcnt vmcnt(6)
	s_barrier
; #define PG8_STAGE(bufoff, gbase, voff) do { _Pragma("unroll") for (int _i = 0; _i < 2; ++_i) \
;     __builtin_amdgcn_global_load_lds((const unsigned*)((const char*)(gbase) + (voff)[_i]), (LAS unsigned*)(lds + (bufoff) + ldsw + _i * 8192), 16, 0, 0); } while (0)
; #define PG8_LDA(dst, b, h) do { _Pragma("unroll") for (int m = 0; m < 4; ++m) _Pragma("unroll") for (int k = 0; k < 2; ++k) dst[m][k] = *(const LAS bf16x8*)(lds + PG8_SA(b, h) + aoff + m * 2048 + k * 1024); } while (0)
; #define PG8_LDB(dst, b, h) do { _Pragma("unroll") for (int n = 0; n < 2; ++n) _Pragma("unroll") for (int k = 0; k < 2; ++k) dst[n][k] = *(const LAS bf16x8*)(lds + PG8_SB(b, h) + boff + n * 2048 + k * 1024); } while (0)
; #define PG8_MMA(ai, bj, At, Bt) do { __builtin_amdgcn_s_setprio(1); _Pragma("unroll") for (int m = 0; m < 4; ++m) _Pragma("unroll") for (int n = 0; n < 2; ++n) _Pragma("unroll") for (int k = 0; k < 2; ++k) \
;     acc[ai][bj][m][n] = __builtin_amdgcn_mfma_f32_16x16x32_bf16(Bt[n][k], At[m][k], acc[ai][bj][m][n], 0, 0, 0); __builtin_amdgcn_s_setprio(0); } while (0)
; #define PG8_WAIT_V(n) asm volatile("s_waitcnt vmcnt(" #n ")" ::: "memory")
; #define PG8_WAIT_L(n) asm volatile("s_waitcnt lgkmcnt(" #n ")" ::: "memory")
; #define PG8_BAR __builtin_amdgcn_s_barrier()
; #define PG8_SCHED __builtin_amdgcn_sched_barrier(0)
; template <class Epi, class Sched>
; DI void gemm_phase(LAS unsigned char* lds, const Gemm g, const Sched& S, const Epi& E) {
;     ...
;       PG8_WAIT_V(6); PG8_BAR; PG8_MMA(1, 1, At, B1); PG8_BAR;
;       PG8_LDB(B0, 1, 0); PG8_SCHED; PG8_LDA(At, 1, 0); PG8_STAGE(PG8_SA(0, 1), a2 + hstep, voffA);
;       PG8_WAIT_L(8); PG8_BAR; PG8_WAIT_L(0); PG8_MMA(0, 0, At, B0); PG8_BAR; PG8_SCHED;
;       PG8_LDB(B1, 1, 1); PG8_STAGE(PG8_SB(1, 0), b3, voffB);
;       PG8_BAR; PG8_WAIT_L(0); PG8_MMA(0, 1, At, B1); PG8_BAR;
;       PG8_LDA(At, 1, 1); PG8_STAGE(PG8_SA(1, 0), a3, voffA);
;       PG8_BAR; PG8_WAIT_L(0); PG8_MMA(1, 0, At, B0); PG8_BAR; PG8_SCHED;
;       PG8_STAGE(PG8_SB(1, 1), b3 + hstep, voffB);
;       PG8_WAIT_V(6); PG8_BAR; PG8_MMA(1, 1, At, B1); PG8_BAR;
	v_mfma_f32_16x16x32_bf16 v[52:55], v[208:211], v[162:165], v[52:55]
	v_mfma_f32_16x16x32_bf16 v[44:47], v[216:219], v[162:165], v[44:47]
	v_mfma_f32_16x16x32_bf16 v[36:39], v[208:211], v[170:173], v[36:39]
	v_mfma_f32_16x16x32_bf16 v[32:35], v[216:219], v[170:173], v[32:35]
	v_mfma_f32_16x16x32_bf16 v[20:23], v[208:211], v[178:181], v[20:23]
	v_mfma_f32_16x16x32_bf16 v[12:15], v[216:219], v[178:181], v[12:15]
	v_mfma_f32_16x16x32_bf16 v[4:7], v[208:211], v[200:203], v[4:7]
	v_mfma_f32_16x16x32_bf16 v[0:3], v[216:219], v[200:203], v[0:3]
	v_mfma_f32_16x16x32_bf16 v[52:55], v[212:215], v[166:169], v[52:55]
	v_mfma_f32_16x16x32_bf16 v[44:47], v[220:223], v[166:169], v[44:47]
	v_mfma_f32_16x16x32_bf16 v[36:39], v[212:215], v[174:177], v[36:39]
	v_mfma_f32_16x16x32_bf16 v[32:35], v[220:223], v[174:177], v[32:35]
	v_mfma_f32_16x16x32_bf16 v[20:23], v[212:215], v[196:199], v[20:23]
	v_mfma_f32_16x16x32_bf16 v[12:15], v[220:223], v[196:199], v[12:15]
	v_mfma_f32_16x16x32_bf16 v[4:7], v[212:215], v[204:207], v[4:7]
	v_mfma_f32_16x16x32_bf16 v[0:3], v[220:223], v[204:207], v[0:3]
	s_barrier
	ds_read_b128 v[146:149], v226
	ds_read_b128 v[150:153], v226 offset:1024
	ds_read_b128 v[154:157], v226 offset:2048
	ds_read_b128 v[158:161], v226 offset:3072
	s_add_u32 s18, s18, 0x40000
	s_addc_u32 s19, s19, 0
	s_mov_b32 m0, s35
	ds_read_b128 v[162:165], v143 offset:32768
	ds_read_b128 v[166:169], v143 offset:33792
	ds_read_b128 v[170:173], v143 offset:34816
	ds_read_b128 v[174:177], v143 offset:35840
	ds_read_b128 v[178:181], v143 offset:36864
	ds_read_b128 v[196:199], v143 offset:37888
	ds_read_b128 v[200:203], v143 offset:38912
	global_load_lds_dwordx4 v134, s[18:19]
	s_mov_b32 m0, s38
	ds_read_b128 v[204:207], v143 offset:39936
	global_load_lds_dwordx4 v130, s[18:19]
	s_waitcnt lgkmcnt(8)
	s_barrier
	s_waitcnt lgkmcnt(0)
	v_mfma_f32_16x16x32_bf16 v[124:127], v[146:149], v[162:165], v[124:127]
	v_mfma_f32_16x16x32_bf16 v[120:123], v[154:157], v[162:165], v[120:123]
	v_mfma_f32_16x16x32_bf16 v[112:115], v[146:149], v[170:173], v[112:115]
	v_mfma_f32_16x16x32_bf16 v[104:107], v[154:157], v[170:173], v[104:107]
	v_mfma_f32_16x16x32_bf16 v[92:95], v[146:149], v[178:181], v[92:95]
	v_mfma_f32_16x16x32_bf16 v[88:91], v[154:157], v[178:181], v[88:91]
	v_mfma_f32_16x16x32_bf16 v[80:83], v[146:149], v[200:203], v[80:83]
	v_mfma_f32_16x16x32_bf16 v[72:75], v[154:157], v[200:203], v[72:75]
	v_mfma_f32_16x16x32_bf16 v[124:127], v[150:153], v[166:169], v[124:127]
	v_mfma_f32_16x16x32_bf16 v[120:123], v[158:161], v[166:169], v[120:123]
	v_mfma_f32_16x16x32_bf16 v[112:115], v[150:153], v[174:177], v[112:115]
	v_mfma_f32_16x16x32_bf16 v[104:107], v[158:161], v[174:177], v[104:107]
	v_mfma_f32_16x16x32_bf16 v[92:95], v[150:153], v[196:199], v[92:95]
	v_mfma_f32_16x16x32_bf16 v[88:91], v[158:161], v[196:199], v[88:91]
	v_mfma_f32_16x16x32_bf16 v[80:83], v[150:153], v[204:207], v[80:83]
	v_mfma_f32_16x16x32_bf16 v[72:75], v[158:161], v[204:207], v[72:75]
	s_barrier
	s_add_i32 s19, s20, 0x18000
	s_mov_b32 m0, s19
	ds_read_b128 v[208:211], v227
	ds_read_b128 v[212:215], v227 offset:1024
	ds_read_b128 v[216:219], v227 offset:2048
	global_load_lds_dwordx4 v132, vcc
	s_add_i32 m0, s19, 0x2000
	ds_read_b128 v[220:223], v227 offset:3072
	global_load_lds_dwordx4 v128, vcc
	s_barrier
	s_waitcnt lgkmcnt(0)
	v_mfma_f32_16x16x32_bf16 v[116:119], v[208:211], v[162:165], v[116:119]
	v_mfma_f32_16x16x32_bf16 v[108:111], v[216:219], v[162:165], v[108:111]
	v_mfma_f32_16x16x32_bf16 v[100:103], v[208:211], v[170:173], v[100:103]
	v_mfma_f32_16x16x32_bf16 v[96:99], v[216:219], v[170:173], v[96:99]
	v_mfma_f32_16x16x32_bf16 v[84:87], v[208:211], v[178:181], v[84:87]
	v_mfma_f32_16x16x32_bf16 v[76:79], v[216:219], v[178:181], v[76:79]
	v_mfma_f32_16x16x32_bf16 v[68:71], v[208:211], v[200:203], v[68:71]
	v_mfma_f32_16x16x32_bf16 v[64:67], v[216:219], v[200:203], v[64:67]
	v_mfma_f32_16x16x32_bf16 v[116:119], v[212:215], v[166:169], v[116:119]
	v_mfma_f32_16x16x32_bf16 v[108:111], v[220:223], v[166:169], v[108:111]
	v_mfma_f32_16x16x32_bf16 v[100:103], v[212:215], v[174:177], v[100:103]
	v_mfma_f32_16x16x32_bf16 v[96:99], v[220:223], v[174:177], v[96:99]
	v_mfma_f32_16x16x32_bf16 v[84:87], v[212:215], v[196:199], v[84:87]
	v_mfma_f32_16x16x32_bf16 v[76:79], v[220:223], v[196:199], v[76:79]
	v_mfma_f32_16x16x32_bf16 v[68:71], v[212:215], v[204:207], v[68:71]
	v_mfma_f32_16x16x32_bf16 v[64:67], v[220:223], v[204:207], v[64:67]
	s_mov_b32 m0, s40
	s_barrier
	ds_read_b128 v[162:165], v143 offset:49152
	ds_read_b128 v[166:169], v143 offset:50176
	ds_read_b128 v[170:173], v143 offset:51200
	ds_read_b128 v[174:177], v143 offset:52224
	ds_read_b128 v[178:181], v143 offset:53248
	ds_read_b128 v[196:199], v143 offset:54272
	ds_read_b128 v[200:203], v143 offset:55296
	global_load_lds_dwordx4 v134, s[100:101]
	s_mov_b32 m0, s41
	ds_read_b128 v[204:207], v143 offset:56320
	global_load_lds_dwordx4 v130, s[100:101]
	s_barrier
	s_waitcnt lgkmcnt(0)
	v_mfma_f32_16x16x32_bf16 v[60:63], v[146:149], v[162:165], v[60:63]
	v_mfma_f32_16x16x32_bf16 v[56:59], v[154:157], v[162:165], v[56:59]
	v_mfma_f32_16x16x32_bf16 v[48:51], v[146:149], v[170:173], v[48:51]
	v_mfma_f32_16x16x32_bf16 v[40:43], v[154:157], v[170:173], v[40:43]
	v_mfma_f32_16x16x32_bf16 v[28:31], v[146:149], v[178:181], v[28:31]
	v_mfma_f32_16x16x32_bf16 v[24:27], v[154:157], v[178:181], v[24:27]
	v_mfma_f32_16x16x32_bf16 v[16:19], v[146:149], v[200:203], v[16:19]
	v_mfma_f32_16x16x32_bf16 v[8:11], v[154:157], v[200:203], v[8:11]
	v_mfma_f32_16x16x32_bf16 v[60:63], v[150:153], v[166:169], v[60:63]
	v_mfma_f32_16x16x32_bf16 v[56:59], v[158:161], v[166:169], v[56:59]
	v_mfma_f32_16x16x32_bf16 v[48:51], v[150:153], v[174:177], v[48:51]
	v_mfma_f32_16x16x32_bf16 v[40:43], v[158:161], v[174:177], v[40:43]
	v_mfma_f32_16x16x32_bf16 v[28:31], v[150:153], v[196:199], v[28:31]
	v_mfma_f32_16x16x32_bf16 v[24:27], v[158:161], v[196:199], v[24:27]
	v_mfma_f32_16x16x32_bf16 v[16:19], v[150:153], v[204:207], v[16:19]
	v_mfma_f32_16x16x32_bf16 v[8:11], v[158:161], v[204:207], v[8:11]
	s_barrier
; #define PG8_STAGE(bufoff, gbase, voff) do { _Pragma("unroll") for (int _i = 0; _i < 2; ++_i) \
;     __builtin_amdgcn_global_load_lds((const unsigned*)((const char*)(gbase) + (voff)[_i]), (LAS unsigned*)(lds + (bufoff) + ldsw + _i * 8192), 16, 0, 0); } while (0)
; #define PG8_MMA(ai, bj, At, Bt) do { __builtin_amdgcn_s_setprio(1); _Pragma("unroll") for (int m = 0; m < 4; ++m) _Pragma("unroll") for (int n = 0; n < 2; ++n) _Pragma("unroll") for (int k = 0; k < 2; ++k) \
;     acc[ai][bj][m][n] = __builtin_amdgcn_mfma_f32_16x16x32_bf16(Bt[n][k], At[m][k], acc[ai][bj][m][n], 0, 0, 0); __builtin_amdgcn_s_setprio(0); } while (0)
; #define PG8_WAIT_V(n) asm volatile("s_waitcnt vmcnt(" #n ")" ::: "memory")
; #define PG8_BAR __builtin_amdgcn_s_barrier()
; template <class Epi, class Sched>
; DI void gemm_phase(LAS unsigned char* lds, const Gemm g, const Sched& S, const Epi& E) {
;     ...
;       PG8_STAGE(PG8_SB(1, 1), b3 + hstep, voffB);
;       PG8_WAIT_V(6); PG8_BAR; PG8_MMA(1, 1, At, B1); PG8_BAR;
;     }
;     E(acc, cur, wr, wc, fr, fq);
;   DI void operator()(const f32x4 (&acc)[2][2][4][2], const pg8::Unit& u, int wr, int wc, int fr_, int fq_) const {
;     ...
;             } else {
;               if (n == 0) {
;                 const f32x4 v1 = acc[ai][bj][m][1];
;                 u32x4 o4;
;                 { const float t0 = fmaxf(v[0], 0.f) * rinv, t1 = fmaxf(v[1], 0.f) * rinv, t2 = fmaxf(v[2], 0.f) * rinv, t3 = fmaxf(v[3], 0.f) * rinv;
;                   o4.x = pack2(t0 * t0, t1 * t1); o4.y = pack2(t2 * t2, t3 * t3); }
;                 { const float t0 = fmaxf(v1[0], 0.f) * rinv, t1 = fmaxf(v1[1], 0.f) * rinv, t2 = fmaxf(v1[2], 0.f) * rinv, t3 = fmaxf(v1[3], 0.f) * rinv;
;                   o4.z = pack2(t0 * t0, t1 * t1); o4.w = pack2(t2 * t2, t3 * t3); }
;                 *(u32x4*)((u16*)big + (size_t)token * 4096 + u.pn * 256 + bj * 128 + wc * 32 + 8 * fq) = o4;
;               }
	s_add_u32 s16, s16, 0x40080
	s_addc_u32 s17, s17, 0
	s_add_i32 s18, s20, 0x1c000
	s_mov_b32 m0, s18
	s_nop 0
	global_load_lds_dwordx4 v132, s[16:17]
	s_add_i32 m0, s18, 0x2000
	s_nop 0
	global_load_lds_dwordx4 v128, s[16:17]
	s_waitcnt vmcnt(6)
	s_barrier
	v_mfma_f32_16x16x32_bf16 v[52:55], v[208:211], v[162:165], v[52:55]
	v_mfma_f32_16x16x32_bf16 v[44:47], v[216:219], v[162:165], v[44:47]
	v_mfma_f32_16x16x32_bf16 v[36:39], v[208:211], v[170:173], v[36:39]
	v_mfma_f32_16x16x32_bf16 v[32:35], v[216:219], v[170:173], v[32:35]
	v_mfma_f32_16x16x32_bf16 v[20:23], v[208:211], v[178:181], v[20:23]
	v_mfma_f32_16x16x32_bf16 v[12:15], v[216:219], v[178:181], v[12:15]
	v_mfma_f32_16x16x32_bf16 v[4:7], v[208:211], v[200:203], v[4:7]
	v_mfma_f32_16x16x32_bf16 v[0:3], v[216:219], v[200:203], v[0:3]
	v_mfma_f32_16x16x32_bf16 v[52:55], v[212:215], v[166:169], v[52:55]
	v_mfma_f32_16x16x32_bf16 v[44:47], v[220:223], v[166:169], v[44:47]
	v_mfma_f32_16x16x32_bf16 v[36:39], v[212:215], v[174:177], v[36:39]
	v_mfma_f32_16x16x32_bf16 v[32:35], v[220:223], v[174:177], v[32:35]
	v_mfma_f32_16x16x32_bf16 v[20:23], v[212:215], v[196:199], v[20:23]
	v_mfma_f32_16x16x32_bf16 v[12:15], v[220:223], v[196:199], v[12:15]
	v_mfma_f32_16x16x32_bf16 v[4:7], v[212:215], v[204:207], v[4:7]
	v_mfma_f32_16x16x32_bf16 v[0:3], v[220:223], v[204:207], v[0:3]
	s_add_i32 s50, s50, 2
	s_add_u32 s14, s14, 0x100
	s_addc_u32 s15, s15, 0
	s_add_u32 s48, s48, 0x100
	s_addc_u32 s49, s49, 0
	s_cmp_gt_u32 s50, 13
	s_barrier
	s_cbranch_scc0 .LBB0_1829
	v_mov_b32_e32 v144, v182
	s_lshl_b32 s5, s43, 10
	s_add_i32 s5, s5, 0
	v_and_or_b32 v141, v144, 15, s39
	v_lshl_add_u32 v140, s44, 8, v141
	v_lshl_add_u32 v141, v141, 2, s5
	v_add_u32_e32 v146, 0x20000, v141
	ds_read2_b32 v[148:149], v146 offset1:16
	v_max_f32_e32 v124, 0, v124
	v_max_f32_e32 v125, 0, v125
	v_max_f32_e32 v126, 0, v126
	v_max_f32_e32 v127, 0, v127
	v_max_f32_e32 v120, 0, v120
	v_max_f32_e32 v121, 0, v121
	s_waitcnt lgkmcnt(0)
	v_pk_mul_f32 v[124:125], v[124:125], v[148:149] op_sel_hi:[1,0]
	v_pk_mul_f32 v[126:127], v[126:127], v[148:149] op_sel_hi:[1,0]
	v_pk_mul_f32 v[120:121], v[120:121], v[148:149] op_sel_hi:[1,0]
	v_pk_mul_f32 v[124:125], v[124:125], v[124:125]
	v_pk_mul_f32 v[126:127], v[126:127], v[126:127]
	v_max_f32_e32 v122, 0, v122
	v_max_f32_e32 v123, 0, v123
	v_pk_mul_f32 v[120:121], v[120:121], v[120:121]
	v_max_f32_e32 v116, 0, v116
	v_max_f32_e32 v117, 0, v117
	v_max_f32_e32 v118, 0, v118
	v_max_f32_e32 v119, 0, v119
	v_max_f32_e32 v108, 0, v108
	v_max_f32_e32 v109, 0, v109
	s_lshl_b32 s14, s45, 8
	v_ashrrev_i32_e32 v141, 31, v140
	v_cvt_pk_bf16_f32 v124, v124, v125
	v_cvt_pk_bf16_f32 v125, v126, v127
	v_cvt_pk_bf16_f32 v126, v120, v121
	v_pk_mul_f32 v[120:121], v[122:123], v[148:149] op_sel_hi:[1,0]
	v_pk_mul_f32 v[116:117], v[116:117], v[148:149] op_sel_hi:[1,0]
	v_pk_mul_f32 v[118:119], v[118:119], v[148:149] op_sel_hi:[1,0]
	v_pk_mul_f32 v[108:109], v[108:109], v[148:149] op_sel_hi:[1,0]
	s_ashr_i32 s15, s14, 31
	v_lshlrev_b64 v[150:151], 13, v[140:141]
	v_pk_mul_f32 v[120:121], v[120:121], v[120:121]
	v_pk_mul_f32 v[116:117], v[116:117], v[116:117]
	v_pk_mul_f32 v[118:119], v[118:119], v[118:119]
	v_max_f32_e32 v110, 0, v110
	v_max_f32_e32 v111, 0, v111
	v_pk_mul_f32 v[108:109], v[108:109], v[108:109]
	v_cvt_pk_bf16_f32 v127, v120, v121
	v_lshl_add_u64 v[120:121], s[2:3], 0, v[150:151]
	s_lshl_b64 s[14:15], s[14:15], 1
	v_cvt_pk_bf16_f32 v116, v116, v117
	v_cvt_pk_bf16_f32 v117, v118, v119
	v_cvt_pk_bf16_f32 v118, v108, v109
	v_pk_mul_f32 v[108:109], v[110:111], v[148:149] op_sel_hi:[1,0]
	v_lshl_add_u64 v[120:121], v[120:121], 0, s[14:15]
	v_pk_mul_f32 v[108:109], v[108:109], v[108:109]
	v_lshl_add_u64 v[120:121], v[120:121], 0, s[24:25]
	v_and_b32_e32 v144, 48, v144
	v_cvt_pk_bf16_f32 v119, v108, v109
	v_add_u32_e32 v108, 16, v140
	v_lshl_add_u64 v[120:121], v[120:121], 0, v[144:145]
	v_ashrrev_i32_e32 v109, 31, v108
	global_store_dwordx4 v[120:121], v[116:119], off offset:256
	v_max_f32_e32 v100, 0, v100
	v_max_f32_e32 v101, 0, v101
	v_lshlrev_b64 v[116:117], 13, v[108:109]
	v_max_f32_e32 v108, v112, v112
	v_mov_b32_e32 v112, v149
	v_max_f32_e32 v102, 0, v102
	v_max_f32_e32 v103, 0, v103
	v_max_f32_e32 v96, 0, v96
	v_max_f32_e32 v97, 0, v97
	v_pk_mul_f32 v[100:101], v[100:101], v[112:113] op_sel_hi:[1,0]
	v_pk_mul_f32 v[102:103], v[102:103], v[112:113] op_sel_hi:[1,0]
	v_pk_mul_f32 v[96:97], v[96:97], v[112:113] op_sel_hi:[1,0]
	v_pk_mul_f32 v[100:101], v[100:101], v[100:101]
	v_pk_mul_f32 v[102:103], v[102:103], v[102:103]
	v_max_f32_e32 v98, 0, v98
	v_max_f32_e32 v99, 0, v99
	v_pk_mul_f32 v[96:97], v[96:97], v[96:97]
	v_cvt_pk_bf16_f32 v100, v100, v101
	v_cvt_pk_bf16_f32 v101, v102, v103
	v_cvt_pk_bf16_f32 v102, v96, v97
	v_pk_mul_f32 v[96:97], v[98:99], v[112:113] op_sel_hi:[1,0]
	ds_read2_b32 v[98:99], v146 offset0:32 offset1:48
	v_max_f32_e32 v92, 0, v92
	v_max_f32_e32 v93, 0, v93
	v_max_f32_e32 v94, 0, v94
	v_max_f32_e32 v95, 0, v95
	v_max_f32_e32 v88, 0, v88
	v_max_f32_e32 v89, 0, v89
	v_pk_mul_f32 v[96:97], v[96:97], v[96:97]
	s_waitcnt lgkmcnt(0)
;   DI void operator()(const f32x4 (&acc)[2][2][4][2], const pg8::Unit& u, int wr, int wc, int fr_, int fq_) const {
;     ...
;             } else {
;               if (n == 0) {
;                 const f32x4 v1 = acc[ai][bj][m][1];
;                 u32x4 o4;
;                 { const float t0 = fmaxf(v[0], 0.f) * rinv, t1 = fmaxf(v[1], 0.f) * rinv, t2 = fmaxf(v[2], 0.f) * rinv, t3 = fmaxf(v[3], 0.f) * rinv;
;                   o4.x = pack2(t0 * t0, t1 * t1); o4.y = pack2(t2 * t2, t3 * t3); }
;                 { const float t0 = fmaxf(v1[0], 0.f) * rinv, t1 = fmaxf(v1[1], 0.f) * rinv, t2 = fmaxf(v1[2], 0.f) * rinv, t3 = fmaxf(v1[3], 0.f) * rinv;
;                   o4.z = pack2(t0 * t0, t1 * t1); o4.w = pack2(t2 * t2, t3 * t3); }
;                 *(u32x4*)((u16*)big + (size_t)token * 4096 + u.pn * 256 + bj * 128 + wc * 32 + 8 * fq) = o4;
;               }
	v_pk_mul_f32 v[92:93], v[92:93], v[98:99] op_sel_hi:[1,0]
	v_pk_mul_f32 v[94:95], v[94:95], v[98:99] op_sel_hi:[1,0]
	v_pk_mul_f32 v[88:89], v[88:89], v[98:99] op_sel_hi:[1,0]
	v_cvt_pk_bf16_f32 v103, v96, v97
	v_add_u32_e32 v96, 32, v140
	v_pk_mul_f32 v[92:93], v[92:93], v[92:93]
	v_pk_mul_f32 v[94:95], v[94:95], v[94:95]
	v_max_f32_e32 v90, 0, v90
	v_max_f32_e32 v91, 0, v91
	v_pk_mul_f32 v[88:89], v[88:89], v[88:89]
	v_max_f32_e32 v84, 0, v84
	v_max_f32_e32 v85, 0, v85
	v_max_f32_e32 v86, 0, v86
	v_max_f32_e32 v87, 0, v87
	v_max_f32_e32 v76, 0, v76
	v_max_f32_e32 v77, 0, v77
	v_ashrrev_i32_e32 v97, 31, v96
	v_cvt_pk_bf16_f32 v92, v92, v93
	v_cvt_pk_bf16_f32 v93, v94, v95
	v_cvt_pk_bf16_f32 v94, v88, v89
	v_pk_mul_f32 v[88:89], v[90:91], v[98:99] op_sel_hi:[1,0]
	v_pk_mul_f32 v[84:85], v[84:85], v[98:99] op_sel_hi:[1,0]
	v_pk_mul_f32 v[86:87], v[86:87], v[98:99] op_sel_hi:[1,0]
	v_pk_mul_f32 v[76:77], v[76:77], v[98:99] op_sel_hi:[1,0]
	v_lshlrev_b64 v[96:97], 13, v[96:97]
	v_pk_mul_f32 v[88:89], v[88:89], v[88:89]
	v_pk_mul_f32 v[84:85], v[84:85], v[84:85]
	v_pk_mul_f32 v[86:87], v[86:87], v[86:87]
	v_max_f32_e32 v78, 0, v78
	v_max_f32_e32 v79, 0, v79
	v_pk_mul_f32 v[76:77], v[76:77], v[76:77]
	v_cvt_pk_bf16_f32 v95, v88, v89
	v_lshl_add_u64 v[88:89], s[2:3], 0, v[96:97]
	v_cvt_pk_bf16_f32 v84, v84, v85
	v_cvt_pk_bf16_f32 v85, v86, v87
	v_cvt_pk_bf16_f32 v86, v76, v77
	v_pk_mul_f32 v[76:77], v[78:79], v[98:99] op_sel_hi:[1,0]
	v_lshl_add_u64 v[88:89], v[88:89], 0, s[14:15]
	v_pk_mul_f32 v[76:77], v[76:77], v[76:77]
	v_lshl_add_u64 v[88:89], v[88:89], 0, s[24:25]
	v_cvt_pk_bf16_f32 v87, v76, v77
	v_add_u32_e32 v76, 48, v140
	v_lshl_add_u64 v[88:89], v[88:89], 0, v[144:145]
	v_ashrrev_i32_e32 v77, 31, v76
	global_store_dwordx4 v[88:89], v[84:87], off offset:256
	v_max_f32_e32 v68, 0, v68
	v_max_f32_e32 v69, 0, v69
	v_lshlrev_b64 v[84:85], 13, v[76:77]
	v_max_f32_e32 v76, v80, v80
	v_mov_b32_e32 v80, v99
	v_max_f32_e32 v70, 0, v70
	v_max_f32_e32 v71, 0, v71
	v_max_f32_e32 v64, 0, v64
	v_max_f32_e32 v65, 0, v65
	v_pk_mul_f32 v[68:69], v[68:69], v[80:81] op_sel_hi:[1,0]
	v_pk_mul_f32 v[70:71], v[70:71], v[80:81] op_sel_hi:[1,0]
	v_pk_mul_f32 v[64:65], v[64:65], v[80:81] op_sel_hi:[1,0]
	v_pk_mul_f32 v[68:69], v[68:69], v[68:69]
	v_pk_mul_f32 v[70:71], v[70:71], v[70:71]
	v_max_f32_e32 v66, 0, v66
	v_max_f32_e32 v67, 0, v67
	v_pk_mul_f32 v[64:65], v[64:65], v[64:65]
	v_cvt_pk_bf16_f32 v68, v68, v69
	v_cvt_pk_bf16_f32 v69, v70, v71
	v_cvt_pk_bf16_f32 v70, v64, v65
	v_pk_mul_f32 v[64:65], v[66:67], v[80:81] op_sel_hi:[1,0]
	ds_read2_b32 v[66:67], v146 offset0:128 offset1:144
	v_max_f32_e32 v60, 0, v60
	v_max_f32_e32 v61, 0, v61
	v_max_f32_e32 v62, 0, v62
	v_max_f32_e32 v63, 0, v63
	v_max_f32_e32 v56, 0, v56
	v_max_f32_e32 v57, 0, v57
	v_pk_mul_f32 v[64:65], v[64:65], v[64:65]
	s_waitcnt lgkmcnt(0)
	v_pk_mul_f32 v[60:61], v[60:61], v[66:67] op_sel_hi:[1,0]
	v_pk_mul_f32 v[62:63], v[62:63], v[66:67] op_sel_hi:[1,0]
	v_pk_mul_f32 v[56:57], v[56:57], v[66:67] op_sel_hi:[1,0]
	v_cvt_pk_bf16_f32 v71, v64, v65
	v_add_u32_e32 v64, 0x80, v140
	v_pk_mul_f32 v[60:61], v[60:61], v[60:61]
	v_pk_mul_f32 v[62:63], v[62:63], v[62:63]
	v_max_f32_e32 v58, 0, v58
	v_max_f32_e32 v59, 0, v59
	v_pk_mul_f32 v[56:57], v[56:57], v[56:57]
	v_max_f32_e32 v52, 0, v52
	v_max_f32_e32 v53, 0, v53
	v_max_f32_e32 v54, 0, v54
	v_max_f32_e32 v55, 0, v55
	v_max_f32_e32 v44, 0, v44
	v_max_f32_e32 v45, 0, v45
	v_ashrrev_i32_e32 v65, 31, v64
	v_cvt_pk_bf16_f32 v60, v60, v61
	v_cvt_pk_bf16_f32 v61, v62, v63
	v_cvt_pk_bf16_f32 v62, v56, v57
	v_pk_mul_f32 v[56:57], v[58:59], v[66:67] op_sel_hi:[1,0]
	v_pk_mul_f32 v[52:53], v[52:53], v[66:67] op_sel_hi:[1,0]
	v_pk_mul_f32 v[54:55], v[54:55], v[66:67] op_sel_hi:[1,0]
	v_pk_mul_f32 v[44:45], v[44:45], v[66:67] op_sel_hi:[1,0]
	v_lshlrev_b64 v[64:65], 13, v[64:65]
	v_pk_mul_f32 v[56:57], v[56:57], v[56:57]
	v_pk_mul_f32 v[52:53], v[52:53], v[52:53]
	v_pk_mul_f32 v[54:55], v[54:55], v[54:55]
	v_max_f32_e32 v46, 0, v46
	v_max_f32_e32 v47, 0, v47
	v_pk_mul_f32 v[44:45], v[44:45], v[44:45]
	v_cvt_pk_bf16_f32 v63, v56, v57
	v_lshl_add_u64 v[56:57], s[2:3], 0, v[64:65]
	v_cvt_pk_bf16_f32 v52, v52, v53
	v_cvt_pk_bf16_f32 v53, v54, v55
	v_cvt_pk_bf16_f32 v54, v44, v45
	v_pk_mul_f32 v[44:45], v[46:47], v[66:67] op_sel_hi:[1,0]
	v_lshl_add_u64 v[56:57], v[56:57], 0, s[14:15]
	v_pk_mul_f32 v[44:45], v[44:45], v[44:45]
	v_lshl_add_u64 v[56:57], v[56:57], 0, s[24:25]
	v_cvt_pk_bf16_f32 v55, v44, v45
	v_add_u32_e32 v44, 0x90, v140
	v_lshl_add_u64 v[56:57], v[56:57], 0, v[144:145]
	v_ashrrev_i32_e32 v45, 31, v44
	global_store_dwordx4 v[56:57], v[52:55], off offset:256
	v_max_f32_e32 v36, 0, v36
	v_max_f32_e32 v37, 0, v37
	v_lshlrev_b64 v[52:53], 13, v[44:45]
	v_max_f32_e32 v44, v48, v48
	v_mov_b32_e32 v48, v67
	v_max_f32_e32 v38, 0, v38
	v_max_f32_e32 v39, 0, v39
	v_max_f32_e32 v32, 0, v32
	v_max_f32_e32 v33, 0, v33
	v_pk_mul_f32 v[36:37], v[36:37], v[48:49] op_sel_hi:[1,0]
	v_pk_mul_f32 v[38:39], v[38:39], v[48:49] op_sel_hi:[1,0]
	v_pk_mul_f32 v[32:33], v[32:33], v[48:49] op_sel_hi:[1,0]
	v_pk_mul_f32 v[36:37], v[36:37], v[36:37]
	v_pk_mul_f32 v[38:39], v[38:39], v[38:39]
	v_max_f32_e32 v34, 0, v34
	v_max_f32_e32 v35, 0, v35
	v_pk_mul_f32 v[32:33], v[32:33], v[32:33]
	v_cvt_pk_bf16_f32 v36, v36, v37
	v_cvt_pk_bf16_f32 v37, v38, v39
	v_cvt_pk_bf16_f32 v38, v32, v33
	v_pk_mul_f32 v[32:33], v[34:35], v[48:49] op_sel_hi:[1,0]
	ds_read2_b32 v[34:35], v146 offset0:160 offset1:176
	v_max_f32_e32 v28, 0, v28
	v_max_f32_e32 v29, 0, v29
	v_max_f32_e32 v30, 0, v30
	v_max_f32_e32 v31, 0, v31
	v_max_f32_e32 v24, 0, v24
	v_max_f32_e32 v25, 0, v25
	v_pk_mul_f32 v[32:33], v[32:33], v[32:33]
	s_waitcnt lgkmcnt(0)
;   DI void operator()(const f32x4 (&acc)[2][2][4][2], const pg8::Unit& u, int wr, int wc, int fr_, int fq_) const {
;     ...
;             } else {
;               if (n == 0) {
;                 const f32x4 v1 = acc[ai][bj][m][1];
;                 u32x4 o4;
;                 { const float t0 = fmaxf(v[0], 0.f) * rinv, t1 = fmaxf(v[1], 0.f) * rinv, t2 = fmaxf(v[2], 0.f) * rinv, t3 = fmaxf(v[3], 0.f) * rinv;
;                   o4.x = pack2(t0 * t0, t1 * t1); o4.y = pack2(t2 * t2, t3 * t3); }
;                 { const float t0 = fmaxf(v1[0], 0.f) * rinv, t1 = fmaxf(v1[1], 0.f) * rinv, t2 = fmaxf(v1[2], 0.f) * rinv, t3 = fmaxf(v1[3], 0.f) * rinv;
;                   o4.z = pack2(t0 * t0, t1 * t1); o4.w = pack2(t2 * t2, t3 * t3); }
;                 *(u32x4*)((u16*)big + (size_t)token * 4096 + u.pn * 256 + bj * 128 + wc * 32 + 8 * fq) = o4;
;               }
	v_pk_mul_f32 v[28:29], v[28:29], v[34:35] op_sel_hi:[1,0]
	v_pk_mul_f32 v[30:31], v[30:31], v[34:35] op_sel_hi:[1,0]
	v_pk_mul_f32 v[24:25], v[24:25], v[34:35] op_sel_hi:[1,0]
	v_cvt_pk_bf16_f32 v39, v32, v33
	v_add_u32_e32 v32, 0xa0, v140
	v_pk_mul_f32 v[28:29], v[28:29], v[28:29]
	v_pk_mul_f32 v[30:31], v[30:31], v[30:31]
	v_max_f32_e32 v26, 0, v26
	v_max_f32_e32 v27, 0, v27
	v_pk_mul_f32 v[24:25], v[24:25], v[24:25]
	v_max_f32_e32 v20, 0, v20
	v_max_f32_e32 v21, 0, v21
	v_max_f32_e32 v22, 0, v22
	v_max_f32_e32 v23, 0, v23
	v_max_f32_e32 v12, 0, v12
	v_max_f32_e32 v13, 0, v13
	v_ashrrev_i32_e32 v33, 31, v32
	v_cvt_pk_bf16_f32 v28, v28, v29
	v_cvt_pk_bf16_f32 v29, v30, v31
	v_cvt_pk_bf16_f32 v30, v24, v25
	v_pk_mul_f32 v[24:25], v[26:27], v[34:35] op_sel_hi:[1,0]
	v_pk_mul_f32 v[20:21], v[20:21], v[34:35] op_sel_hi:[1,0]
	v_pk_mul_f32 v[22:23], v[22:23], v[34:35] op_sel_hi:[1,0]
	v_pk_mul_f32 v[12:13], v[12:13], v[34:35] op_sel_hi:[1,0]
	v_lshlrev_b64 v[32:33], 13, v[32:33]
	v_pk_mul_f32 v[24:25], v[24:25], v[24:25]
	v_pk_mul_f32 v[20:21], v[20:21], v[20:21]
	v_pk_mul_f32 v[22:23], v[22:23], v[22:23]
	v_max_f32_e32 v14, 0, v14
	v_max_f32_e32 v15, 0, v15
	v_pk_mul_f32 v[12:13], v[12:13], v[12:13]
	v_cvt_pk_bf16_f32 v31, v24, v25
	v_lshl_add_u64 v[24:25], s[2:3], 0, v[32:33]
	v_cvt_pk_bf16_f32 v20, v20, v21
	v_cvt_pk_bf16_f32 v21, v22, v23
	v_cvt_pk_bf16_f32 v22, v12, v13
	v_pk_mul_f32 v[12:13], v[14:15], v[34:35] op_sel_hi:[1,0]
	v_lshl_add_u64 v[24:25], v[24:25], 0, s[14:15]
	v_pk_mul_f32 v[12:13], v[12:13], v[12:13]
	v_lshl_add_u64 v[24:25], v[24:25], 0, s[24:25]
	v_cvt_pk_bf16_f32 v23, v12, v13
	v_add_u32_e32 v12, 0xb0, v140
	v_lshl_add_u64 v[24:25], v[24:25], 0, v[144:145]
	v_ashrrev_i32_e32 v13, 31, v12
	v_max_f32_e32 v109, v113, v113
	v_max_f32_e32 v110, v114, v114
	v_max_f32_e32 v111, v115, v115
	v_max_f32_e32 v77, v81, v81
	v_max_f32_e32 v78, v82, v82
	v_max_f32_e32 v79, v83, v83
	v_max_f32_e32 v45, v49, v49
	v_max_f32_e32 v46, v50, v50
	v_max_f32_e32 v47, v51, v51
	global_store_dwordx4 v[24:25], v[20:23], off offset:256
	v_max_f32_e32 v14, v18, v18
	v_max_f32_e32 v15, v19, v19
	v_lshlrev_b64 v[20:21], 13, v[12:13]
	v_max_f32_e32 v12, v16, v16
	v_max_f32_e32 v13, v17, v17
	v_max_f32_e32 v108, 0, v108
	v_max_f32_e32 v109, 0, v109
	v_max_f32_e32 v110, 0, v110
	v_max_f32_e32 v111, 0, v111
	v_max_f32_e32 v104, 0, v104
	v_max_f32_e32 v105, 0, v105
	v_max_f32_e32 v76, 0, v76
	v_max_f32_e32 v77, 0, v77
	v_max_f32_e32 v78, 0, v78
	v_max_f32_e32 v79, 0, v79
	v_max_f32_e32 v72, 0, v72
	v_max_f32_e32 v73, 0, v73
	v_max_f32_e32 v44, 0, v44
	v_max_f32_e32 v45, 0, v45
	v_max_f32_e32 v46, 0, v46
	v_max_f32_e32 v47, 0, v47
	v_max_f32_e32 v40, 0, v40
	v_max_f32_e32 v41, 0, v41
	v_max_f32_e32 v12, 0, v12
	v_max_f32_e32 v13, 0, v13
	v_max_f32_e32 v14, 0, v14
	v_max_f32_e32 v15, 0, v15
	v_mov_b32_e32 v16, v35
	v_max_f32_e32 v8, 0, v8
	v_max_f32_e32 v9, 0, v9
	v_pk_mul_f32 v[108:109], v[108:109], v[112:113] op_sel_hi:[1,0]
	v_pk_mul_f32 v[110:111], v[110:111], v[112:113] op_sel_hi:[1,0]
	v_pk_mul_f32 v[104:105], v[104:105], v[112:113] op_sel_hi:[1,0]
	v_pk_mul_f32 v[76:77], v[76:77], v[80:81] op_sel_hi:[1,0]
	v_pk_mul_f32 v[78:79], v[78:79], v[80:81] op_sel_hi:[1,0]
	v_pk_mul_f32 v[72:73], v[72:73], v[80:81] op_sel_hi:[1,0]
	v_pk_mul_f32 v[44:45], v[44:45], v[48:49] op_sel_hi:[1,0]
	v_pk_mul_f32 v[46:47], v[46:47], v[48:49] op_sel_hi:[1,0]
	v_pk_mul_f32 v[40:41], v[40:41], v[48:49] op_sel_hi:[1,0]
	v_pk_mul_f32 v[12:13], v[12:13], v[16:17] op_sel_hi:[1,0]
	v_pk_mul_f32 v[14:15], v[14:15], v[16:17] op_sel_hi:[1,0]
	v_pk_mul_f32 v[8:9], v[8:9], v[16:17] op_sel_hi:[1,0]
	v_pk_mul_f32 v[108:109], v[108:109], v[108:109]
	v_pk_mul_f32 v[110:111], v[110:111], v[110:111]
	v_max_f32_e32 v106, 0, v106
	v_max_f32_e32 v107, 0, v107
	v_pk_mul_f32 v[104:105], v[104:105], v[104:105]
; #define PG8_WAIT_V(n) asm volatile("s_waitcnt vmcnt(" #n ")" ::: "memory")
; #define PG8_BAR __builtin_amdgcn_s_barrier()
; template <class Epi, class Sched>
; DI void gemm_phase(LAS unsigned char* lds, const Gemm g, const Sched& S, const Epi& E) {
;     ...
;     if (!has_next) break;
; #pragma unroll
;     for (int a = 0; a < 2; ++a)
; #pragma unroll
;       for (int b = 0; b < 2; ++b)
; #pragma unroll
;         for (int m = 0; m < 4; ++m)
; #pragma unroll
;           for (int n = 0; n < 2; ++n) acc[a][b][m][n] = (f32x4){0.f, 0.f, 0.f, 0.f};
;     cur = nxt; cA = nA; cB = nB; ++ui;
;   }
;   PG8_WAIT_V(0);
;   if (wr == 0) PG8_BAR;
;   PG8_BAR;
;   DI void operator()(const f32x4 (&acc)[2][2][4][2], const pg8::Unit& u, int wr, int wc, int fr_, int fq_) const {
;     ...
;             } else {
;               if (n == 0) {
;                 const f32x4 v1 = acc[ai][bj][m][1];
;                 u32x4 o4;
;                 { const float t0 = fmaxf(v[0], 0.f) * rinv, t1 = fmaxf(v[1], 0.f) * rinv, t2 = fmaxf(v[2], 0.f) * rinv, t3 = fmaxf(v[3], 0.f) * rinv;
;                   o4.x = pack2(t0 * t0, t1 * t1); o4.y = pack2(t2 * t2, t3 * t3); }
;                 { const float t0 = fmaxf(v1[0], 0.f) * rinv, t1 = fmaxf(v1[1], 0.f) * rinv, t2 = fmaxf(v1[2], 0.f) * rinv, t3 = fmaxf(v1[3], 0.f) * rinv;
;                   o4.z = pack2(t0 * t0, t1 * t1); o4.w = pack2(t2 * t2, t3 * t3); }
;                 *(u32x4*)((u16*)big + (size_t)token * 4096 + u.pn * 256 + bj * 128 + wc * 32 + 8 * fq) = o4;
;               }
	v_pk_mul_f32 v[76:77], v[76:77], v[76:77]
	v_pk_mul_f32 v[78:79], v[78:79], v[78:79]
	v_max_f32_e32 v74, 0, v74
	v_max_f32_e32 v75, 0, v75
	v_pk_mul_f32 v[72:73], v[72:73], v[72:73]
	v_pk_mul_f32 v[44:45], v[44:45], v[44:45]
	v_pk_mul_f32 v[46:47], v[46:47], v[46:47]
	v_max_f32_e32 v42, 0, v42
	v_max_f32_e32 v43, 0, v43
	v_pk_mul_f32 v[40:41], v[40:41], v[40:41]
	v_pk_mul_f32 v[12:13], v[12:13], v[12:13]
	v_pk_mul_f32 v[14:15], v[14:15], v[14:15]
	v_max_f32_e32 v10, 0, v10
	v_max_f32_e32 v11, 0, v11
	v_pk_mul_f32 v[8:9], v[8:9], v[8:9]
	v_cvt_pk_bf16_f32 v108, v108, v109
	v_cvt_pk_bf16_f32 v109, v110, v111
	v_cvt_pk_bf16_f32 v110, v104, v105
	v_pk_mul_f32 v[104:105], v[106:107], v[112:113] op_sel_hi:[1,0]
	v_cvt_pk_bf16_f32 v76, v76, v77
	v_cvt_pk_bf16_f32 v77, v78, v79
	v_cvt_pk_bf16_f32 v78, v72, v73
	v_pk_mul_f32 v[72:73], v[74:75], v[80:81] op_sel_hi:[1,0]
	v_cvt_pk_bf16_f32 v44, v44, v45
	v_cvt_pk_bf16_f32 v45, v46, v47
	v_cvt_pk_bf16_f32 v46, v40, v41
	v_pk_mul_f32 v[40:41], v[42:43], v[48:49] op_sel_hi:[1,0]
	v_cvt_pk_bf16_f32 v12, v12, v13
	v_cvt_pk_bf16_f32 v13, v14, v15
	v_cvt_pk_bf16_f32 v14, v8, v9
	v_pk_mul_f32 v[8:9], v[10:11], v[16:17] op_sel_hi:[1,0]
	v_max_f32_e32 v4, 0, v4
	v_max_f32_e32 v5, 0, v5
	v_max_f32_e32 v6, 0, v6
	v_max_f32_e32 v7, 0, v7
	v_max_f32_e32 v0, 0, v0
	v_max_f32_e32 v1, 0, v1
	v_pk_mul_f32 v[104:105], v[104:105], v[104:105]
	v_pk_mul_f32 v[72:73], v[72:73], v[72:73]
	v_pk_mul_f32 v[40:41], v[40:41], v[40:41]
	v_pk_mul_f32 v[8:9], v[8:9], v[8:9]
	v_pk_mul_f32 v[4:5], v[4:5], v[16:17] op_sel_hi:[1,0]
	v_pk_mul_f32 v[6:7], v[6:7], v[16:17] op_sel_hi:[1,0]
	v_pk_mul_f32 v[0:1], v[0:1], v[16:17] op_sel_hi:[1,0]
	v_cvt_pk_bf16_f32 v111, v104, v105
	v_lshl_add_u64 v[104:105], s[2:3], 0, v[116:117]
	v_cvt_pk_bf16_f32 v79, v72, v73
	v_lshl_add_u64 v[72:73], s[2:3], 0, v[84:85]
	v_cvt_pk_bf16_f32 v47, v40, v41
	v_lshl_add_u64 v[40:41], s[2:3], 0, v[52:53]
	v_cvt_pk_bf16_f32 v15, v8, v9
	v_lshl_add_u64 v[8:9], s[2:3], 0, v[20:21]
	v_pk_mul_f32 v[4:5], v[4:5], v[4:5]
	v_pk_mul_f32 v[6:7], v[6:7], v[6:7]
	v_max_f32_e32 v2, 0, v2
	v_max_f32_e32 v3, 0, v3
	v_pk_mul_f32 v[0:1], v[0:1], v[0:1]
	v_lshl_add_u64 v[104:105], v[104:105], 0, s[14:15]
	v_lshl_add_u64 v[72:73], v[72:73], 0, s[14:15]
	v_lshl_add_u64 v[40:41], v[40:41], 0, s[14:15]
	v_lshl_add_u64 v[8:9], v[8:9], 0, s[14:15]
	v_cvt_pk_bf16_f32 v4, v4, v5
	v_cvt_pk_bf16_f32 v5, v6, v7
	v_cvt_pk_bf16_f32 v6, v0, v1
	v_pk_mul_f32 v[0:1], v[2:3], v[16:17] op_sel_hi:[1,0]
	v_lshl_add_u64 v[104:105], v[104:105], 0, s[24:25]
	v_lshl_add_u64 v[72:73], v[72:73], 0, s[24:25]
	v_lshl_add_u64 v[40:41], v[40:41], 0, s[24:25]
	v_lshl_add_u64 v[8:9], v[8:9], 0, s[24:25]
	v_pk_mul_f32 v[0:1], v[0:1], v[0:1]
	v_lshl_add_u64 v[104:105], v[104:105], 0, v[144:145]
	v_lshl_add_u64 v[72:73], v[72:73], 0, v[144:145]
	v_lshl_add_u64 v[40:41], v[40:41], 0, v[144:145]
	v_lshl_add_u64 v[8:9], v[8:9], 0, v[144:145]
	v_cvt_pk_bf16_f32 v7, v0, v1
	s_and_b64 vcc, exec, s[36:37]
	s_mov_b32 s43, s42
	s_mov_b32 s45, s4
	s_mov_b32 s44, s6
	s_mov_b64 s[16:17], s[12:13]
	s_mov_b64 s[14:15], s[10:11]
	v_readlane_b32 s51, v237, 11
	global_store_dwordx4 v[120:121], v[124:127], off
	global_store_dwordx4 v[104:105], v[108:111], off
	global_store_dwordx4 v[104:105], v[100:103], off offset:256
	global_store_dwordx4 v[88:89], v[92:95], off
	global_store_dwordx4 v[72:73], v[76:79], off
	global_store_dwordx4 v[72:73], v[68:71], off offset:256
	global_store_dwordx4 v[56:57], v[60:63], off
	global_store_dwordx4 v[40:41], v[44:47], off
	global_store_dwordx4 v[40:41], v[36:39], off offset:256
	global_store_dwordx4 v[24:25], v[28:31], off
	global_store_dwordx4 v[8:9], v[12:15], off
	global_store_dwordx4 v[8:9], v[4:7], off offset:256
	s_cbranch_vccz .LBB0_1822
	s_waitcnt vmcnt(0)
	s_cmpk_gt_u32 s9, 0xff
	s_cbranch_scc1 .LBB0_1833
	s_barrier

; #define PG8_STAGE(bufoff, gbase, voff) do { _Pragma("unroll") for (int _i = 0; _i < 2; ++_i) \
;     __builtin_amdgcn_global_load_lds((const unsigned*)((const char*)(gbase) + (voff)[_i]), (LAS unsigned*)(lds + (bufoff) + ldsw + _i * 8192), 16, 0, 0); } while (0)
; #define PG8_LDA(dst, b, h) do { _Pragma("unroll") for (int m = 0; m < 4; ++m) _Pragma("unroll") for (int k = 0; k < 2; ++k) dst[m][k] = *(const LAS bf16x8*)(lds + PG8_SA(b, h) + aoff + m * 2048 + k * 1024); } while (0)
; #define PG8_LDB(dst, b, h) do { _Pragma("unroll") for (int n = 0; n < 2; ++n) _Pragma("unroll") for (int k = 0; k < 2; ++k) dst[n][k] = *(const LAS bf16x8*)(lds + PG8_SB(b, h) + boff + n * 2048 + k * 1024); } while (0)
; #define PG8_MMA(ai, bj, At, Bt) do { __builtin_amdgcn_s_setprio(1); _Pragma("unroll") for (int m = 0; m < 4; ++m) _Pragma("unroll") for (int n = 0; n < 2; ++n) _Pragma("unroll") for (int k = 0; k < 2; ++k) \
;     acc[ai][bj][m][n] = __builtin_amdgcn_mfma_f32_16x16x32_bf16(Bt[n][k], At[m][k], acc[ai][bj][m][n], 0, 0, 0); __builtin_amdgcn_s_setprio(0); } while (0)
; #define PG8_WAIT_V(n) asm volatile("s_waitcnt vmcnt(" #n ")" ::: "memory")
; template <class Epi, class Sched>
; DI void gemm_phase(LAS unsigned char* lds, const Gemm g, const Sched& S, const Epi& E) {
;     ...
;     for (int t = 0; t < nt; t += 2) {
;       const bool last = (t == nt - 2);
;       const char* a1 = cA + (size_t)(t + 1) * kstep;
;       const char* a2 = last ? nA : cA + (size_t)(t + 2) * kstep; const char* b2 = last ? nB : cB + (size_t)(t + 2) * kstep;
;       const char* a3 = a2 + kstep; const char* b3 = b2 + kstep;
;       PG8_LDB(B0, 0, 0); PG8_SCHED; PG8_LDA(At, 0, 0); PG8_STAGE(PG8_SA(1, 1), a1 + hstep, voffA);
;       PG8_WAIT_L(8); PG8_BAR; PG8_WAIT_L(0); PG8_MMA(0, 0, At, B0); PG8_BAR; PG8_SCHED;
;       PG8_LDB(B1, 0, 1); PG8_STAGE(PG8_SB(0, 0), b2, voffB);
;       PG8_BAR; PG8_WAIT_L(0); PG8_MMA(0, 1, At, B1); PG8_BAR;
;       PG8_LDA(At, 0, 1); PG8_STAGE(PG8_SA(0, 0), a2, voffA);
;       PG8_BAR; PG8_WAIT_L(0); PG8_MMA(1, 0, At, B0); PG8_BAR; PG8_SCHED;
;       PG8_STAGE(PG8_SB(0, 1), b2 + hstep, voffB);
;       PG8_WAIT_V(6); PG8_BAR; PG8_MMA(1, 1, At, B1); PG8_BAR;
;       PG8_LDB(B0, 1, 0); PG8_SCHED; PG8_LDA(At, 1, 0); PG8_STAGE(PG8_SA(0, 1), a2 + hstep, voffA);
;       PG8_WAIT_L(8); PG8_BAR; PG8_WAIT_L(0); PG8_MMA(0, 0, At, B0); PG8_BAR; PG8_SCHED;
.LBB0_1905:
	s_add_u32 s22, s20, 0xfff00080
	s_addc_u32 s23, s21, -1
	ds_read_b128 v[138:141], v224
	ds_read_b128 v[148:151], v224 offset:1024
	ds_read_b128 v[152:155], v224 offset:2048
	ds_read_b128 v[156:159], v224 offset:3072
	s_cmp_eq_u32 s50, 60
	s_cselect_b32 s29, s11, s23
	s_cselect_b32 s28, s17, s22
	s_cselect_b32 s23, s7, s49
	s_cselect_b32 s22, s19, s24
	s_add_i32 m0, s39, 0xc000
	ds_read_b128 v[160:163], v147
	ds_read_b128 v[164:167], v147 offset:1024
	ds_read_b128 v[168:171], v147 offset:2048
	ds_read_b128 v[172:175], v147 offset:3072
	ds_read_b128 v[176:179], v147 offset:4096
	ds_read_b128 v[196:199], v147 offset:5120
	ds_read_b128 v[200:203], v147 offset:6144
	global_load_lds_dwordx4 v134, s[20:21]
	s_add_i32 m0, s39, 0xe000
	ds_read_b128 v[204:207], v147 offset:7168
	global_load_lds_dwordx4 v136, s[20:21]
	s_waitcnt lgkmcnt(8)
	s_barrier
	s_waitcnt lgkmcnt(0)
	v_mfma_f32_16x16x32_bf16 v[124:127], v[138:141], v[160:163], v[124:127]
	v_mfma_f32_16x16x32_bf16 v[120:123], v[152:155], v[160:163], v[120:123]
	v_mfma_f32_16x16x32_bf16 v[108:111], v[138:141], v[168:171], v[108:111]
	v_mfma_f32_16x16x32_bf16 v[104:107], v[152:155], v[168:171], v[104:107]
	v_mfma_f32_16x16x32_bf16 v[92:95], v[138:141], v[176:179], v[92:95]
	v_mfma_f32_16x16x32_bf16 v[88:91], v[152:155], v[176:179], v[88:91]
	v_mfma_f32_16x16x32_bf16 v[76:79], v[138:141], v[200:203], v[76:79]
	v_mfma_f32_16x16x32_bf16 v[72:75], v[152:155], v[200:203], v[72:75]
	v_mfma_f32_16x16x32_bf16 v[124:127], v[148:151], v[164:167], v[124:127]
	v_mfma_f32_16x16x32_bf16 v[120:123], v[156:159], v[164:167], v[120:123]
	v_mfma_f32_16x16x32_bf16 v[108:111], v[148:151], v[172:175], v[108:111]
	v_mfma_f32_16x16x32_bf16 v[104:107], v[156:159], v[172:175], v[104:107]
	v_mfma_f32_16x16x32_bf16 v[92:95], v[148:151], v[196:199], v[92:95]
	v_mfma_f32_16x16x32_bf16 v[88:91], v[156:159], v[196:199], v[88:91]
	v_mfma_f32_16x16x32_bf16 v[76:79], v[148:151], v[204:207], v[76:79]
	v_mfma_f32_16x16x32_bf16 v[72:75], v[156:159], v[204:207], v[72:75]
	s_barrier
	s_add_i32 s51, s38, 0x10000
	ds_read_b128 v[208:211], v225
	ds_read_b128 v[212:215], v225 offset:1024
	s_add_u32 vcc_lo, s22, s0
	s_addc_u32 vcc_hi, s23, s1
	s_mov_b32 m0, s51
	ds_read_b128 v[220:223], v225 offset:3072
	global_load_lds_dwordx4 v144, s[22:23]
	s_add_i32 m0, s51, 0x2000
	ds_read_b128 v[216:219], v225 offset:2048
	global_load_lds_dwordx4 v132, s[22:23]
	s_barrier
	s_waitcnt lgkmcnt(0)
	v_mfma_f32_16x16x32_bf16 v[116:119], v[208:211], v[160:163], v[116:119]
	v_mfma_f32_16x16x32_bf16 v[112:115], v[216:219], v[160:163], v[112:115]
	v_mfma_f32_16x16x32_bf16 v[100:103], v[208:211], v[168:171], v[100:103]
	v_mfma_f32_16x16x32_bf16 v[96:99], v[216:219], v[168:171], v[96:99]
	v_mfma_f32_16x16x32_bf16 v[84:87], v[208:211], v[176:179], v[84:87]
	v_mfma_f32_16x16x32_bf16 v[80:83], v[216:219], v[176:179], v[80:83]
	v_mfma_f32_16x16x32_bf16 v[68:71], v[208:211], v[200:203], v[68:71]
	v_mfma_f32_16x16x32_bf16 v[64:67], v[216:219], v[200:203], v[64:67]
	v_mfma_f32_16x16x32_bf16 v[116:119], v[212:215], v[164:167], v[116:119]
	v_mfma_f32_16x16x32_bf16 v[112:115], v[220:223], v[164:167], v[112:115]
	v_mfma_f32_16x16x32_bf16 v[100:103], v[212:215], v[172:175], v[100:103]
	v_mfma_f32_16x16x32_bf16 v[96:99], v[220:223], v[172:175], v[96:99]
	v_mfma_f32_16x16x32_bf16 v[84:87], v[212:215], v[196:199], v[84:87]
	v_mfma_f32_16x16x32_bf16 v[80:83], v[220:223], v[196:199], v[80:83]
	v_mfma_f32_16x16x32_bf16 v[68:71], v[212:215], v[204:207], v[68:71]
	v_mfma_f32_16x16x32_bf16 v[64:67], v[220:223], v[204:207], v[64:67]
	s_mov_b32 m0, s39
	s_add_u32 s100, s28, s0
	s_addc_u32 s101, s29, s1
	s_barrier
	ds_read_b128 v[160:163], v147 offset:16384
	ds_read_b128 v[164:167], v147 offset:17408
	ds_read_b128 v[168:171], v147 offset:18432
	ds_read_b128 v[172:175], v147 offset:19456
	ds_read_b128 v[176:179], v147 offset:20480
	ds_read_b128 v[196:199], v147 offset:21504
	ds_read_b128 v[200:203], v147 offset:22528
	global_load_lds_dwordx4 v128, s[28:29]
	s_mov_b32 m0, s40
	ds_read_b128 v[204:207], v147 offset:23552
	global_load_lds_dwordx4 v130, s[28:29]
	s_barrier
	s_waitcnt lgkmcnt(0)
	v_mfma_f32_16x16x32_bf16 v[60:63], v[138:141], v[160:163], v[60:63]
	v_mfma_f32_16x16x32_bf16 v[56:59], v[152:155], v[160:163], v[56:59]
	v_mfma_f32_16x16x32_bf16 v[44:47], v[138:141], v[168:171], v[44:47]
	v_mfma_f32_16x16x32_bf16 v[40:43], v[152:155], v[168:171], v[40:43]
	v_mfma_f32_16x16x32_bf16 v[28:31], v[138:141], v[176:179], v[28:31]
	v_mfma_f32_16x16x32_bf16 v[24:27], v[152:155], v[176:179], v[24:27]
	v_mfma_f32_16x16x32_bf16 v[12:15], v[138:141], v[200:203], v[12:15]
	v_mfma_f32_16x16x32_bf16 v[8:11], v[152:155], v[200:203], v[8:11]
	v_mfma_f32_16x16x32_bf16 v[60:63], v[148:151], v[164:167], v[60:63]
	v_mfma_f32_16x16x32_bf16 v[56:59], v[156:159], v[164:167], v[56:59]
	v_mfma_f32_16x16x32_bf16 v[44:47], v[148:151], v[172:175], v[44:47]
	v_mfma_f32_16x16x32_bf16 v[40:43], v[156:159], v[172:175], v[40:43]
	v_mfma_f32_16x16x32_bf16 v[28:31], v[148:151], v[196:199], v[28:31]
	v_mfma_f32_16x16x32_bf16 v[24:27], v[156:159], v[196:199], v[24:27]
	v_mfma_f32_16x16x32_bf16 v[12:15], v[148:151], v[204:207], v[12:15]
	v_mfma_f32_16x16x32_bf16 v[8:11], v[156:159], v[204:207], v[8:11]
	s_barrier
	s_add_u32 s52, s22, 0x100000
	s_addc_u32 s53, s23, 0
	s_add_i32 s51, s38, 0x14000
	s_mov_b32 m0, s51
	s_nop 0
	global_load_lds_dwordx4 v144, s[52:53]
	s_add_i32 m0, s51, 0x2000
	s_nop 0
	global_load_lds_dwordx4 v132, s[52:53]
	s_waitcnt vmcnt(6)
	s_barrier
; #define PG8_STAGE(bufoff, gbase, voff) do { _Pragma("unroll") for (int _i = 0; _i < 2; ++_i) \
;     __builtin_amdgcn_global_load_lds((const unsigned*)((const char*)(gbase) + (voff)[_i]), (LAS unsigned*)(lds + (bufoff) + ldsw + _i * 8192), 16, 0, 0); } while (0)
; #define PG8_LDA(dst, b, h) do { _Pragma("unroll") for (int m = 0; m < 4; ++m) _Pragma("unroll") for (int k = 0; k < 2; ++k) dst[m][k] = *(const LAS bf16x8*)(lds + PG8_SA(b, h) + aoff + m * 2048 + k * 1024); } while (0)
; #define PG8_LDB(dst, b, h) do { _Pragma("unroll") for (int n = 0; n < 2; ++n) _Pragma("unroll") for (int k = 0; k < 2; ++k) dst[n][k] = *(const LAS bf16x8*)(lds + PG8_SB(b, h) + boff + n * 2048 + k * 1024); } while (0)
; #define PG8_MMA(ai, bj, At, Bt) do { __builtin_amdgcn_s_setprio(1); _Pragma("unroll") for (int m = 0; m < 4; ++m) _Pragma("unroll") for (int n = 0; n < 2; ++n) _Pragma("unroll") for (int k = 0; k < 2; ++k) \
;     acc[ai][bj][m][n] = __builtin_amdgcn_mfma_f32_16x16x32_bf16(Bt[n][k], At[m][k], acc[ai][bj][m][n], 0, 0, 0); __builtin_amdgcn_s_setprio(0); } while (0)
; #define PG8_WAIT_V(n) asm volatile("s_waitcnt vmcnt(" #n ")" ::: "memory")
; #define PG8_WAIT_L(n) asm volatile("s_waitcnt lgkmcnt(" #n ")" ::: "memory")
; #define PG8_BAR __builtin_amdgcn_s_barrier()
; #define PG8_SCHED __builtin_amdgcn_sched_barrier(0)
; template <class Epi, class Sched>
; DI void gemm_phase(LAS unsigned char* lds, const Gemm g, const Sched& S, const Epi& E) {
;     ...
;       PG8_BAR; PG8_WAIT_L(0); PG8_MMA(1, 0, At, B0); PG8_BAR; PG8_SCHED;
;       PG8_STAGE(PG8_SB(0, 1), b2 + hstep, voffB);
;       PG8_WAIT_V(6); PG8_BAR; PG8_MMA(1, 1, At, B1); PG8_BAR;
;       PG8_LDB(B0, 1, 0); PG8_SCHED; PG8_LDA(At, 1, 0); PG8_STAGE(PG8_SA(0, 1), a2 + hstep, voffA);
;       PG8_WAIT_L(8); PG8_BAR; PG8_WAIT_L(0); PG8_MMA(0, 0, At, B0); PG8_BAR; PG8_SCHED;
;       PG8_LDB(B1, 1, 1); PG8_STAGE(PG8_SB(1, 0), b3, voffB);
;       PG8_BAR; PG8_WAIT_L(0); PG8_MMA(0, 1, At, B1); PG8_BAR;
;       PG8_LDA(At, 1, 1); PG8_STAGE(PG8_SA(1, 0), a3, voffA);
;       PG8_BAR; PG8_WAIT_L(0); PG8_MMA(1, 0, At, B0); PG8_BAR; PG8_SCHED;
	v_mfma_f32_16x16x32_bf16 v[52:55], v[208:211], v[160:163], v[52:55]
	v_mfma_f32_16x16x32_bf16 v[48:51], v[216:219], v[160:163], v[48:51]
	v_mfma_f32_16x16x32_bf16 v[36:39], v[208:211], v[168:171], v[36:39]
	v_mfma_f32_16x16x32_bf16 v[32:35], v[216:219], v[168:171], v[32:35]
	v_mfma_f32_16x16x32_bf16 v[20:23], v[208:211], v[176:179], v[20:23]
	v_mfma_f32_16x16x32_bf16 v[16:19], v[216:219], v[176:179], v[16:19]
	v_mfma_f32_16x16x32_bf16 v[4:7], v[208:211], v[200:203], v[4:7]
	v_mfma_f32_16x16x32_bf16 v[0:3], v[216:219], v[200:203], v[0:3]
	v_mfma_f32_16x16x32_bf16 v[52:55], v[212:215], v[164:167], v[52:55]
	v_mfma_f32_16x16x32_bf16 v[48:51], v[220:223], v[164:167], v[48:51]
	v_mfma_f32_16x16x32_bf16 v[36:39], v[212:215], v[172:175], v[36:39]
	v_mfma_f32_16x16x32_bf16 v[32:35], v[220:223], v[172:175], v[32:35]
	v_mfma_f32_16x16x32_bf16 v[20:23], v[212:215], v[196:199], v[20:23]
	v_mfma_f32_16x16x32_bf16 v[16:19], v[220:223], v[196:199], v[16:19]
	v_mfma_f32_16x16x32_bf16 v[4:7], v[212:215], v[204:207], v[4:7]
	v_mfma_f32_16x16x32_bf16 v[0:3], v[220:223], v[204:207], v[0:3]
	s_barrier
	ds_read_b128 v[138:141], v226
	ds_read_b128 v[148:151], v226 offset:1024
	ds_read_b128 v[152:155], v226 offset:2048
	ds_read_b128 v[156:159], v226 offset:3072
	s_add_u32 s28, s28, 0x100000
	s_addc_u32 s29, s29, 0
	s_mov_b32 m0, s41
	ds_read_b128 v[160:163], v147 offset:32768
	ds_read_b128 v[164:167], v147 offset:33792
	ds_read_b128 v[168:171], v147 offset:34816
	ds_read_b128 v[172:175], v147 offset:35840
	ds_read_b128 v[176:179], v147 offset:36864
	ds_read_b128 v[196:199], v147 offset:37888
	ds_read_b128 v[200:203], v147 offset:38912
	global_load_lds_dwordx4 v128, s[28:29]
	s_mov_b32 m0, s42
	ds_read_b128 v[204:207], v147 offset:39936
	global_load_lds_dwordx4 v130, s[28:29]
	s_waitcnt lgkmcnt(8)
	s_barrier
	s_waitcnt lgkmcnt(0)
	v_mfma_f32_16x16x32_bf16 v[124:127], v[138:141], v[160:163], v[124:127]
	v_mfma_f32_16x16x32_bf16 v[120:123], v[152:155], v[160:163], v[120:123]
	v_mfma_f32_16x16x32_bf16 v[108:111], v[138:141], v[168:171], v[108:111]
	v_mfma_f32_16x16x32_bf16 v[104:107], v[152:155], v[168:171], v[104:107]
	v_mfma_f32_16x16x32_bf16 v[92:95], v[138:141], v[176:179], v[92:95]
	v_mfma_f32_16x16x32_bf16 v[88:91], v[152:155], v[176:179], v[88:91]
	v_mfma_f32_16x16x32_bf16 v[76:79], v[138:141], v[200:203], v[76:79]
	v_mfma_f32_16x16x32_bf16 v[72:75], v[152:155], v[200:203], v[72:75]
	v_mfma_f32_16x16x32_bf16 v[124:127], v[148:151], v[164:167], v[124:127]
	v_mfma_f32_16x16x32_bf16 v[120:123], v[156:159], v[164:167], v[120:123]
	v_mfma_f32_16x16x32_bf16 v[108:111], v[148:151], v[172:175], v[108:111]
	v_mfma_f32_16x16x32_bf16 v[104:107], v[156:159], v[172:175], v[104:107]
	v_mfma_f32_16x16x32_bf16 v[92:95], v[148:151], v[196:199], v[92:95]
	v_mfma_f32_16x16x32_bf16 v[88:91], v[156:159], v[196:199], v[88:91]
	v_mfma_f32_16x16x32_bf16 v[76:79], v[148:151], v[204:207], v[76:79]
	v_mfma_f32_16x16x32_bf16 v[72:75], v[156:159], v[204:207], v[72:75]
	s_barrier
	s_add_i32 s29, s38, 0x18000
	s_mov_b32 m0, s29
	ds_read_b128 v[208:211], v227
	ds_read_b128 v[212:215], v227 offset:1024
	ds_read_b128 v[216:219], v227 offset:2048
	global_load_lds_dwordx4 v144, vcc
	s_add_i32 m0, s29, 0x2000
	ds_read_b128 v[220:223], v227 offset:3072
	global_load_lds_dwordx4 v132, vcc
	s_barrier
	s_waitcnt lgkmcnt(0)
	v_mfma_f32_16x16x32_bf16 v[116:119], v[208:211], v[160:163], v[116:119]
	v_mfma_f32_16x16x32_bf16 v[112:115], v[216:219], v[160:163], v[112:115]
	v_mfma_f32_16x16x32_bf16 v[100:103], v[208:211], v[168:171], v[100:103]
	v_mfma_f32_16x16x32_bf16 v[96:99], v[216:219], v[168:171], v[96:99]
	v_mfma_f32_16x16x32_bf16 v[84:87], v[208:211], v[176:179], v[84:87]
	v_mfma_f32_16x16x32_bf16 v[80:83], v[216:219], v[176:179], v[80:83]
	v_mfma_f32_16x16x32_bf16 v[68:71], v[208:211], v[200:203], v[68:71]
	v_mfma_f32_16x16x32_bf16 v[64:67], v[216:219], v[200:203], v[64:67]
	v_mfma_f32_16x16x32_bf16 v[116:119], v[212:215], v[164:167], v[116:119]
	v_mfma_f32_16x16x32_bf16 v[112:115], v[220:223], v[164:167], v[112:115]
	v_mfma_f32_16x16x32_bf16 v[100:103], v[212:215], v[172:175], v[100:103]
	v_mfma_f32_16x16x32_bf16 v[96:99], v[220:223], v[172:175], v[96:99]
	v_mfma_f32_16x16x32_bf16 v[84:87], v[212:215], v[196:199], v[84:87]
	v_mfma_f32_16x16x32_bf16 v[80:83], v[220:223], v[196:199], v[80:83]
	v_mfma_f32_16x16x32_bf16 v[68:71], v[212:215], v[204:207], v[68:71]
	v_mfma_f32_16x16x32_bf16 v[64:67], v[220:223], v[204:207], v[64:67]
	s_mov_b32 m0, s46
	s_barrier
	ds_read_b128 v[160:163], v147 offset:49152
	ds_read_b128 v[164:167], v147 offset:50176
	ds_read_b128 v[168:171], v147 offset:51200
	ds_read_b128 v[172:175], v147 offset:52224
	ds_read_b128 v[176:179], v147 offset:53248
	ds_read_b128 v[196:199], v147 offset:54272
	ds_read_b128 v[200:203], v147 offset:55296
	global_load_lds_dwordx4 v128, s[100:101]
	s_mov_b32 m0, s47
	ds_read_b128 v[204:207], v147 offset:56320
	global_load_lds_dwordx4 v130, s[100:101]
	s_barrier
; template <class Epi, class Sched>
; DI void gemm_phase(LAS unsigned char* lds, const Gemm g, const Sched& S, const Epi& E) {
;     ...
;       PG8_LDA(At, 1, 1); PG8_STAGE(PG8_SA(1, 0), a3, voffA);
;       PG8_BAR; PG8_WAIT_L(0); PG8_MMA(1, 0, At, B0); PG8_BAR; PG8_SCHED;
;       PG8_STAGE(PG8_SB(1, 1), b3 + hstep, voffB);
;       PG8_WAIT_V(6); PG8_BAR; PG8_MMA(1, 1, At, B1); PG8_BAR;
;     }
;     E(acc, cur, wr, wc, fr, fq);
;   DI void operator()(const f32x4 (&acc)[2][2][4][2], const pg8::Unit& u, int wr, int wc, int fr_, int fq_) const {
;     ...
;               if (n == 0) {
;                 const int f8 = u.pn * 256 + bj * 128 + wc * 32 + 8 * fq;
;                 const f32x4 v1 = acc[ai][bj][m][1];
;                 f32x4 r0, r1;
;                 if (rsrc) {
;                   r0 = *(const f32x4*)(rsrc + (size_t)token * 1024 + f8); r1 = *(const f32x4*)(rsrc + (size_t)token * 1024 + f8 + 4);
;                 } else {
;                   const u32x4 xu = *(const u32x4*)(xr + (size_t)token * 1024 + f8);
;                   r0 = (f32x4){bf2f(xu.x & 0xffffu), bf2f(xu.x >> 16), bf2f(xu.y & 0xffffu), bf2f(xu.y >> 16)};
;                   r1 = (f32x4){bf2f(xu.z & 0xffffu), bf2f(xu.z >> 16), bf2f(xu.w & 0xffffu), bf2f(xu.w >> 16)};
;                 }
;                 r0 += v; r1 += v1;
;                 st_bf8(xr + (size_t)token * 1024 + f8, r0, r1, 1.f);
;                 ssq += r0[0] * r0[0] + r0[1] * r0[1] + r0[2] * r0[2] + r0[3] * r0[3] + r1[0] * r1[0] + r1[1] * r1[1] + r1[2] * r1[2] + r1[3] * r1[3];
;               }
;             } else {
;               if (n == 0) {
;                 const f32x4 v1 = acc[ai][bj][m][1];
;                 u32x4 o4;
;                 { const float t0 = fmaxf(v[0], 0.f) * rinv, t1 = fmaxf(v[1], 0.f) * rinv, t2 = fmaxf(v[2], 0.f) * rinv, t3 = fmaxf(v[3], 0.f) * rinv;
;                   o4.x = pack2(t0 * t0, t1 * t1); o4.y = pack2(t2 * t2, t3 * t3); }
;                 { const float t0 = fmaxf(v1[0], 0.f) * rinv, t1 = fmaxf(v1[1], 0.f) * rinv, t2 = fmaxf(v1[2], 0.f) * rinv, t3 = fmaxf(v1[3], 0.f) * rinv;
;                   o4.z = pack2(t0 * t0, t1 * t1); o4.w = pack2(t2 * t2, t3 * t3); }
;                 *(u32x4*)((u16*)big + (size_t)token * 4096 + u.pn * 256 + bj * 128 + wc * 32 + 8 * fq) = o4;
;               }
;             }
;           }
;         if (EPI == EPI_RESID) {
;           ssq += shx(ssq, 16, t_ & 63);
	s_waitcnt lgkmcnt(0)
	v_mfma_f32_16x16x32_bf16 v[60:63], v[138:141], v[160:163], v[60:63]
	v_mfma_f32_16x16x32_bf16 v[56:59], v[152:155], v[160:163], v[56:59]
	v_mfma_f32_16x16x32_bf16 v[44:47], v[138:141], v[168:171], v[44:47]
	v_mfma_f32_16x16x32_bf16 v[40:43], v[152:155], v[168:171], v[40:43]
	v_mfma_f32_16x16x32_bf16 v[28:31], v[138:141], v[176:179], v[28:31]
	v_mfma_f32_16x16x32_bf16 v[24:27], v[152:155], v[176:179], v[24:27]
	v_mfma_f32_16x16x32_bf16 v[12:15], v[138:141], v[200:203], v[12:15]
	v_mfma_f32_16x16x32_bf16 v[8:11], v[152:155], v[200:203], v[8:11]
	v_mfma_f32_16x16x32_bf16 v[60:63], v[148:151], v[164:167], v[60:63]
	v_mfma_f32_16x16x32_bf16 v[56:59], v[156:159], v[164:167], v[56:59]
	v_mfma_f32_16x16x32_bf16 v[44:47], v[148:151], v[172:175], v[44:47]
	v_mfma_f32_16x16x32_bf16 v[40:43], v[156:159], v[172:175], v[40:43]
	v_mfma_f32_16x16x32_bf16 v[28:31], v[148:151], v[196:199], v[28:31]
	v_mfma_f32_16x16x32_bf16 v[24:27], v[156:159], v[196:199], v[24:27]
	v_mfma_f32_16x16x32_bf16 v[12:15], v[148:151], v[204:207], v[12:15]
	v_mfma_f32_16x16x32_bf16 v[8:11], v[156:159], v[204:207], v[8:11]
	s_barrier
	s_add_u32 s22, s22, 0x100080
	s_addc_u32 s23, s23, 0
	s_add_i32 s28, s38, 0x1c000
	s_mov_b32 m0, s28
	s_nop 0
	global_load_lds_dwordx4 v144, s[22:23]
	s_add_i32 m0, s28, 0x2000
	s_nop 0
	global_load_lds_dwordx4 v132, s[22:23]
	s_waitcnt vmcnt(6)
	s_barrier
	v_mfma_f32_16x16x32_bf16 v[52:55], v[208:211], v[160:163], v[52:55]
	v_mfma_f32_16x16x32_bf16 v[48:51], v[216:219], v[160:163], v[48:51]
	v_mfma_f32_16x16x32_bf16 v[36:39], v[208:211], v[168:171], v[36:39]
	v_mfma_f32_16x16x32_bf16 v[32:35], v[216:219], v[168:171], v[32:35]
	v_mfma_f32_16x16x32_bf16 v[20:23], v[208:211], v[176:179], v[20:23]
	v_mfma_f32_16x16x32_bf16 v[16:19], v[216:219], v[176:179], v[16:19]
	v_mfma_f32_16x16x32_bf16 v[4:7], v[208:211], v[200:203], v[4:7]
	v_mfma_f32_16x16x32_bf16 v[0:3], v[216:219], v[200:203], v[0:3]
	v_mfma_f32_16x16x32_bf16 v[52:55], v[212:215], v[164:167], v[52:55]
	v_mfma_f32_16x16x32_bf16 v[48:51], v[220:223], v[164:167], v[48:51]
	v_mfma_f32_16x16x32_bf16 v[36:39], v[212:215], v[172:175], v[36:39]
	v_mfma_f32_16x16x32_bf16 v[32:35], v[220:223], v[172:175], v[32:35]
	v_mfma_f32_16x16x32_bf16 v[20:23], v[212:215], v[196:199], v[20:23]
	v_mfma_f32_16x16x32_bf16 v[16:19], v[220:223], v[196:199], v[16:19]
	v_mfma_f32_16x16x32_bf16 v[4:7], v[212:215], v[204:207], v[4:7]
	v_mfma_f32_16x16x32_bf16 v[0:3], v[220:223], v[204:207], v[0:3]
	s_add_i32 s50, s50, 2
	s_add_u32 s20, s20, 0x100
	s_addc_u32 s21, s21, 0
	s_add_u32 s24, s24, 0x100
	s_addc_u32 s49, s49, 0
	s_cmp_gt_u32 s50, 61
	s_barrier
	s_cbranch_scc0 .LBB0_1905
	s_lshl_b32 s7, s18, 8
	v_mov_b32_e32 v139, v182
	s_add_i32 s7, s7, s44
	s_nop 0
	v_and_or_b32 v140, v139, 15, s7
	s_lshl_b32 s7, s16, 8
	v_bfe_u32 v141, v139, 4, 2
	s_or_b32 s7, s7, s45
	v_lshl_or_b32 v138, v141, 3, s7
	v_cmp_eq_u32_e32 vcc, 0, v141
	v_ashrrev_i32_e32 v141, 31, v140
	v_lshlrev_b32_e32 v139, 2, v139
	s_movk_i32 s7, 0x80
	v_lshlrev_b64 v[142:143], 11, v[140:141]
	v_bitop3_b32 v149, v139, 64, v190 bitop3:0x6c
	v_bitop3_b32 v148, v139, s7, v190 bitop3:0x6c
	v_ashrrev_i32_e32 v139, 31, v138
	v_lshl_add_u64 v[142:143], s[4:5], 0, v[142:143]
	v_lshl_add_u64 v[142:143], v[138:139], 1, v[142:143]
	global_load_dwordx4 v[150:153], v[142:143], off
	s_lshl_b32 s16, s16, 2
	s_ashr_i32 s17, s16, 31
	s_waitcnt vmcnt(0)
	v_lshlrev_b32_e32 v154, 16, v150
	v_and_b32_e32 v155, 0xffff0000, v150
	v_lshlrev_b32_e32 v150, 16, v151
	v_and_b32_e32 v151, 0xffff0000, v151
	v_lshlrev_b32_e32 v156, 16, v152
	v_and_b32_e32 v157, 0xffff0000, v152
	v_lshlrev_b32_e32 v152, 16, v153
	v_and_b32_e32 v153, 0xffff0000, v153
	v_pk_add_f32 v[126:127], v[126:127], v[150:151]
	v_pk_add_f32 v[124:125], v[124:125], v[154:155]
	v_pk_add_f32 v[150:151], v[122:123], v[152:153]
	v_pk_add_f32 v[152:153], v[120:121], v[156:157]
	v_cvt_pk_bf16_f32 v120, v124, v125
	v_cvt_pk_bf16_f32 v121, v126, v127
	v_cvt_pk_bf16_f32 v122, v152, v153
	v_cvt_pk_bf16_f32 v123, v150, v151
	global_store_dwordx4 v[142:143], v[120:123], off
	global_load_dwordx4 v[120:123], v[142:143], off offset:256
	v_mul_f32_e32 v154, v125, v125
	v_fmac_f32_e32 v154, v124, v124
	v_fmac_f32_e32 v154, v126, v126
	v_fmac_f32_e32 v154, v127, v127
	v_fmac_f32_e32 v154, v152, v152
	v_fmac_f32_e32 v154, v153, v153
	v_fmac_f32_e32 v154, v150, v150
	v_fmac_f32_e32 v154, v151, v151
	s_waitcnt vmcnt(0)
	v_lshlrev_b32_e32 v124, 16, v120
	v_and_b32_e32 v125, 0xffff0000, v120
	v_lshlrev_b32_e32 v120, 16, v121
	v_and_b32_e32 v121, 0xffff0000, v121
	v_lshlrev_b32_e32 v126, 16, v122
	v_and_b32_e32 v127, 0xffff0000, v122
	v_lshlrev_b32_e32 v122, 16, v123
	v_and_b32_e32 v123, 0xffff0000, v123
	v_pk_add_f32 v[118:119], v[118:119], v[120:121]
	v_pk_add_f32 v[116:117], v[116:117], v[124:125]
	v_pk_add_f32 v[120:121], v[114:115], v[122:123]
	v_pk_add_f32 v[122:123], v[112:113], v[126:127]
	v_cvt_pk_bf16_f32 v112, v116, v117
	v_cvt_pk_bf16_f32 v113, v118, v119
	v_cvt_pk_bf16_f32 v114, v122, v123
	v_cvt_pk_bf16_f32 v115, v120, v121
	global_store_dwordx4 v[142:143], v[112:115], off offset:256
	s_nop 1
	v_mul_f32_e32 v112, v117, v117
	v_fmac_f32_e32 v112, v116, v116
	v_fmac_f32_e32 v112, v118, v118
	v_fmac_f32_e32 v112, v119, v119
	v_fmac_f32_e32 v112, v122, v122
	v_fmac_f32_e32 v112, v123, v123
	v_fmac_f32_e32 v112, v120, v120
	v_fmac_f32_e32 v112, v121, v121
	v_add_f32_e32 v112, v154, v112
	ds_bpermute_b32 v113, v149, v112
	s_waitcnt lgkmcnt(0)
	v_add_f32_e32 v112, v112, v113
	ds_bpermute_b32 v113, v148, v112
	s_and_saveexec_b64 s[18:19], vcc
	s_cbranch_execz .LBB0_1908
	s_waitcnt lgkmcnt(0)
	v_add_f32_e32 v114, v112, v113
	v_lshlrev_b64 v[112:113], 6, v[140:141]
	v_lshl_add_u64 v[112:113], s[2:3], 0, v[112:113]
	v_lshl_add_u64 v[112:113], s[16:17], 2, v[112:113]
	s_lshl_b32 s24, s43, 2
	v_lshl_add_u64 v[112:113], v[112:113], 0, s[24:25]
	global_store_dword v[112:113], v114, off
